# inproj, wout, w1, w2 all as 256x128-tile GEMMs with fragment-blocked weights read straight to VGPRs (new converter for w_in, w_out, mlp_w1, mlp_w2); merge persistent 128
# speedup vs baseline: 1.1028x; 1.0215x over previous
.LBB0_24:
	s_andn2_b64 vcc, exec, s[4:5]
	s_cbranch_vccnz .LBB0_30
	v_readlane_b32 s4, v239, 0
	v_readlane_b32 s5, v239, 1
	s_andn2_b64 vcc, exec, s[4:5]
	s_cbranch_vccnz .LBB0_30
	s_load_dwordx2 s[4:5], s[0:1], 0x130
	s_load_dwordx2 s[24:25], s[0:1], 0x128
	v_and_b32_e32 v0, 63, v133
	v_lshrrev_b32_e32 v131, 6, v133
	v_lshrrev_b32_e32 v195, 2, v0
	v_readfirstlane_b32 s15, v131
	v_mul_u32_u24_e32 v218, 0x2000, v195
	v_and_b32_e32 v195, 3, v0
	v_lshlrev_b32_e32 v195, 4, v195
	v_lshrrev_b32_e32 v131, 5, v0
	v_lshlrev_b32_e32 v131, 5, v131
	v_xor_b32_e32 v195, v195, v131
	v_add_u32_e32 v218, v218, v195
	v_and_b32_e32 v195, 15, v0
	v_lshrrev_b32_e32 v131, 4, v0
	v_lshlrev_b32_e32 v216, 6, v195
	v_lshl_or_b32 v216, v131, 4, v216
	v_and_b32_e32 v219, 8, v0
	v_lshlrev_b32_e32 v219, 2, v219
	v_xor_b32_e32 v216, v216, v219
	v_mul_u32_u24_e32 v219, 0x1000, v195
	v_lshl_or_b32 v219, v131, 4, v219
	v_lshlrev_b32_e32 v222, 4, v0
	s_waitcnt lgkmcnt(0)
	s_add_u32 s18, s4, 0x4b27800
	s_addc_u32 s19, s5, 0
	s_add_u32 s20, s4, 0x2327800
	s_addc_u32 s21, s5, 0
	s_mul_i32 s3, s62, 73728
	s_add_u32 s3, s3, 20480
	s_add_u32 s4, s4, s3
	s_addc_u32 s5, s5, 0
	v_lshlrev_b32_e32 v225, 4, v131
	s_lshl_b32 s22, s15, 13
	s_mov_b32 s12, s79
.Lg256b_w2_first_retry:
	s_cmp_ge_u32 s12, 64
	s_cbranch_scc1 .Lg256b_w2_done
	s_lshr_b32 s3, s12, 6
	s_lshl_b32 s3, s3, 3
	s_add_u32 s3, s3, s65
	s_mov_b32 s17, s3
	s_mov_b32 s3, 0
	s_lshl_b32 s17, s17, 3
	s_bfe_u32 s23, s12, 0x30003
	s_add_u32 s13, s17, s23
	s_lshl_b32 s3, s3, 3
	s_and_b32 s23, s12, 7
	s_add_u32 s14, s3, s23
	s_lshl_b32 s13, s13, 8
	s_lshl_b32 s14, s14, 7
	s_lshl_b32 s3, s15, 6
	s_add_u32 s17, s3, s13
	s_mul_i32 s17, s17, 0x2000
	s_add_u32 s6, s18, s17
	s_addc_u32 s7, s19, 0
	s_lshr_b32 s3, s14, 4
	s_lshl_b32 s17, s15, 1
	s_add_u32 s3, s3, s17
	s_mul_i32 s17, s3, 0x20000
	s_add_u32 s8, s20, s17
	s_addc_u32 s9, s21, 0
	s_barrier
	v_mov_b32_e32 v217, v218
	v_mov_b32_e32 v220, v222
	v_add_u32_e32 v221, 0x20000, v222
	s_add_u32 m0, s22, 0x0
	v_mov_b32_e32 v223, v217
	global_load_lds_dwordx4 v223, s[6:7]
	s_add_u32 m0, s22, 0x400
	v_add_u32_e32 v224, 0x40, v217
	global_load_lds_dwordx4 v224, s[6:7]
	s_add_u32 m0, s22, 0x800
	v_add_u32_e32 v223, 0x20000, v217
	global_load_lds_dwordx4 v223, s[6:7]
	s_add_u32 m0, s22, 0xc00
	v_add_u32_e32 v224, 0x20040, v217
	global_load_lds_dwordx4 v224, s[6:7]
	s_add_u32 m0, s22, 0x1000
	v_add_u32_e32 v223, 0x40000, v217
	global_load_lds_dwordx4 v223, s[6:7]
	s_add_u32 m0, s22, 0x1400
	v_add_u32_e32 v224, 0x40040, v217
	global_load_lds_dwordx4 v224, s[6:7]
	s_add_u32 m0, s22, 0x1800
	v_add_u32_e32 v223, 0x60000, v217
	global_load_lds_dwordx4 v223, s[6:7]
	s_add_u32 m0, s22, 0x1c00
	v_add_u32_e32 v224, 0x60040, v217
	global_load_lds_dwordx4 v224, s[6:7]
	v_add_u32_e32 v217, 0x80, v217
	s_add_u32 m0, s22, 0x8000
	v_mov_b32_e32 v223, v217
	global_load_lds_dwordx4 v223, s[6:7]
	s_add_u32 m0, s22, 0x8400
	v_add_u32_e32 v224, 0x40, v217
	global_load_lds_dwordx4 v224, s[6:7]
	s_add_u32 m0, s22, 0x8800
	v_add_u32_e32 v223, 0x20000, v217
	global_load_lds_dwordx4 v223, s[6:7]
	s_add_u32 m0, s22, 0x8c00
	v_add_u32_e32 v224, 0x20040, v217
	global_load_lds_dwordx4 v224, s[6:7]
	s_add_u32 m0, s22, 0x9000
	v_add_u32_e32 v223, 0x40000, v217
	global_load_lds_dwordx4 v223, s[6:7]
	s_add_u32 m0, s22, 0x9400
	v_add_u32_e32 v224, 0x40040, v217
	global_load_lds_dwordx4 v224, s[6:7]
	s_add_u32 m0, s22, 0x9800
	v_add_u32_e32 v223, 0x60000, v217
	global_load_lds_dwordx4 v223, s[6:7]
	s_add_u32 m0, s22, 0x9c00
	v_add_u32_e32 v224, 0x60040, v217
	global_load_lds_dwordx4 v224, s[6:7]
	v_add_u32_e32 v217, 0x80, v217
	global_load_dwordx4 v[166:169], v220, s[8:9]
	global_load_dwordx4 v[170:173], v220, s[8:9] offset:1024
	global_load_dwordx4 v[174:177], v221, s[8:9]
	global_load_dwordx4 v[178:181], v221, s[8:9] offset:1024
	v_add_u32_e32 v220, 0x800, v220
	v_add_u32_e32 v221, 0x800, v221
	s_waitcnt vmcnt(0)
	s_barrier
	ds_read_b128 v[134:137], v216
	ds_read_b128 v[138:141], v216 offset:2048
	ds_read_b128 v[142:145], v216 offset:4096
	ds_read_b128 v[146:149], v216 offset:6144
	ds_read_b128 v[150:153], v216 offset:8192
	ds_read_b128 v[154:157], v216 offset:10240
.Lg256b_w2_tile:
	s_mul_i32 s17, s13, 0x1000
	s_lshl_b32 s3, s15, 5
	s_add_u32 s3, s3, s14
	s_mul_i32 s3, s3, 4
	s_add_u32 s17, s17, s3
	s_add_u32 s10, s24, s17
	s_addc_u32 s11, s25, 0
	s_lshl_b32 s3, s15, 5
	s_add_u32 s3, s3, s14
	s_lshl_b32 s3, s3, 2
	s_lshr_b32 s17, s13, 12
	s_max_u32 s17, s17, 1
	s_sub_u32 s17, s17, 1
	s_mul_i32 s17, s17, 24576
	s_add_u32 s3, s3, s17
	v_add_u32_e32 v234, s3, v225
	s_mov_b64 s[26:27], s[10:11]
	ds_read_b128 v[158:161], v216 offset:12288
	s_waitcnt vmcnt(16) lgkmcnt(6)
	v_mfma_f32_16x16x32_bf16 v[2:5], v[166:169], v[134:137], 0
	global_load_dwordx4 v[196:199], v220, s[8:9]
	v_mfma_f32_16x16x32_bf16 v[6:9], v[174:177], v[134:137], 0
	global_load_dwordx4 v[200:203], v220, s[8:9] offset:1024
	ds_read_b128 v[162:165], v216 offset:14336
	s_waitcnt lgkmcnt(6)
	v_mfma_f32_16x16x32_bf16 v[10:13], v[166:169], v[138:141], 0
	global_load_dwordx4 v[204:207], v221, s[8:9]
	v_mfma_f32_16x16x32_bf16 v[14:17], v[174:177], v[138:141], 0
	global_load_dwordx4 v[212:215], v221, s[8:9] offset:1024
	ds_read_b128 v[134:137], v216 offset:16384
	s_waitcnt lgkmcnt(6)
	v_mfma_f32_16x16x32_bf16 v[18:21], v[166:169], v[142:145], 0
	v_mfma_f32_16x16x32_bf16 v[22:25], v[174:177], v[142:145], 0
	ds_read_b128 v[138:141], v216 offset:18432
	s_waitcnt lgkmcnt(6)
	v_mfma_f32_16x16x32_bf16 v[26:29], v[166:169], v[146:149], 0
	v_mfma_f32_16x16x32_bf16 v[30:33], v[174:177], v[146:149], 0
	ds_read_b128 v[142:145], v216 offset:20480
	s_waitcnt lgkmcnt(6)
	v_mfma_f32_16x16x32_bf16 v[34:37], v[166:169], v[150:153], 0
	v_mfma_f32_16x16x32_bf16 v[38:41], v[174:177], v[150:153], 0
	ds_read_b128 v[146:149], v216 offset:22528
	s_waitcnt lgkmcnt(6)
	v_mfma_f32_16x16x32_bf16 v[42:45], v[166:169], v[154:157], 0
	v_mfma_f32_16x16x32_bf16 v[46:49], v[174:177], v[154:157], 0
	ds_read_b128 v[150:153], v216 offset:24576
	s_waitcnt lgkmcnt(6)
	v_mfma_f32_16x16x32_bf16 v[50:53], v[166:169], v[158:161], 0
	v_mfma_f32_16x16x32_bf16 v[54:57], v[174:177], v[158:161], 0
	ds_read_b128 v[154:157], v216 offset:26624
	s_waitcnt lgkmcnt(6)
	v_mfma_f32_16x16x32_bf16 v[58:61], v[166:169], v[162:165], 0
	v_mfma_f32_16x16x32_bf16 v[62:65], v[174:177], v[162:165], 0
	ds_read_b128 v[158:161], v216 offset:28672
	s_waitcnt lgkmcnt(6)
	v_mfma_f32_16x16x32_bf16 v[66:69], v[166:169], v[134:137], 0
	v_mfma_f32_16x16x32_bf16 v[70:73], v[174:177], v[134:137], 0
	ds_read_b128 v[162:165], v216 offset:30720
	s_waitcnt lgkmcnt(6)
	v_mfma_f32_16x16x32_bf16 v[74:77], v[166:169], v[138:141], 0
	v_mfma_f32_16x16x32_bf16 v[78:81], v[174:177], v[138:141], 0
	ds_read_b128 v[134:137], v216 offset:1024
	s_waitcnt lgkmcnt(6)
	v_mfma_f32_16x16x32_bf16 v[82:85], v[166:169], v[142:145], 0
	v_mfma_f32_16x16x32_bf16 v[86:89], v[174:177], v[142:145], 0
	ds_read_b128 v[138:141], v216 offset:3072
	s_waitcnt lgkmcnt(6)
	v_mfma_f32_16x16x32_bf16 v[90:93], v[166:169], v[146:149], 0
	v_mfma_f32_16x16x32_bf16 v[94:97], v[174:177], v[146:149], 0
	ds_read_b128 v[142:145], v216 offset:5120
	s_waitcnt lgkmcnt(6)
	v_mfma_f32_16x16x32_bf16 v[98:101], v[166:169], v[150:153], 0
	v_mfma_f32_16x16x32_bf16 v[102:105], v[174:177], v[150:153], 0
	ds_read_b128 v[146:149], v216 offset:7168
	s_waitcnt lgkmcnt(6)
	v_mfma_f32_16x16x32_bf16 v[106:109], v[166:169], v[154:157], 0
	v_mfma_f32_16x16x32_bf16 v[110:113], v[174:177], v[154:157], 0
	ds_read_b128 v[150:153], v216 offset:9216
	s_waitcnt lgkmcnt(6)
	v_mfma_f32_16x16x32_bf16 v[114:117], v[166:169], v[158:161], 0
	v_mfma_f32_16x16x32_bf16 v[118:121], v[174:177], v[158:161], 0
	ds_read_b128 v[154:157], v216 offset:11264
	s_waitcnt lgkmcnt(6)
	v_mfma_f32_16x16x32_bf16 v[122:125], v[166:169], v[162:165], 0
	v_mfma_f32_16x16x32_bf16 v[126:129], v[174:177], v[162:165], 0
	ds_read_b128 v[158:161], v216 offset:13312
	s_waitcnt lgkmcnt(6)
	v_mfma_f32_16x16x32_bf16 v[2:5], v[170:173], v[134:137], v[2:5]
	v_mfma_f32_16x16x32_bf16 v[6:9], v[178:181], v[134:137], v[6:9]
	ds_read_b128 v[162:165], v216 offset:15360
	s_waitcnt lgkmcnt(6)
	v_mfma_f32_16x16x32_bf16 v[10:13], v[170:173], v[138:141], v[10:13]
	v_mfma_f32_16x16x32_bf16 v[14:17], v[178:181], v[138:141], v[14:17]
	ds_read_b128 v[134:137], v216 offset:17408
	s_waitcnt lgkmcnt(6)
	v_mfma_f32_16x16x32_bf16 v[18:21], v[170:173], v[142:145], v[18:21]
	v_mfma_f32_16x16x32_bf16 v[22:25], v[178:181], v[142:145], v[22:25]
	ds_read_b128 v[138:141], v216 offset:19456
	s_waitcnt lgkmcnt(6)
	v_mfma_f32_16x16x32_bf16 v[26:29], v[170:173], v[146:149], v[26:29]
	v_mfma_f32_16x16x32_bf16 v[30:33], v[178:181], v[146:149], v[30:33]
	ds_read_b128 v[142:145], v216 offset:21504
	s_waitcnt lgkmcnt(6)
	v_mfma_f32_16x16x32_bf16 v[34:37], v[170:173], v[150:153], v[34:37]
	v_mfma_f32_16x16x32_bf16 v[38:41], v[178:181], v[150:153], v[38:41]
	ds_read_b128 v[146:149], v216 offset:23552
	s_waitcnt lgkmcnt(6)
	v_mfma_f32_16x16x32_bf16 v[42:45], v[170:173], v[154:157], v[42:45]
	v_mfma_f32_16x16x32_bf16 v[46:49], v[178:181], v[154:157], v[46:49]
	ds_read_b128 v[150:153], v216 offset:25600
	s_waitcnt lgkmcnt(6)
	v_mfma_f32_16x16x32_bf16 v[50:53], v[170:173], v[158:161], v[50:53]
	v_mfma_f32_16x16x32_bf16 v[54:57], v[178:181], v[158:161], v[54:57]
	ds_read_b128 v[154:157], v216 offset:27648
	s_waitcnt lgkmcnt(6)
	v_mfma_f32_16x16x32_bf16 v[58:61], v[170:173], v[162:165], v[58:61]
	v_mfma_f32_16x16x32_bf16 v[62:65], v[178:181], v[162:165], v[62:65]
	ds_read_b128 v[158:161], v216 offset:29696
	s_waitcnt lgkmcnt(6)
	v_mfma_f32_16x16x32_bf16 v[66:69], v[170:173], v[134:137], v[66:69]
	v_mfma_f32_16x16x32_bf16 v[70:73], v[178:181], v[134:137], v[70:73]
	ds_read_b128 v[162:165], v216 offset:31744
	s_waitcnt vmcnt(12) lgkmcnt(0)
	s_barrier
	v_mfma_f32_16x16x32_bf16 v[74:77], v[170:173], v[138:141], v[74:77]
	s_add_u32 m0, s22, 0x0
	v_mov_b32_e32 v223, v217
	global_load_lds_dwordx4 v223, s[6:7]
	v_mfma_f32_16x16x32_bf16 v[78:81], v[178:181], v[138:141], v[78:81]
	s_add_u32 m0, s22, 0x400
	v_add_u32_e32 v224, 0x40, v217
	global_load_lds_dwordx4 v224, s[6:7]
	ds_read_b128 v[134:137], v216 offset:32768
	s_waitcnt lgkmcnt(6)
	v_mfma_f32_16x16x32_bf16 v[82:85], v[170:173], v[142:145], v[82:85]
	s_add_u32 m0, s22, 0x800
	v_add_u32_e32 v223, 0x20000, v217
	global_load_lds_dwordx4 v223, s[6:7]
	v_mfma_f32_16x16x32_bf16 v[86:89], v[178:181], v[142:145], v[86:89]
	s_add_u32 m0, s22, 0xc00
	v_add_u32_e32 v224, 0x20040, v217
	global_load_lds_dwordx4 v224, s[6:7]
	ds_read_b128 v[138:141], v216 offset:34816
	s_waitcnt lgkmcnt(6)
	v_mfma_f32_16x16x32_bf16 v[90:93], v[170:173], v[146:149], v[90:93]
	s_add_u32 m0, s22, 0x1000
	v_add_u32_e32 v223, 0x40000, v217
	global_load_lds_dwordx4 v223, s[6:7]
	v_mfma_f32_16x16x32_bf16 v[94:97], v[178:181], v[146:149], v[94:97]
	s_add_u32 m0, s22, 0x1400
	v_add_u32_e32 v224, 0x40040, v217
	global_load_lds_dwordx4 v224, s[6:7]
	ds_read_b128 v[142:145], v216 offset:36864
	s_waitcnt lgkmcnt(6)
	v_mfma_f32_16x16x32_bf16 v[98:101], v[170:173], v[150:153], v[98:101]
	s_add_u32 m0, s22, 0x1800
	v_add_u32_e32 v223, 0x60000, v217
	global_load_lds_dwordx4 v223, s[6:7]
	v_mfma_f32_16x16x32_bf16 v[102:105], v[178:181], v[150:153], v[102:105]
	s_add_u32 m0, s22, 0x1c00
	v_add_u32_e32 v224, 0x60040, v217
	global_load_lds_dwordx4 v224, s[6:7]
	ds_read_b128 v[146:149], v216 offset:38912
	s_waitcnt lgkmcnt(6)
	v_mfma_f32_16x16x32_bf16 v[106:109], v[170:173], v[154:157], v[106:109]
	v_mfma_f32_16x16x32_bf16 v[110:113], v[178:181], v[154:157], v[110:113]
	ds_read_b128 v[150:153], v216 offset:40960
	s_waitcnt lgkmcnt(6)
	v_mfma_f32_16x16x32_bf16 v[114:117], v[170:173], v[158:161], v[114:117]
	v_mfma_f32_16x16x32_bf16 v[118:121], v[178:181], v[158:161], v[118:121]
	ds_read_b128 v[154:157], v216 offset:43008
	s_waitcnt lgkmcnt(6)
	v_mfma_f32_16x16x32_bf16 v[122:125], v[170:173], v[162:165], v[122:125]
	v_mfma_f32_16x16x32_bf16 v[126:129], v[178:181], v[162:165], v[126:129]
	v_add_u32_e32 v217, 0x80, v217
	v_add_u32_e32 v220, 0x800, v220
	v_add_u32_e32 v221, 0x800, v221
	ds_read_b128 v[158:161], v216 offset:45056
	s_waitcnt vmcnt(8) lgkmcnt(6)
	v_mfma_f32_16x16x32_bf16 v[2:5], v[196:199], v[134:137], v[2:5]
	global_load_dwordx4 v[166:169], v220, s[8:9]
	v_mfma_f32_16x16x32_bf16 v[6:9], v[204:207], v[134:137], v[6:9]
	global_load_dwordx4 v[170:173], v220, s[8:9] offset:1024
	ds_read_b128 v[162:165], v216 offset:47104
	s_waitcnt lgkmcnt(6)
	v_mfma_f32_16x16x32_bf16 v[10:13], v[196:199], v[138:141], v[10:13]
	global_load_dwordx4 v[174:177], v221, s[8:9]
	v_mfma_f32_16x16x32_bf16 v[14:17], v[204:207], v[138:141], v[14:17]
	global_load_dwordx4 v[178:181], v221, s[8:9] offset:1024
	ds_read_b128 v[134:137], v216 offset:49152
	s_waitcnt lgkmcnt(6)
	v_mfma_f32_16x16x32_bf16 v[18:21], v[196:199], v[142:145], v[18:21]
	v_mfma_f32_16x16x32_bf16 v[22:25], v[204:207], v[142:145], v[22:25]
	ds_read_b128 v[138:141], v216 offset:51200
	s_waitcnt lgkmcnt(6)
	v_mfma_f32_16x16x32_bf16 v[26:29], v[196:199], v[146:149], v[26:29]
	v_mfma_f32_16x16x32_bf16 v[30:33], v[204:207], v[146:149], v[30:33]
	ds_read_b128 v[142:145], v216 offset:53248
	s_waitcnt lgkmcnt(6)
	v_mfma_f32_16x16x32_bf16 v[34:37], v[196:199], v[150:153], v[34:37]
	v_mfma_f32_16x16x32_bf16 v[38:41], v[204:207], v[150:153], v[38:41]
	ds_read_b128 v[146:149], v216 offset:55296
	s_waitcnt lgkmcnt(6)
	v_mfma_f32_16x16x32_bf16 v[42:45], v[196:199], v[154:157], v[42:45]
	v_mfma_f32_16x16x32_bf16 v[46:49], v[204:207], v[154:157], v[46:49]
	ds_read_b128 v[150:153], v216 offset:57344
	s_waitcnt lgkmcnt(6)
	v_mfma_f32_16x16x32_bf16 v[50:53], v[196:199], v[158:161], v[50:53]
	v_mfma_f32_16x16x32_bf16 v[54:57], v[204:207], v[158:161], v[54:57]
	ds_read_b128 v[154:157], v216 offset:59392
	s_waitcnt lgkmcnt(6)
	v_mfma_f32_16x16x32_bf16 v[58:61], v[196:199], v[162:165], v[58:61]
	v_mfma_f32_16x16x32_bf16 v[62:65], v[204:207], v[162:165], v[62:65]
	ds_read_b128 v[158:161], v216 offset:61440
	s_waitcnt lgkmcnt(6)
	v_mfma_f32_16x16x32_bf16 v[66:69], v[196:199], v[134:137], v[66:69]
	v_mfma_f32_16x16x32_bf16 v[70:73], v[204:207], v[134:137], v[70:73]
	ds_read_b128 v[162:165], v216 offset:63488
	s_waitcnt lgkmcnt(6)
	v_mfma_f32_16x16x32_bf16 v[74:77], v[196:199], v[138:141], v[74:77]
	v_mfma_f32_16x16x32_bf16 v[78:81], v[204:207], v[138:141], v[78:81]
	ds_read_b128 v[134:137], v216 offset:33792
	s_waitcnt lgkmcnt(6)
	v_mfma_f32_16x16x32_bf16 v[82:85], v[196:199], v[142:145], v[82:85]
	v_mfma_f32_16x16x32_bf16 v[86:89], v[204:207], v[142:145], v[86:89]
	ds_read_b128 v[138:141], v216 offset:35840
	s_waitcnt lgkmcnt(6)
	v_mfma_f32_16x16x32_bf16 v[90:93], v[196:199], v[146:149], v[90:93]
	v_mfma_f32_16x16x32_bf16 v[94:97], v[204:207], v[146:149], v[94:97]
	ds_read_b128 v[142:145], v216 offset:37888
	s_waitcnt lgkmcnt(6)
	v_mfma_f32_16x16x32_bf16 v[98:101], v[196:199], v[150:153], v[98:101]
	v_mfma_f32_16x16x32_bf16 v[102:105], v[204:207], v[150:153], v[102:105]
	ds_read_b128 v[146:149], v216 offset:39936
	s_waitcnt lgkmcnt(6)
	v_mfma_f32_16x16x32_bf16 v[106:109], v[196:199], v[154:157], v[106:109]
	v_mfma_f32_16x16x32_bf16 v[110:113], v[204:207], v[154:157], v[110:113]
	ds_read_b128 v[150:153], v216 offset:41984
	s_waitcnt lgkmcnt(6)
	v_mfma_f32_16x16x32_bf16 v[114:117], v[196:199], v[158:161], v[114:117]
	v_mfma_f32_16x16x32_bf16 v[118:121], v[204:207], v[158:161], v[118:121]
	ds_read_b128 v[154:157], v216 offset:44032
	s_waitcnt lgkmcnt(6)
	v_mfma_f32_16x16x32_bf16 v[122:125], v[196:199], v[162:165], v[122:125]
	v_mfma_f32_16x16x32_bf16 v[126:129], v[204:207], v[162:165], v[126:129]
	ds_read_b128 v[158:161], v216 offset:46080
	s_waitcnt lgkmcnt(6)
	v_mfma_f32_16x16x32_bf16 v[2:5], v[200:203], v[134:137], v[2:5]
	v_mfma_f32_16x16x32_bf16 v[6:9], v[212:215], v[134:137], v[6:9]
	ds_read_b128 v[162:165], v216 offset:48128
	s_waitcnt lgkmcnt(6)
	v_mfma_f32_16x16x32_bf16 v[10:13], v[200:203], v[138:141], v[10:13]
	v_mfma_f32_16x16x32_bf16 v[14:17], v[212:215], v[138:141], v[14:17]
	ds_read_b128 v[134:137], v216 offset:50176
	s_waitcnt lgkmcnt(6)
	v_mfma_f32_16x16x32_bf16 v[18:21], v[200:203], v[142:145], v[18:21]
	v_mfma_f32_16x16x32_bf16 v[22:25], v[212:215], v[142:145], v[22:25]
	ds_read_b128 v[138:141], v216 offset:52224
	s_waitcnt lgkmcnt(6)
	v_mfma_f32_16x16x32_bf16 v[26:29], v[200:203], v[146:149], v[26:29]
	v_mfma_f32_16x16x32_bf16 v[30:33], v[212:215], v[146:149], v[30:33]
	ds_read_b128 v[142:145], v216 offset:54272
	s_waitcnt lgkmcnt(6)
	v_mfma_f32_16x16x32_bf16 v[34:37], v[200:203], v[150:153], v[34:37]
	v_mfma_f32_16x16x32_bf16 v[38:41], v[212:215], v[150:153], v[38:41]
	ds_read_b128 v[146:149], v216 offset:56320
	s_waitcnt lgkmcnt(6)
	v_mfma_f32_16x16x32_bf16 v[42:45], v[200:203], v[154:157], v[42:45]
	v_mfma_f32_16x16x32_bf16 v[46:49], v[212:215], v[154:157], v[46:49]
	ds_read_b128 v[150:153], v216 offset:58368
	s_waitcnt lgkmcnt(6)
	v_mfma_f32_16x16x32_bf16 v[50:53], v[200:203], v[158:161], v[50:53]
	v_mfma_f32_16x16x32_bf16 v[54:57], v[212:215], v[158:161], v[54:57]
	ds_read_b128 v[154:157], v216 offset:60416
	s_waitcnt lgkmcnt(6)
	v_mfma_f32_16x16x32_bf16 v[58:61], v[200:203], v[162:165], v[58:61]
	v_mfma_f32_16x16x32_bf16 v[62:65], v[212:215], v[162:165], v[62:65]
	ds_read_b128 v[158:161], v216 offset:62464
	s_waitcnt lgkmcnt(6)
	v_mfma_f32_16x16x32_bf16 v[66:69], v[200:203], v[134:137], v[66:69]
	v_mfma_f32_16x16x32_bf16 v[70:73], v[212:215], v[134:137], v[70:73]
	ds_read_b128 v[162:165], v216 offset:64512
	s_waitcnt vmcnt(4) lgkmcnt(0)
	s_barrier
	v_mfma_f32_16x16x32_bf16 v[74:77], v[200:203], v[138:141], v[74:77]
	s_add_u32 m0, s22, 0x8000
	v_mov_b32_e32 v223, v217
	global_load_lds_dwordx4 v223, s[6:7]
	v_mfma_f32_16x16x32_bf16 v[78:81], v[212:215], v[138:141], v[78:81]
	s_add_u32 m0, s22, 0x8400
	v_add_u32_e32 v224, 0x40, v217
	global_load_lds_dwordx4 v224, s[6:7]
	ds_read_b128 v[134:137], v216
	s_waitcnt lgkmcnt(6)
	v_mfma_f32_16x16x32_bf16 v[82:85], v[200:203], v[142:145], v[82:85]
	s_add_u32 m0, s22, 0x8800
	v_add_u32_e32 v223, 0x20000, v217
	global_load_lds_dwordx4 v223, s[6:7]
	v_mfma_f32_16x16x32_bf16 v[86:89], v[212:215], v[142:145], v[86:89]
	s_add_u32 m0, s22, 0x8c00
	v_add_u32_e32 v224, 0x20040, v217
	global_load_lds_dwordx4 v224, s[6:7]
	ds_read_b128 v[138:141], v216 offset:2048
	s_waitcnt lgkmcnt(6)
	v_mfma_f32_16x16x32_bf16 v[90:93], v[200:203], v[146:149], v[90:93]
	s_add_u32 m0, s22, 0x9000
	v_add_u32_e32 v223, 0x40000, v217
	global_load_lds_dwordx4 v223, s[6:7]
	v_mfma_f32_16x16x32_bf16 v[94:97], v[212:215], v[146:149], v[94:97]
	s_add_u32 m0, s22, 0x9400
	v_add_u32_e32 v224, 0x40040, v217
	global_load_lds_dwordx4 v224, s[6:7]
	ds_read_b128 v[142:145], v216 offset:4096
	s_waitcnt lgkmcnt(6)
	v_mfma_f32_16x16x32_bf16 v[98:101], v[200:203], v[150:153], v[98:101]
	s_add_u32 m0, s22, 0x9800
	v_add_u32_e32 v223, 0x60000, v217
	global_load_lds_dwordx4 v223, s[6:7]
	v_mfma_f32_16x16x32_bf16 v[102:105], v[212:215], v[150:153], v[102:105]
	s_add_u32 m0, s22, 0x9c00
	v_add_u32_e32 v224, 0x60040, v217
	global_load_lds_dwordx4 v224, s[6:7]
	ds_read_b128 v[146:149], v216 offset:6144
	s_waitcnt lgkmcnt(6)
	v_mfma_f32_16x16x32_bf16 v[106:109], v[200:203], v[154:157], v[106:109]
	v_mfma_f32_16x16x32_bf16 v[110:113], v[212:215], v[154:157], v[110:113]
	ds_read_b128 v[150:153], v216 offset:8192
	s_waitcnt lgkmcnt(6)
	v_mfma_f32_16x16x32_bf16 v[114:117], v[200:203], v[158:161], v[114:117]
	v_mfma_f32_16x16x32_bf16 v[118:121], v[212:215], v[158:161], v[118:121]
	ds_read_b128 v[154:157], v216 offset:10240
	s_waitcnt lgkmcnt(6)
	v_mfma_f32_16x16x32_bf16 v[122:125], v[200:203], v[162:165], v[122:125]
	v_mfma_f32_16x16x32_bf16 v[126:129], v[212:215], v[162:165], v[126:129]
	v_add_u32_e32 v217, 0x80, v217
	v_add_u32_e32 v220, 0x800, v220
	v_add_u32_e32 v221, 0x800, v221
	s_mov_b32 s16, 30
.Lg256b_w2_loop:
	ds_read_b128 v[158:161], v216 offset:12288
	s_waitcnt vmcnt(8) lgkmcnt(6)
	v_mfma_f32_16x16x32_bf16 v[2:5], v[166:169], v[134:137], v[2:5]
	global_load_dwordx4 v[196:199], v220, s[8:9]
	v_mfma_f32_16x16x32_bf16 v[6:9], v[174:177], v[134:137], v[6:9]
	global_load_dwordx4 v[200:203], v220, s[8:9] offset:1024
	ds_read_b128 v[162:165], v216 offset:14336
	s_waitcnt lgkmcnt(6)
	v_mfma_f32_16x16x32_bf16 v[10:13], v[166:169], v[138:141], v[10:13]
	global_load_dwordx4 v[204:207], v221, s[8:9]
	v_mfma_f32_16x16x32_bf16 v[14:17], v[174:177], v[138:141], v[14:17]
	global_load_dwordx4 v[212:215], v221, s[8:9] offset:1024
	ds_read_b128 v[134:137], v216 offset:16384
	s_waitcnt lgkmcnt(6)
	v_mfma_f32_16x16x32_bf16 v[18:21], v[166:169], v[142:145], v[18:21]
	v_mfma_f32_16x16x32_bf16 v[22:25], v[174:177], v[142:145], v[22:25]
	ds_read_b128 v[138:141], v216 offset:18432
	s_waitcnt lgkmcnt(6)
	v_mfma_f32_16x16x32_bf16 v[26:29], v[166:169], v[146:149], v[26:29]
	v_mfma_f32_16x16x32_bf16 v[30:33], v[174:177], v[146:149], v[30:33]
	ds_read_b128 v[142:145], v216 offset:20480
	s_waitcnt lgkmcnt(6)
	v_mfma_f32_16x16x32_bf16 v[34:37], v[166:169], v[150:153], v[34:37]
	v_mfma_f32_16x16x32_bf16 v[38:41], v[174:177], v[150:153], v[38:41]
	ds_read_b128 v[146:149], v216 offset:22528
	s_waitcnt lgkmcnt(6)
	v_mfma_f32_16x16x32_bf16 v[42:45], v[166:169], v[154:157], v[42:45]
	v_mfma_f32_16x16x32_bf16 v[46:49], v[174:177], v[154:157], v[46:49]
	ds_read_b128 v[150:153], v216 offset:24576
	s_waitcnt lgkmcnt(6)
	v_mfma_f32_16x16x32_bf16 v[50:53], v[166:169], v[158:161], v[50:53]
	v_mfma_f32_16x16x32_bf16 v[54:57], v[174:177], v[158:161], v[54:57]
	ds_read_b128 v[154:157], v216 offset:26624
	s_waitcnt lgkmcnt(6)
	v_mfma_f32_16x16x32_bf16 v[58:61], v[166:169], v[162:165], v[58:61]
	v_mfma_f32_16x16x32_bf16 v[62:65], v[174:177], v[162:165], v[62:65]
	ds_read_b128 v[158:161], v216 offset:28672
	s_waitcnt lgkmcnt(6)
	v_mfma_f32_16x16x32_bf16 v[66:69], v[166:169], v[134:137], v[66:69]
	v_mfma_f32_16x16x32_bf16 v[70:73], v[174:177], v[134:137], v[70:73]
	ds_read_b128 v[162:165], v216 offset:30720
	s_waitcnt lgkmcnt(6)
	v_mfma_f32_16x16x32_bf16 v[74:77], v[166:169], v[138:141], v[74:77]
	v_mfma_f32_16x16x32_bf16 v[78:81], v[174:177], v[138:141], v[78:81]
	ds_read_b128 v[134:137], v216 offset:1024
	s_waitcnt lgkmcnt(6)
	v_mfma_f32_16x16x32_bf16 v[82:85], v[166:169], v[142:145], v[82:85]
	v_mfma_f32_16x16x32_bf16 v[86:89], v[174:177], v[142:145], v[86:89]
	ds_read_b128 v[138:141], v216 offset:3072
	s_waitcnt lgkmcnt(6)
	v_mfma_f32_16x16x32_bf16 v[90:93], v[166:169], v[146:149], v[90:93]
	v_mfma_f32_16x16x32_bf16 v[94:97], v[174:177], v[146:149], v[94:97]
	ds_read_b128 v[142:145], v216 offset:5120
	s_waitcnt lgkmcnt(6)
	v_mfma_f32_16x16x32_bf16 v[98:101], v[166:169], v[150:153], v[98:101]
	v_mfma_f32_16x16x32_bf16 v[102:105], v[174:177], v[150:153], v[102:105]
	ds_read_b128 v[146:149], v216 offset:7168
	s_waitcnt lgkmcnt(6)
	v_mfma_f32_16x16x32_bf16 v[106:109], v[166:169], v[154:157], v[106:109]
	v_mfma_f32_16x16x32_bf16 v[110:113], v[174:177], v[154:157], v[110:113]
	ds_read_b128 v[150:153], v216 offset:9216
	s_waitcnt lgkmcnt(6)
	v_mfma_f32_16x16x32_bf16 v[114:117], v[166:169], v[158:161], v[114:117]
	v_mfma_f32_16x16x32_bf16 v[118:121], v[174:177], v[158:161], v[118:121]
	ds_read_b128 v[154:157], v216 offset:11264
	s_waitcnt lgkmcnt(6)
	v_mfma_f32_16x16x32_bf16 v[122:125], v[166:169], v[162:165], v[122:125]
	v_mfma_f32_16x16x32_bf16 v[126:129], v[174:177], v[162:165], v[126:129]
	ds_read_b128 v[158:161], v216 offset:13312
	s_waitcnt lgkmcnt(6)
	v_mfma_f32_16x16x32_bf16 v[2:5], v[170:173], v[134:137], v[2:5]
	v_mfma_f32_16x16x32_bf16 v[6:9], v[178:181], v[134:137], v[6:9]
	ds_read_b128 v[162:165], v216 offset:15360
	s_waitcnt lgkmcnt(6)
	v_mfma_f32_16x16x32_bf16 v[10:13], v[170:173], v[138:141], v[10:13]
	v_mfma_f32_16x16x32_bf16 v[14:17], v[178:181], v[138:141], v[14:17]
	ds_read_b128 v[134:137], v216 offset:17408
	s_waitcnt lgkmcnt(6)
	v_mfma_f32_16x16x32_bf16 v[18:21], v[170:173], v[142:145], v[18:21]
	v_mfma_f32_16x16x32_bf16 v[22:25], v[178:181], v[142:145], v[22:25]
	ds_read_b128 v[138:141], v216 offset:19456
	s_waitcnt lgkmcnt(6)
	v_mfma_f32_16x16x32_bf16 v[26:29], v[170:173], v[146:149], v[26:29]
	v_mfma_f32_16x16x32_bf16 v[30:33], v[178:181], v[146:149], v[30:33]
	ds_read_b128 v[142:145], v216 offset:21504
	s_waitcnt lgkmcnt(6)
	v_mfma_f32_16x16x32_bf16 v[34:37], v[170:173], v[150:153], v[34:37]
	v_mfma_f32_16x16x32_bf16 v[38:41], v[178:181], v[150:153], v[38:41]
	ds_read_b128 v[146:149], v216 offset:23552
	s_waitcnt lgkmcnt(6)
	v_mfma_f32_16x16x32_bf16 v[42:45], v[170:173], v[154:157], v[42:45]
	v_mfma_f32_16x16x32_bf16 v[46:49], v[178:181], v[154:157], v[46:49]
	ds_read_b128 v[150:153], v216 offset:25600
	s_waitcnt lgkmcnt(6)
	v_mfma_f32_16x16x32_bf16 v[50:53], v[170:173], v[158:161], v[50:53]
	v_mfma_f32_16x16x32_bf16 v[54:57], v[178:181], v[158:161], v[54:57]
	ds_read_b128 v[154:157], v216 offset:27648
	s_waitcnt lgkmcnt(6)
	v_mfma_f32_16x16x32_bf16 v[58:61], v[170:173], v[162:165], v[58:61]
	v_mfma_f32_16x16x32_bf16 v[62:65], v[178:181], v[162:165], v[62:65]
	ds_read_b128 v[158:161], v216 offset:29696
	s_waitcnt lgkmcnt(6)
	v_mfma_f32_16x16x32_bf16 v[66:69], v[170:173], v[134:137], v[66:69]
	v_mfma_f32_16x16x32_bf16 v[70:73], v[178:181], v[134:137], v[70:73]
	ds_read_b128 v[162:165], v216 offset:31744
	s_waitcnt vmcnt(4) lgkmcnt(0)
	s_barrier
	v_mfma_f32_16x16x32_bf16 v[74:77], v[170:173], v[138:141], v[74:77]
	s_add_u32 m0, s22, 0x0
	v_mov_b32_e32 v223, v217
	global_load_lds_dwordx4 v223, s[6:7]
	v_mfma_f32_16x16x32_bf16 v[78:81], v[178:181], v[138:141], v[78:81]
	s_add_u32 m0, s22, 0x400
	v_add_u32_e32 v224, 0x40, v217
	global_load_lds_dwordx4 v224, s[6:7]
	ds_read_b128 v[134:137], v216 offset:32768
	s_waitcnt lgkmcnt(6)
	v_mfma_f32_16x16x32_bf16 v[82:85], v[170:173], v[142:145], v[82:85]
	s_add_u32 m0, s22, 0x800
	v_add_u32_e32 v223, 0x20000, v217
	global_load_lds_dwordx4 v223, s[6:7]
	v_mfma_f32_16x16x32_bf16 v[86:89], v[178:181], v[142:145], v[86:89]
	s_add_u32 m0, s22, 0xc00
	v_add_u32_e32 v224, 0x20040, v217
	global_load_lds_dwordx4 v224, s[6:7]
	ds_read_b128 v[138:141], v216 offset:34816
	s_waitcnt lgkmcnt(6)
	v_mfma_f32_16x16x32_bf16 v[90:93], v[170:173], v[146:149], v[90:93]
	s_add_u32 m0, s22, 0x1000
	v_add_u32_e32 v223, 0x40000, v217
	global_load_lds_dwordx4 v223, s[6:7]
	v_mfma_f32_16x16x32_bf16 v[94:97], v[178:181], v[146:149], v[94:97]
	s_add_u32 m0, s22, 0x1400
	v_add_u32_e32 v224, 0x40040, v217
	global_load_lds_dwordx4 v224, s[6:7]
	ds_read_b128 v[142:145], v216 offset:36864
	s_waitcnt lgkmcnt(6)
	v_mfma_f32_16x16x32_bf16 v[98:101], v[170:173], v[150:153], v[98:101]
	s_add_u32 m0, s22, 0x1800
	v_add_u32_e32 v223, 0x60000, v217
	global_load_lds_dwordx4 v223, s[6:7]
	v_mfma_f32_16x16x32_bf16 v[102:105], v[178:181], v[150:153], v[102:105]
	s_add_u32 m0, s22, 0x1c00
	v_add_u32_e32 v224, 0x60040, v217
	global_load_lds_dwordx4 v224, s[6:7]
	ds_read_b128 v[146:149], v216 offset:38912
	s_waitcnt lgkmcnt(6)
	v_mfma_f32_16x16x32_bf16 v[106:109], v[170:173], v[154:157], v[106:109]
	v_mfma_f32_16x16x32_bf16 v[110:113], v[178:181], v[154:157], v[110:113]
	ds_read_b128 v[150:153], v216 offset:40960
	s_waitcnt lgkmcnt(6)
	v_mfma_f32_16x16x32_bf16 v[114:117], v[170:173], v[158:161], v[114:117]
	v_mfma_f32_16x16x32_bf16 v[118:121], v[178:181], v[158:161], v[118:121]
	ds_read_b128 v[154:157], v216 offset:43008
	s_waitcnt lgkmcnt(6)
	v_mfma_f32_16x16x32_bf16 v[122:125], v[170:173], v[162:165], v[122:125]
	v_mfma_f32_16x16x32_bf16 v[126:129], v[178:181], v[162:165], v[126:129]
	v_add_u32_e32 v217, 0x80, v217
	v_add_u32_e32 v220, 0x800, v220
	v_add_u32_e32 v221, 0x800, v221
	ds_read_b128 v[158:161], v216 offset:45056
	s_waitcnt vmcnt(8) lgkmcnt(6)
	v_mfma_f32_16x16x32_bf16 v[2:5], v[196:199], v[134:137], v[2:5]
	global_load_dwordx4 v[166:169], v220, s[8:9]
	v_mfma_f32_16x16x32_bf16 v[6:9], v[204:207], v[134:137], v[6:9]
	global_load_dwordx4 v[170:173], v220, s[8:9] offset:1024
	ds_read_b128 v[162:165], v216 offset:47104
	s_waitcnt lgkmcnt(6)
	v_mfma_f32_16x16x32_bf16 v[10:13], v[196:199], v[138:141], v[10:13]
	global_load_dwordx4 v[174:177], v221, s[8:9]
	v_mfma_f32_16x16x32_bf16 v[14:17], v[204:207], v[138:141], v[14:17]
	global_load_dwordx4 v[178:181], v221, s[8:9] offset:1024
	ds_read_b128 v[134:137], v216 offset:49152
	s_waitcnt lgkmcnt(6)
	v_mfma_f32_16x16x32_bf16 v[18:21], v[196:199], v[142:145], v[18:21]
	v_mfma_f32_16x16x32_bf16 v[22:25], v[204:207], v[142:145], v[22:25]
	ds_read_b128 v[138:141], v216 offset:51200
	s_waitcnt lgkmcnt(6)
	v_mfma_f32_16x16x32_bf16 v[26:29], v[196:199], v[146:149], v[26:29]
	v_mfma_f32_16x16x32_bf16 v[30:33], v[204:207], v[146:149], v[30:33]
	ds_read_b128 v[142:145], v216 offset:53248
	s_waitcnt lgkmcnt(6)
	v_mfma_f32_16x16x32_bf16 v[34:37], v[196:199], v[150:153], v[34:37]
	v_mfma_f32_16x16x32_bf16 v[38:41], v[204:207], v[150:153], v[38:41]
	ds_read_b128 v[146:149], v216 offset:55296
	s_waitcnt lgkmcnt(6)
	v_mfma_f32_16x16x32_bf16 v[42:45], v[196:199], v[154:157], v[42:45]
	v_mfma_f32_16x16x32_bf16 v[46:49], v[204:207], v[154:157], v[46:49]
	ds_read_b128 v[150:153], v216 offset:57344
	s_waitcnt lgkmcnt(6)
	v_mfma_f32_16x16x32_bf16 v[50:53], v[196:199], v[158:161], v[50:53]
	v_mfma_f32_16x16x32_bf16 v[54:57], v[204:207], v[158:161], v[54:57]
	ds_read_b128 v[154:157], v216 offset:59392
	s_waitcnt lgkmcnt(6)
	v_mfma_f32_16x16x32_bf16 v[58:61], v[196:199], v[162:165], v[58:61]
	v_mfma_f32_16x16x32_bf16 v[62:65], v[204:207], v[162:165], v[62:65]
	ds_read_b128 v[158:161], v216 offset:61440
	s_waitcnt lgkmcnt(6)
	v_mfma_f32_16x16x32_bf16 v[66:69], v[196:199], v[134:137], v[66:69]
	v_mfma_f32_16x16x32_bf16 v[70:73], v[204:207], v[134:137], v[70:73]
	ds_read_b128 v[162:165], v216 offset:63488
	s_waitcnt lgkmcnt(6)
	v_mfma_f32_16x16x32_bf16 v[74:77], v[196:199], v[138:141], v[74:77]
	v_mfma_f32_16x16x32_bf16 v[78:81], v[204:207], v[138:141], v[78:81]
	ds_read_b128 v[134:137], v216 offset:33792
	s_waitcnt lgkmcnt(6)
	v_mfma_f32_16x16x32_bf16 v[82:85], v[196:199], v[142:145], v[82:85]
	v_mfma_f32_16x16x32_bf16 v[86:89], v[204:207], v[142:145], v[86:89]
	ds_read_b128 v[138:141], v216 offset:35840
	s_waitcnt lgkmcnt(6)
	v_mfma_f32_16x16x32_bf16 v[90:93], v[196:199], v[146:149], v[90:93]
	v_mfma_f32_16x16x32_bf16 v[94:97], v[204:207], v[146:149], v[94:97]
	ds_read_b128 v[142:145], v216 offset:37888
	s_waitcnt lgkmcnt(6)
	v_mfma_f32_16x16x32_bf16 v[98:101], v[196:199], v[150:153], v[98:101]
	v_mfma_f32_16x16x32_bf16 v[102:105], v[204:207], v[150:153], v[102:105]
	ds_read_b128 v[146:149], v216 offset:39936
	s_waitcnt lgkmcnt(6)
	v_mfma_f32_16x16x32_bf16 v[106:109], v[196:199], v[154:157], v[106:109]
	v_mfma_f32_16x16x32_bf16 v[110:113], v[204:207], v[154:157], v[110:113]
	ds_read_b128 v[150:153], v216 offset:41984
	s_waitcnt lgkmcnt(6)
	v_mfma_f32_16x16x32_bf16 v[114:117], v[196:199], v[158:161], v[114:117]
	v_mfma_f32_16x16x32_bf16 v[118:121], v[204:207], v[158:161], v[118:121]
	ds_read_b128 v[154:157], v216 offset:44032
	s_waitcnt lgkmcnt(6)
	v_mfma_f32_16x16x32_bf16 v[122:125], v[196:199], v[162:165], v[122:125]
	v_mfma_f32_16x16x32_bf16 v[126:129], v[204:207], v[162:165], v[126:129]
	ds_read_b128 v[158:161], v216 offset:46080
	s_waitcnt lgkmcnt(6)
	v_mfma_f32_16x16x32_bf16 v[2:5], v[200:203], v[134:137], v[2:5]
	v_mfma_f32_16x16x32_bf16 v[6:9], v[212:215], v[134:137], v[6:9]
	ds_read_b128 v[162:165], v216 offset:48128
	s_waitcnt lgkmcnt(6)
	v_mfma_f32_16x16x32_bf16 v[10:13], v[200:203], v[138:141], v[10:13]
	v_mfma_f32_16x16x32_bf16 v[14:17], v[212:215], v[138:141], v[14:17]
	ds_read_b128 v[134:137], v216 offset:50176
	s_waitcnt lgkmcnt(6)
	v_mfma_f32_16x16x32_bf16 v[18:21], v[200:203], v[142:145], v[18:21]
	v_mfma_f32_16x16x32_bf16 v[22:25], v[212:215], v[142:145], v[22:25]
	ds_read_b128 v[138:141], v216 offset:52224
	s_waitcnt lgkmcnt(6)
	v_mfma_f32_16x16x32_bf16 v[26:29], v[200:203], v[146:149], v[26:29]
	v_mfma_f32_16x16x32_bf16 v[30:33], v[212:215], v[146:149], v[30:33]
	ds_read_b128 v[142:145], v216 offset:54272
	s_waitcnt lgkmcnt(6)
	v_mfma_f32_16x16x32_bf16 v[34:37], v[200:203], v[150:153], v[34:37]
	v_mfma_f32_16x16x32_bf16 v[38:41], v[212:215], v[150:153], v[38:41]
	ds_read_b128 v[146:149], v216 offset:56320
	s_waitcnt lgkmcnt(6)
	v_mfma_f32_16x16x32_bf16 v[42:45], v[200:203], v[154:157], v[42:45]
	v_mfma_f32_16x16x32_bf16 v[46:49], v[212:215], v[154:157], v[46:49]
	ds_read_b128 v[150:153], v216 offset:58368
	s_waitcnt lgkmcnt(6)
	v_mfma_f32_16x16x32_bf16 v[50:53], v[200:203], v[158:161], v[50:53]
	v_mfma_f32_16x16x32_bf16 v[54:57], v[212:215], v[158:161], v[54:57]
	ds_read_b128 v[154:157], v216 offset:60416
	s_waitcnt lgkmcnt(6)
	v_mfma_f32_16x16x32_bf16 v[58:61], v[200:203], v[162:165], v[58:61]
	v_mfma_f32_16x16x32_bf16 v[62:65], v[212:215], v[162:165], v[62:65]
	ds_read_b128 v[158:161], v216 offset:62464
	s_waitcnt lgkmcnt(6)
	v_mfma_f32_16x16x32_bf16 v[66:69], v[200:203], v[134:137], v[66:69]
	v_mfma_f32_16x16x32_bf16 v[70:73], v[212:215], v[134:137], v[70:73]
	ds_read_b128 v[162:165], v216 offset:64512
	s_waitcnt vmcnt(4) lgkmcnt(0)
	s_barrier
	v_mfma_f32_16x16x32_bf16 v[74:77], v[200:203], v[138:141], v[74:77]
	s_add_u32 m0, s22, 0x8000
	v_mov_b32_e32 v223, v217
	global_load_lds_dwordx4 v223, s[6:7]
	v_mfma_f32_16x16x32_bf16 v[78:81], v[212:215], v[138:141], v[78:81]
	s_add_u32 m0, s22, 0x8400
	v_add_u32_e32 v224, 0x40, v217
	global_load_lds_dwordx4 v224, s[6:7]
	ds_read_b128 v[134:137], v216
	s_waitcnt lgkmcnt(6)
	v_mfma_f32_16x16x32_bf16 v[82:85], v[200:203], v[142:145], v[82:85]
	s_add_u32 m0, s22, 0x8800
	v_add_u32_e32 v223, 0x20000, v217
	global_load_lds_dwordx4 v223, s[6:7]
	v_mfma_f32_16x16x32_bf16 v[86:89], v[212:215], v[142:145], v[86:89]
	s_add_u32 m0, s22, 0x8c00
	v_add_u32_e32 v224, 0x20040, v217
	global_load_lds_dwordx4 v224, s[6:7]
	ds_read_b128 v[138:141], v216 offset:2048
	s_waitcnt lgkmcnt(6)
	v_mfma_f32_16x16x32_bf16 v[90:93], v[200:203], v[146:149], v[90:93]
	s_add_u32 m0, s22, 0x9000
	v_add_u32_e32 v223, 0x40000, v217
	global_load_lds_dwordx4 v223, s[6:7]
	v_mfma_f32_16x16x32_bf16 v[94:97], v[212:215], v[146:149], v[94:97]
	s_add_u32 m0, s22, 0x9400
	v_add_u32_e32 v224, 0x40040, v217
	global_load_lds_dwordx4 v224, s[6:7]
	ds_read_b128 v[142:145], v216 offset:4096
	s_waitcnt lgkmcnt(6)
	v_mfma_f32_16x16x32_bf16 v[98:101], v[200:203], v[150:153], v[98:101]
	s_add_u32 m0, s22, 0x9800
	v_add_u32_e32 v223, 0x60000, v217
	global_load_lds_dwordx4 v223, s[6:7]
	v_mfma_f32_16x16x32_bf16 v[102:105], v[212:215], v[150:153], v[102:105]
	s_add_u32 m0, s22, 0x9c00
	v_add_u32_e32 v224, 0x60040, v217
	global_load_lds_dwordx4 v224, s[6:7]
	ds_read_b128 v[146:149], v216 offset:6144
	s_waitcnt lgkmcnt(6)
	v_mfma_f32_16x16x32_bf16 v[106:109], v[200:203], v[154:157], v[106:109]
	v_mfma_f32_16x16x32_bf16 v[110:113], v[212:215], v[154:157], v[110:113]
	ds_read_b128 v[150:153], v216 offset:8192
	s_waitcnt lgkmcnt(6)
	v_mfma_f32_16x16x32_bf16 v[114:117], v[200:203], v[158:161], v[114:117]
	v_mfma_f32_16x16x32_bf16 v[118:121], v[212:215], v[158:161], v[118:121]
	ds_read_b128 v[154:157], v216 offset:10240
	s_waitcnt lgkmcnt(6)
	v_mfma_f32_16x16x32_bf16 v[122:125], v[200:203], v[162:165], v[122:125]
	v_mfma_f32_16x16x32_bf16 v[126:129], v[212:215], v[162:165], v[126:129]
	v_add_u32_e32 v217, 0x80, v217
	v_add_u32_e32 v220, 0x800, v220
	v_add_u32_e32 v221, 0x800, v221
	s_sub_u32 s16, s16, 1
	s_cmp_lg_u32 s16, 0
	s_cbranch_scc1 .Lg256b_w2_loop
	s_add_u32 s12, s12, s83
.Lg256b_w2_next_retry:
	s_cmp_ge_u32 s12, 64
	s_cbranch_scc1 .Lg256b_w2_nonext
	s_lshr_b32 s3, s12, 6
	s_lshl_b32 s3, s3, 3
	s_add_u32 s3, s3, s65
	s_mov_b32 s17, s3
	s_mov_b32 s3, 0
	s_lshl_b32 s17, s17, 3
	s_bfe_u32 s23, s12, 0x30003
	s_add_u32 s13, s17, s23
	s_lshl_b32 s3, s3, 3
	s_and_b32 s23, s12, 7
	s_add_u32 s14, s3, s23
	s_lshl_b32 s13, s13, 8
	s_lshl_b32 s14, s14, 7
	s_lshl_b32 s3, s15, 6
	s_add_u32 s17, s3, s13
	s_mul_i32 s17, s17, 0x2000
	s_add_u32 s6, s18, s17
	s_addc_u32 s7, s19, 0
	v_mov_b32_e32 v217, v218
	ds_read_b128 v[158:161], v216 offset:12288
	s_waitcnt vmcnt(8) lgkmcnt(6)
	v_mfma_f32_16x16x32_bf16 v[2:5], v[166:169], v[134:137], v[2:5]
	global_load_dwordx4 v[196:199], v220, s[8:9]
	v_mfma_f32_16x16x32_bf16 v[6:9], v[174:177], v[134:137], v[6:9]
	global_load_dwordx4 v[200:203], v220, s[8:9] offset:1024
	ds_read_b128 v[162:165], v216 offset:14336
	s_waitcnt lgkmcnt(6)
	v_mfma_f32_16x16x32_bf16 v[10:13], v[166:169], v[138:141], v[10:13]
	global_load_dwordx4 v[204:207], v221, s[8:9]
	v_mfma_f32_16x16x32_bf16 v[14:17], v[174:177], v[138:141], v[14:17]
	global_load_dwordx4 v[212:215], v221, s[8:9] offset:1024
	ds_read_b128 v[134:137], v216 offset:16384
	s_waitcnt lgkmcnt(6)
	v_mfma_f32_16x16x32_bf16 v[18:21], v[166:169], v[142:145], v[18:21]
	v_mfma_f32_16x16x32_bf16 v[22:25], v[174:177], v[142:145], v[22:25]
	ds_read_b128 v[138:141], v216 offset:18432
	s_waitcnt lgkmcnt(6)
	v_mfma_f32_16x16x32_bf16 v[26:29], v[166:169], v[146:149], v[26:29]
	v_mfma_f32_16x16x32_bf16 v[30:33], v[174:177], v[146:149], v[30:33]
	ds_read_b128 v[142:145], v216 offset:20480
	s_waitcnt lgkmcnt(6)
	v_mfma_f32_16x16x32_bf16 v[34:37], v[166:169], v[150:153], v[34:37]
	v_mfma_f32_16x16x32_bf16 v[38:41], v[174:177], v[150:153], v[38:41]
	ds_read_b128 v[146:149], v216 offset:22528
	s_waitcnt lgkmcnt(6)
	v_mfma_f32_16x16x32_bf16 v[42:45], v[166:169], v[154:157], v[42:45]
	v_mfma_f32_16x16x32_bf16 v[46:49], v[174:177], v[154:157], v[46:49]
	ds_read_b128 v[150:153], v216 offset:24576
	s_waitcnt lgkmcnt(6)
	v_mfma_f32_16x16x32_bf16 v[50:53], v[166:169], v[158:161], v[50:53]
	v_mfma_f32_16x16x32_bf16 v[54:57], v[174:177], v[158:161], v[54:57]
	ds_read_b128 v[154:157], v216 offset:26624
	s_waitcnt lgkmcnt(6)
	v_mfma_f32_16x16x32_bf16 v[58:61], v[166:169], v[162:165], v[58:61]
	v_mfma_f32_16x16x32_bf16 v[62:65], v[174:177], v[162:165], v[62:65]
	ds_read_b128 v[158:161], v216 offset:28672
	s_waitcnt lgkmcnt(6)
	v_mfma_f32_16x16x32_bf16 v[66:69], v[166:169], v[134:137], v[66:69]
	v_mfma_f32_16x16x32_bf16 v[70:73], v[174:177], v[134:137], v[70:73]
	ds_read_b128 v[162:165], v216 offset:30720
	s_waitcnt lgkmcnt(6)
	v_mfma_f32_16x16x32_bf16 v[74:77], v[166:169], v[138:141], v[74:77]
	v_mfma_f32_16x16x32_bf16 v[78:81], v[174:177], v[138:141], v[78:81]
	ds_read_b128 v[134:137], v216 offset:1024
	s_waitcnt lgkmcnt(6)
	v_mfma_f32_16x16x32_bf16 v[82:85], v[166:169], v[142:145], v[82:85]
	v_mfma_f32_16x16x32_bf16 v[86:89], v[174:177], v[142:145], v[86:89]
	ds_read_b128 v[138:141], v216 offset:3072
	s_waitcnt lgkmcnt(6)
	v_mfma_f32_16x16x32_bf16 v[90:93], v[166:169], v[146:149], v[90:93]
	v_mfma_f32_16x16x32_bf16 v[94:97], v[174:177], v[146:149], v[94:97]
	ds_read_b128 v[142:145], v216 offset:5120
	s_waitcnt lgkmcnt(6)
	v_mfma_f32_16x16x32_bf16 v[98:101], v[166:169], v[150:153], v[98:101]
	v_mfma_f32_16x16x32_bf16 v[102:105], v[174:177], v[150:153], v[102:105]
	ds_read_b128 v[146:149], v216 offset:7168
	s_waitcnt lgkmcnt(6)
	v_mfma_f32_16x16x32_bf16 v[106:109], v[166:169], v[154:157], v[106:109]
	v_mfma_f32_16x16x32_bf16 v[110:113], v[174:177], v[154:157], v[110:113]
	ds_read_b128 v[150:153], v216 offset:9216
	s_waitcnt lgkmcnt(6)
	v_mfma_f32_16x16x32_bf16 v[114:117], v[166:169], v[158:161], v[114:117]
	v_mfma_f32_16x16x32_bf16 v[118:121], v[174:177], v[158:161], v[118:121]
	ds_read_b128 v[154:157], v216 offset:11264
	s_waitcnt lgkmcnt(6)
	v_mfma_f32_16x16x32_bf16 v[122:125], v[166:169], v[162:165], v[122:125]
	v_mfma_f32_16x16x32_bf16 v[126:129], v[174:177], v[162:165], v[126:129]
	ds_read_b128 v[158:161], v216 offset:13312
	s_waitcnt lgkmcnt(6)
	v_mfma_f32_16x16x32_bf16 v[2:5], v[170:173], v[134:137], v[2:5]
	v_mfma_f32_16x16x32_bf16 v[6:9], v[178:181], v[134:137], v[6:9]
	ds_read_b128 v[162:165], v216 offset:15360
	s_waitcnt lgkmcnt(6)
	v_mfma_f32_16x16x32_bf16 v[10:13], v[170:173], v[138:141], v[10:13]
	v_mfma_f32_16x16x32_bf16 v[14:17], v[178:181], v[138:141], v[14:17]
	ds_read_b128 v[134:137], v216 offset:17408
	s_waitcnt lgkmcnt(6)
	v_mfma_f32_16x16x32_bf16 v[18:21], v[170:173], v[142:145], v[18:21]
	v_mfma_f32_16x16x32_bf16 v[22:25], v[178:181], v[142:145], v[22:25]
	ds_read_b128 v[138:141], v216 offset:19456
	s_waitcnt lgkmcnt(6)
	v_mfma_f32_16x16x32_bf16 v[26:29], v[170:173], v[146:149], v[26:29]
	v_mfma_f32_16x16x32_bf16 v[30:33], v[178:181], v[146:149], v[30:33]
	ds_read_b128 v[142:145], v216 offset:21504
	s_waitcnt lgkmcnt(6)
	v_mfma_f32_16x16x32_bf16 v[34:37], v[170:173], v[150:153], v[34:37]
	v_mfma_f32_16x16x32_bf16 v[38:41], v[178:181], v[150:153], v[38:41]
	ds_read_b128 v[146:149], v216 offset:23552
	s_waitcnt lgkmcnt(6)
	v_mfma_f32_16x16x32_bf16 v[42:45], v[170:173], v[154:157], v[42:45]
	v_mfma_f32_16x16x32_bf16 v[46:49], v[178:181], v[154:157], v[46:49]
	ds_read_b128 v[150:153], v216 offset:25600
	s_waitcnt lgkmcnt(6)
	v_mfma_f32_16x16x32_bf16 v[50:53], v[170:173], v[158:161], v[50:53]
	v_mfma_f32_16x16x32_bf16 v[54:57], v[178:181], v[158:161], v[54:57]
	ds_read_b128 v[154:157], v216 offset:27648
	s_waitcnt lgkmcnt(6)
	v_mfma_f32_16x16x32_bf16 v[58:61], v[170:173], v[162:165], v[58:61]
	v_mfma_f32_16x16x32_bf16 v[62:65], v[178:181], v[162:165], v[62:65]
	ds_read_b128 v[158:161], v216 offset:29696
	s_waitcnt lgkmcnt(6)
	v_mfma_f32_16x16x32_bf16 v[66:69], v[170:173], v[134:137], v[66:69]
	v_mfma_f32_16x16x32_bf16 v[70:73], v[178:181], v[134:137], v[70:73]
	ds_read_b128 v[162:165], v216 offset:31744
	s_waitcnt vmcnt(4) lgkmcnt(0)
	s_barrier
	v_mfma_f32_16x16x32_bf16 v[74:77], v[170:173], v[138:141], v[74:77]
	s_add_u32 m0, s22, 0x0
	v_mov_b32_e32 v223, v217
	global_load_lds_dwordx4 v223, s[6:7]
	v_mfma_f32_16x16x32_bf16 v[78:81], v[178:181], v[138:141], v[78:81]
	s_add_u32 m0, s22, 0x400
	v_add_u32_e32 v224, 0x40, v217
	global_load_lds_dwordx4 v224, s[6:7]
	ds_read_b128 v[134:137], v216 offset:32768
	s_waitcnt lgkmcnt(6)
	v_mfma_f32_16x16x32_bf16 v[82:85], v[170:173], v[142:145], v[82:85]
	s_add_u32 m0, s22, 0x800
	v_add_u32_e32 v223, 0x20000, v217
	global_load_lds_dwordx4 v223, s[6:7]
	v_mfma_f32_16x16x32_bf16 v[86:89], v[178:181], v[142:145], v[86:89]
	s_add_u32 m0, s22, 0xc00
	v_add_u32_e32 v224, 0x20040, v217
	global_load_lds_dwordx4 v224, s[6:7]
	ds_read_b128 v[138:141], v216 offset:34816
	s_waitcnt lgkmcnt(6)
	v_mfma_f32_16x16x32_bf16 v[90:93], v[170:173], v[146:149], v[90:93]
	s_add_u32 m0, s22, 0x1000
	v_add_u32_e32 v223, 0x40000, v217
	global_load_lds_dwordx4 v223, s[6:7]
	v_mfma_f32_16x16x32_bf16 v[94:97], v[178:181], v[146:149], v[94:97]
	s_add_u32 m0, s22, 0x1400
	v_add_u32_e32 v224, 0x40040, v217
	global_load_lds_dwordx4 v224, s[6:7]
	ds_read_b128 v[142:145], v216 offset:36864
	s_waitcnt lgkmcnt(6)
	v_mfma_f32_16x16x32_bf16 v[98:101], v[170:173], v[150:153], v[98:101]
	s_add_u32 m0, s22, 0x1800
	v_add_u32_e32 v223, 0x60000, v217
	global_load_lds_dwordx4 v223, s[6:7]
	v_mfma_f32_16x16x32_bf16 v[102:105], v[178:181], v[150:153], v[102:105]
	s_add_u32 m0, s22, 0x1c00
	v_add_u32_e32 v224, 0x60040, v217
	global_load_lds_dwordx4 v224, s[6:7]
	ds_read_b128 v[146:149], v216 offset:38912
	s_waitcnt lgkmcnt(6)
	v_mfma_f32_16x16x32_bf16 v[106:109], v[170:173], v[154:157], v[106:109]
	v_mfma_f32_16x16x32_bf16 v[110:113], v[178:181], v[154:157], v[110:113]
	ds_read_b128 v[150:153], v216 offset:40960
	s_waitcnt lgkmcnt(6)
	v_mfma_f32_16x16x32_bf16 v[114:117], v[170:173], v[158:161], v[114:117]
	v_mfma_f32_16x16x32_bf16 v[118:121], v[178:181], v[158:161], v[118:121]
	ds_read_b128 v[154:157], v216 offset:43008
	s_waitcnt lgkmcnt(6)
	v_mfma_f32_16x16x32_bf16 v[122:125], v[170:173], v[162:165], v[122:125]
	v_mfma_f32_16x16x32_bf16 v[126:129], v[178:181], v[162:165], v[126:129]
	v_add_u32_e32 v217, 0x80, v217
	v_add_u32_e32 v220, 0x800, v220
	v_add_u32_e32 v221, 0x800, v221
	s_lshr_b32 s3, s14, 4
	s_lshl_b32 s17, s15, 1
	s_add_u32 s3, s3, s17
	s_mul_i32 s17, s3, 0x20000
	s_add_u32 s8, s20, s17
	s_addc_u32 s9, s21, 0
	v_mov_b32_e32 v220, v222
	v_add_u32_e32 v221, 0x20000, v222
	ds_read_b128 v[158:161], v216 offset:45056
	s_waitcnt vmcnt(8) lgkmcnt(6)
	v_mfma_f32_16x16x32_bf16 v[2:5], v[196:199], v[134:137], v[2:5]
	global_load_dwordx4 v[166:169], v220, s[8:9]
	v_mfma_f32_16x16x32_bf16 v[6:9], v[204:207], v[134:137], v[6:9]
	global_load_dwordx4 v[170:173], v220, s[8:9] offset:1024
	ds_read_b128 v[162:165], v216 offset:47104
	s_waitcnt lgkmcnt(6)
	v_mfma_f32_16x16x32_bf16 v[10:13], v[196:199], v[138:141], v[10:13]
	global_load_dwordx4 v[174:177], v221, s[8:9]
	v_mfma_f32_16x16x32_bf16 v[14:17], v[204:207], v[138:141], v[14:17]
	global_load_dwordx4 v[178:181], v221, s[8:9] offset:1024
	ds_read_b128 v[134:137], v216 offset:49152
	s_waitcnt lgkmcnt(6)
	v_mfma_f32_16x16x32_bf16 v[18:21], v[196:199], v[142:145], v[18:21]
	v_mfma_f32_16x16x32_bf16 v[22:25], v[204:207], v[142:145], v[22:25]
	ds_read_b128 v[138:141], v216 offset:51200
	s_waitcnt lgkmcnt(6)
	v_mfma_f32_16x16x32_bf16 v[26:29], v[196:199], v[146:149], v[26:29]
	v_mfma_f32_16x16x32_bf16 v[30:33], v[204:207], v[146:149], v[30:33]
	ds_read_b128 v[142:145], v216 offset:53248
	s_waitcnt lgkmcnt(6)
	v_mfma_f32_16x16x32_bf16 v[34:37], v[196:199], v[150:153], v[34:37]
	v_mfma_f32_16x16x32_bf16 v[38:41], v[204:207], v[150:153], v[38:41]
	ds_read_b128 v[146:149], v216 offset:55296
	s_waitcnt lgkmcnt(6)
	v_mfma_f32_16x16x32_bf16 v[42:45], v[196:199], v[154:157], v[42:45]
	v_mfma_f32_16x16x32_bf16 v[46:49], v[204:207], v[154:157], v[46:49]
	ds_read_b128 v[150:153], v216 offset:57344
	s_waitcnt lgkmcnt(6)
	v_mfma_f32_16x16x32_bf16 v[50:53], v[196:199], v[158:161], v[50:53]
	v_mfma_f32_16x16x32_bf16 v[54:57], v[204:207], v[158:161], v[54:57]
	ds_read_b128 v[154:157], v216 offset:59392
	s_waitcnt lgkmcnt(6)
	v_mfma_f32_16x16x32_bf16 v[58:61], v[196:199], v[162:165], v[58:61]
	v_mfma_f32_16x16x32_bf16 v[62:65], v[204:207], v[162:165], v[62:65]
	ds_read_b128 v[158:161], v216 offset:61440
	s_waitcnt lgkmcnt(6)
	v_mfma_f32_16x16x32_bf16 v[66:69], v[196:199], v[134:137], v[66:69]
	v_mfma_f32_16x16x32_bf16 v[70:73], v[204:207], v[134:137], v[70:73]
	ds_read_b128 v[162:165], v216 offset:63488
	s_waitcnt lgkmcnt(6)
	v_mfma_f32_16x16x32_bf16 v[74:77], v[196:199], v[138:141], v[74:77]
	v_mfma_f32_16x16x32_bf16 v[78:81], v[204:207], v[138:141], v[78:81]
	ds_read_b128 v[134:137], v216 offset:33792
	s_waitcnt lgkmcnt(6)
	v_mfma_f32_16x16x32_bf16 v[82:85], v[196:199], v[142:145], v[82:85]
	v_mfma_f32_16x16x32_bf16 v[86:89], v[204:207], v[142:145], v[86:89]
	ds_read_b128 v[138:141], v216 offset:35840
	s_waitcnt lgkmcnt(6)
	v_mfma_f32_16x16x32_bf16 v[90:93], v[196:199], v[146:149], v[90:93]
	v_mfma_f32_16x16x32_bf16 v[94:97], v[204:207], v[146:149], v[94:97]
	ds_read_b128 v[142:145], v216 offset:37888
	s_waitcnt lgkmcnt(6)
	v_mfma_f32_16x16x32_bf16 v[98:101], v[196:199], v[150:153], v[98:101]
	v_mfma_f32_16x16x32_bf16 v[102:105], v[204:207], v[150:153], v[102:105]
	ds_read_b128 v[146:149], v216 offset:39936
	s_waitcnt lgkmcnt(6)
	v_mfma_f32_16x16x32_bf16 v[106:109], v[196:199], v[154:157], v[106:109]
	v_mfma_f32_16x16x32_bf16 v[110:113], v[204:207], v[154:157], v[110:113]
	ds_read_b128 v[150:153], v216 offset:41984
	s_waitcnt lgkmcnt(6)
	v_mfma_f32_16x16x32_bf16 v[114:117], v[196:199], v[158:161], v[114:117]
	v_mfma_f32_16x16x32_bf16 v[118:121], v[204:207], v[158:161], v[118:121]
	ds_read_b128 v[154:157], v216 offset:44032
	s_waitcnt lgkmcnt(6)
	v_mfma_f32_16x16x32_bf16 v[122:125], v[196:199], v[162:165], v[122:125]
	v_mfma_f32_16x16x32_bf16 v[126:129], v[204:207], v[162:165], v[126:129]
	ds_read_b128 v[158:161], v216 offset:46080
	s_waitcnt lgkmcnt(6)
	v_mfma_f32_16x16x32_bf16 v[2:5], v[200:203], v[134:137], v[2:5]
	v_mfma_f32_16x16x32_bf16 v[6:9], v[212:215], v[134:137], v[6:9]
	ds_read_b128 v[162:165], v216 offset:48128
	s_waitcnt lgkmcnt(6)
	v_mfma_f32_16x16x32_bf16 v[10:13], v[200:203], v[138:141], v[10:13]
	v_mfma_f32_16x16x32_bf16 v[14:17], v[212:215], v[138:141], v[14:17]
	ds_read_b128 v[134:137], v216 offset:50176
	s_waitcnt lgkmcnt(6)
	v_mfma_f32_16x16x32_bf16 v[18:21], v[200:203], v[142:145], v[18:21]
	v_mfma_f32_16x16x32_bf16 v[22:25], v[212:215], v[142:145], v[22:25]
	ds_read_b128 v[138:141], v216 offset:52224
	s_waitcnt lgkmcnt(6)
	v_mfma_f32_16x16x32_bf16 v[26:29], v[200:203], v[146:149], v[26:29]
	v_mfma_f32_16x16x32_bf16 v[30:33], v[212:215], v[146:149], v[30:33]
	ds_read_b128 v[142:145], v216 offset:54272
	s_waitcnt lgkmcnt(6)
	v_mfma_f32_16x16x32_bf16 v[34:37], v[200:203], v[150:153], v[34:37]
	v_mfma_f32_16x16x32_bf16 v[38:41], v[212:215], v[150:153], v[38:41]
	ds_read_b128 v[146:149], v216 offset:56320
	s_waitcnt lgkmcnt(6)
	v_mfma_f32_16x16x32_bf16 v[42:45], v[200:203], v[154:157], v[42:45]
	v_mfma_f32_16x16x32_bf16 v[46:49], v[212:215], v[154:157], v[46:49]
	ds_read_b128 v[150:153], v216 offset:58368
	s_waitcnt lgkmcnt(6)
	v_mfma_f32_16x16x32_bf16 v[50:53], v[200:203], v[158:161], v[50:53]
	v_mfma_f32_16x16x32_bf16 v[54:57], v[212:215], v[158:161], v[54:57]
	ds_read_b128 v[154:157], v216 offset:60416
	s_waitcnt lgkmcnt(6)
	v_mfma_f32_16x16x32_bf16 v[58:61], v[200:203], v[162:165], v[58:61]
	v_mfma_f32_16x16x32_bf16 v[62:65], v[212:215], v[162:165], v[62:65]
	ds_read_b128 v[158:161], v216 offset:62464
	s_waitcnt lgkmcnt(6)
	v_mfma_f32_16x16x32_bf16 v[66:69], v[200:203], v[134:137], v[66:69]
	v_mfma_f32_16x16x32_bf16 v[70:73], v[212:215], v[134:137], v[70:73]
	ds_read_b128 v[162:165], v216 offset:64512
	s_waitcnt vmcnt(4) lgkmcnt(0)
	s_barrier
	v_mfma_f32_16x16x32_bf16 v[74:77], v[200:203], v[138:141], v[74:77]
	s_add_u32 m0, s22, 0x8000
	v_mov_b32_e32 v223, v217
	global_load_lds_dwordx4 v223, s[6:7]
	v_mfma_f32_16x16x32_bf16 v[78:81], v[212:215], v[138:141], v[78:81]
	s_add_u32 m0, s22, 0x8400
	v_add_u32_e32 v224, 0x40, v217
	global_load_lds_dwordx4 v224, s[6:7]
	ds_read_b128 v[134:137], v216
	s_waitcnt lgkmcnt(6)
	v_mfma_f32_16x16x32_bf16 v[82:85], v[200:203], v[142:145], v[82:85]
	s_add_u32 m0, s22, 0x8800
	v_add_u32_e32 v223, 0x20000, v217
	global_load_lds_dwordx4 v223, s[6:7]
	v_mfma_f32_16x16x32_bf16 v[86:89], v[212:215], v[142:145], v[86:89]
	s_add_u32 m0, s22, 0x8c00
	v_add_u32_e32 v224, 0x20040, v217
	global_load_lds_dwordx4 v224, s[6:7]
	ds_read_b128 v[138:141], v216 offset:2048
	s_waitcnt lgkmcnt(6)
	v_mfma_f32_16x16x32_bf16 v[90:93], v[200:203], v[146:149], v[90:93]
	s_add_u32 m0, s22, 0x9000
	v_add_u32_e32 v223, 0x40000, v217
	global_load_lds_dwordx4 v223, s[6:7]
	v_mfma_f32_16x16x32_bf16 v[94:97], v[212:215], v[146:149], v[94:97]
	s_add_u32 m0, s22, 0x9400
	v_add_u32_e32 v224, 0x40040, v217
	global_load_lds_dwordx4 v224, s[6:7]
	ds_read_b128 v[142:145], v216 offset:4096
	s_waitcnt lgkmcnt(6)
	v_mfma_f32_16x16x32_bf16 v[98:101], v[200:203], v[150:153], v[98:101]
	s_add_u32 m0, s22, 0x9800
	v_add_u32_e32 v223, 0x60000, v217
	global_load_lds_dwordx4 v223, s[6:7]
	v_mfma_f32_16x16x32_bf16 v[102:105], v[212:215], v[150:153], v[102:105]
	s_add_u32 m0, s22, 0x9c00
	v_add_u32_e32 v224, 0x60040, v217
	global_load_lds_dwordx4 v224, s[6:7]
	ds_read_b128 v[146:149], v216 offset:6144
	s_waitcnt lgkmcnt(6)
	v_mfma_f32_16x16x32_bf16 v[106:109], v[200:203], v[154:157], v[106:109]
	v_mfma_f32_16x16x32_bf16 v[110:113], v[212:215], v[154:157], v[110:113]
	ds_read_b128 v[150:153], v216 offset:8192
	s_waitcnt lgkmcnt(6)
	v_mfma_f32_16x16x32_bf16 v[114:117], v[200:203], v[158:161], v[114:117]
	v_mfma_f32_16x16x32_bf16 v[118:121], v[212:215], v[158:161], v[118:121]
	ds_read_b128 v[154:157], v216 offset:10240
	s_waitcnt lgkmcnt(6)
	v_mfma_f32_16x16x32_bf16 v[122:125], v[200:203], v[162:165], v[122:125]
	v_mfma_f32_16x16x32_bf16 v[126:129], v[212:215], v[162:165], v[126:129]
	v_add_u32_e32 v217, 0x80, v217
	v_add_u32_e32 v220, 0x800, v220
	v_add_u32_e32 v221, 0x800, v221
	s_mov_b32 s16, 1
	s_branch .Lg256b_w2_epi

.Lg256b_w2_epi:
	global_load_dwordx4 v[226:229], v234, s[4:5]
	global_load_dwordx4 v[230:233], v234, s[4:5] offset:64
	global_load_dwordx4 v[158:161], v219, s[26:27]
	global_load_dwordx4 v[162:165], v219, s[26:27] offset:64
	v_add_u32_e32 v249, 0x10000, v219
	global_load_dwordx4 v[196:199], v249, s[26:27]
	global_load_dwordx4 v[200:203], v249, s[26:27] offset:64
	v_add_u32_e32 v248, 0x20000, v219
	global_load_dwordx4 v[204:207], v248, s[26:27]
	global_load_dwordx4 v[212:215], v248, s[26:27] offset:64
	v_add_u32_e32 v249, 0x30000, v219
	global_load_dwordx4 v[240:243], v249, s[26:27]
	global_load_dwordx4 v[244:247], v249, s[26:27] offset:64
	s_waitcnt vmcnt(0)
	v_pk_fma_f32 v[2:3], v[226:227], v[2:3], v[158:159]
	v_pk_fma_f32 v[4:5], v[228:229], v[4:5], v[160:161]
	v_pk_fma_f32 v[6:7], v[230:231], v[6:7], v[162:163]
	v_pk_fma_f32 v[8:9], v[232:233], v[8:9], v[164:165]
	v_pk_fma_f32 v[10:11], v[226:227], v[10:11], v[196:197]
	v_pk_fma_f32 v[12:13], v[228:229], v[12:13], v[198:199]
	v_pk_fma_f32 v[14:15], v[230:231], v[14:15], v[200:201]
	v_pk_fma_f32 v[16:17], v[232:233], v[16:17], v[202:203]
	v_pk_fma_f32 v[18:19], v[226:227], v[18:19], v[204:205]
	v_pk_fma_f32 v[20:21], v[228:229], v[20:21], v[206:207]
	v_pk_fma_f32 v[22:23], v[230:231], v[22:23], v[212:213]
	v_pk_fma_f32 v[24:25], v[232:233], v[24:25], v[214:215]
	v_pk_fma_f32 v[26:27], v[226:227], v[26:27], v[240:241]
	v_pk_fma_f32 v[28:29], v[228:229], v[28:29], v[242:243]
	v_pk_fma_f32 v[30:31], v[230:231], v[30:31], v[244:245]
	v_pk_fma_f32 v[32:33], v[232:233], v[32:33], v[246:247]
	v_add_u32_e32 v248, 0x40000, v219
	global_load_dwordx4 v[158:161], v248, s[26:27]
	global_load_dwordx4 v[162:165], v248, s[26:27] offset:64
	v_add_u32_e32 v249, 0x50000, v219
	global_load_dwordx4 v[196:199], v249, s[26:27]
	global_load_dwordx4 v[200:203], v249, s[26:27] offset:64
	v_add_u32_e32 v248, 0x60000, v219
	global_load_dwordx4 v[204:207], v248, s[26:27]
	global_load_dwordx4 v[212:215], v248, s[26:27] offset:64
	v_add_u32_e32 v249, 0x70000, v219
	global_load_dwordx4 v[240:243], v249, s[26:27]
	global_load_dwordx4 v[244:247], v249, s[26:27] offset:64
	global_store_dwordx4 v219, v[2:5], s[10:11]
	global_store_dwordx4 v219, v[6:9], s[10:11] offset:64
	v_add_u32_e32 v251, 0x10000, v219
	global_store_dwordx4 v251, v[10:13], s[10:11]
	global_store_dwordx4 v251, v[14:17], s[10:11] offset:64
	v_add_u32_e32 v250, 0x20000, v219
	global_store_dwordx4 v250, v[18:21], s[10:11]
	global_store_dwordx4 v250, v[22:25], s[10:11] offset:64
	v_add_u32_e32 v251, 0x30000, v219
	global_store_dwordx4 v251, v[26:29], s[10:11]
	global_store_dwordx4 v251, v[30:33], s[10:11] offset:64
	s_waitcnt vmcnt(8)
	v_pk_fma_f32 v[34:35], v[226:227], v[34:35], v[158:159]
	v_pk_fma_f32 v[36:37], v[228:229], v[36:37], v[160:161]
	v_pk_fma_f32 v[38:39], v[230:231], v[38:39], v[162:163]
	v_pk_fma_f32 v[40:41], v[232:233], v[40:41], v[164:165]
	v_pk_fma_f32 v[42:43], v[226:227], v[42:43], v[196:197]
	v_pk_fma_f32 v[44:45], v[228:229], v[44:45], v[198:199]
	v_pk_fma_f32 v[46:47], v[230:231], v[46:47], v[200:201]
	v_pk_fma_f32 v[48:49], v[232:233], v[48:49], v[202:203]
	v_pk_fma_f32 v[50:51], v[226:227], v[50:51], v[204:205]
	v_pk_fma_f32 v[52:53], v[228:229], v[52:53], v[206:207]
	v_pk_fma_f32 v[54:55], v[230:231], v[54:55], v[212:213]
	v_pk_fma_f32 v[56:57], v[232:233], v[56:57], v[214:215]
	v_pk_fma_f32 v[58:59], v[226:227], v[58:59], v[240:241]
	v_pk_fma_f32 v[60:61], v[228:229], v[60:61], v[242:243]
	v_pk_fma_f32 v[62:63], v[230:231], v[62:63], v[244:245]
	v_pk_fma_f32 v[64:65], v[232:233], v[64:65], v[246:247]
	v_add_u32_e32 v248, 0x80000, v219
	global_load_dwordx4 v[158:161], v248, s[26:27]
	global_load_dwordx4 v[162:165], v248, s[26:27] offset:64
	v_add_u32_e32 v249, 0x90000, v219
	global_load_dwordx4 v[196:199], v249, s[26:27]
	global_load_dwordx4 v[200:203], v249, s[26:27] offset:64
	v_add_u32_e32 v248, 0xa0000, v219
	global_load_dwordx4 v[204:207], v248, s[26:27]
	global_load_dwordx4 v[212:215], v248, s[26:27] offset:64
	v_add_u32_e32 v249, 0xb0000, v219
	global_load_dwordx4 v[240:243], v249, s[26:27]
	global_load_dwordx4 v[244:247], v249, s[26:27] offset:64
	v_add_u32_e32 v250, 0x40000, v219
	global_store_dwordx4 v250, v[34:37], s[10:11]
	global_store_dwordx4 v250, v[38:41], s[10:11] offset:64
	v_add_u32_e32 v251, 0x50000, v219
	global_store_dwordx4 v251, v[42:45], s[10:11]
	global_store_dwordx4 v251, v[46:49], s[10:11] offset:64
	v_add_u32_e32 v250, 0x60000, v219
	global_store_dwordx4 v250, v[50:53], s[10:11]
	global_store_dwordx4 v250, v[54:57], s[10:11] offset:64
	v_add_u32_e32 v251, 0x70000, v219
	global_store_dwordx4 v251, v[58:61], s[10:11]
	global_store_dwordx4 v251, v[62:65], s[10:11] offset:64
	s_waitcnt vmcnt(8)
	v_pk_fma_f32 v[66:67], v[226:227], v[66:67], v[158:159]
	v_pk_fma_f32 v[68:69], v[228:229], v[68:69], v[160:161]
	v_pk_fma_f32 v[70:71], v[230:231], v[70:71], v[162:163]
	v_pk_fma_f32 v[72:73], v[232:233], v[72:73], v[164:165]
	v_pk_fma_f32 v[74:75], v[226:227], v[74:75], v[196:197]
	v_pk_fma_f32 v[76:77], v[228:229], v[76:77], v[198:199]
	v_pk_fma_f32 v[78:79], v[230:231], v[78:79], v[200:201]
	v_pk_fma_f32 v[80:81], v[232:233], v[80:81], v[202:203]
	v_pk_fma_f32 v[82:83], v[226:227], v[82:83], v[204:205]
	v_pk_fma_f32 v[84:85], v[228:229], v[84:85], v[206:207]
	v_pk_fma_f32 v[86:87], v[230:231], v[86:87], v[212:213]
	v_pk_fma_f32 v[88:89], v[232:233], v[88:89], v[214:215]
	v_pk_fma_f32 v[90:91], v[226:227], v[90:91], v[240:241]
	v_pk_fma_f32 v[92:93], v[228:229], v[92:93], v[242:243]
	v_pk_fma_f32 v[94:95], v[230:231], v[94:95], v[244:245]
	v_pk_fma_f32 v[96:97], v[232:233], v[96:97], v[246:247]
	v_add_u32_e32 v248, 0xc0000, v219
	global_load_dwordx4 v[158:161], v248, s[26:27]
	global_load_dwordx4 v[162:165], v248, s[26:27] offset:64
	v_add_u32_e32 v249, 0xd0000, v219
	global_load_dwordx4 v[196:199], v249, s[26:27]
	global_load_dwordx4 v[200:203], v249, s[26:27] offset:64
	v_add_u32_e32 v248, 0xe0000, v219
	global_load_dwordx4 v[204:207], v248, s[26:27]
	global_load_dwordx4 v[212:215], v248, s[26:27] offset:64
	v_add_u32_e32 v249, 0xf0000, v219
	global_load_dwordx4 v[240:243], v249, s[26:27]
	global_load_dwordx4 v[244:247], v249, s[26:27] offset:64
	v_add_u32_e32 v250, 0x80000, v219
	global_store_dwordx4 v250, v[66:69], s[10:11]
	global_store_dwordx4 v250, v[70:73], s[10:11] offset:64
	v_add_u32_e32 v251, 0x90000, v219
	global_store_dwordx4 v251, v[74:77], s[10:11]
	global_store_dwordx4 v251, v[78:81], s[10:11] offset:64
	v_add_u32_e32 v250, 0xa0000, v219
	global_store_dwordx4 v250, v[82:85], s[10:11]
	global_store_dwordx4 v250, v[86:89], s[10:11] offset:64
	v_add_u32_e32 v251, 0xb0000, v219
	global_store_dwordx4 v251, v[90:93], s[10:11]
	global_store_dwordx4 v251, v[94:97], s[10:11] offset:64
	s_waitcnt vmcnt(8)
	v_pk_fma_f32 v[98:99], v[226:227], v[98:99], v[158:159]
	v_pk_fma_f32 v[100:101], v[228:229], v[100:101], v[160:161]
	v_pk_fma_f32 v[102:103], v[230:231], v[102:103], v[162:163]
	v_pk_fma_f32 v[104:105], v[232:233], v[104:105], v[164:165]
	v_pk_fma_f32 v[106:107], v[226:227], v[106:107], v[196:197]
	v_pk_fma_f32 v[108:109], v[228:229], v[108:109], v[198:199]
	v_pk_fma_f32 v[110:111], v[230:231], v[110:111], v[200:201]
	v_pk_fma_f32 v[112:113], v[232:233], v[112:113], v[202:203]
	v_pk_fma_f32 v[114:115], v[226:227], v[114:115], v[204:205]
	v_pk_fma_f32 v[116:117], v[228:229], v[116:117], v[206:207]
	v_pk_fma_f32 v[118:119], v[230:231], v[118:119], v[212:213]
	v_pk_fma_f32 v[120:121], v[232:233], v[120:121], v[214:215]
	v_pk_fma_f32 v[122:123], v[226:227], v[122:123], v[240:241]
	v_pk_fma_f32 v[124:125], v[228:229], v[124:125], v[242:243]
	v_pk_fma_f32 v[126:127], v[230:231], v[126:127], v[244:245]
	v_pk_fma_f32 v[128:129], v[232:233], v[128:129], v[246:247]
	v_add_u32_e32 v250, 0xc0000, v219
	global_store_dwordx4 v250, v[98:101], s[10:11]
	global_store_dwordx4 v250, v[102:105], s[10:11] offset:64
	v_add_u32_e32 v251, 0xd0000, v219
	global_store_dwordx4 v251, v[106:109], s[10:11]
	global_store_dwordx4 v251, v[110:113], s[10:11] offset:64
	v_add_u32_e32 v250, 0xe0000, v219
	global_store_dwordx4 v250, v[114:117], s[10:11]
	global_store_dwordx4 v250, v[118:121], s[10:11] offset:64
	v_add_u32_e32 v251, 0xf0000, v219
	global_store_dwordx4 v251, v[122:125], s[10:11]
	global_store_dwordx4 v251, v[126:129], s[10:11] offset:64
	s_cmp_lg_u32 s16, 0
	s_cbranch_scc1 .Lg256b_w2_tile

.Lg256b_w1_first_retry:
	s_cmp_ge_u32 s12, 256
	s_cbranch_scc1 .Lg256b_w1_done
	s_lshr_b32 s3, s12, 6
	s_lshl_b32 s3, s3, 3
	s_add_u32 s3, s3, s65
	s_lshr_b32 s17, s3, 2
	s_and_b32 s3, s3, 3
	s_lshl_b32 s17, s17, 3
	s_bfe_u32 s23, s12, 0x30003
	s_add_u32 s13, s17, s23
	s_lshl_b32 s3, s3, 3
	s_and_b32 s23, s12, 7
	s_add_u32 s14, s3, s23
	s_lshl_b32 s13, s13, 8
	s_lshl_b32 s14, s14, 7
	s_lshl_b32 s3, s15, 6
	s_add_u32 s17, s3, s13
	s_mul_i32 s17, s17, 0x800
	s_add_u32 s6, s18, s17
	s_addc_u32 s7, s19, 0
	s_lshr_b32 s3, s14, 4
	s_lshl_b32 s17, s15, 1
	s_add_u32 s3, s3, s17
	s_mul_i32 s17, s3, 0x8000
	s_add_u32 s8, s20, s17
	s_addc_u32 s9, s21, 0
	s_barrier
	v_mov_b32_e32 v217, v218
	v_mov_b32_e32 v220, v222
	v_add_u32_e32 v221, 0x8000, v222
	s_add_u32 m0, s22, 0x0
	v_mov_b32_e32 v223, v217
	global_load_lds_dwordx4 v223, s[6:7]
	s_add_u32 m0, s22, 0x400
	v_add_u32_e32 v224, 0x40, v217
	global_load_lds_dwordx4 v224, s[6:7]
	s_add_u32 m0, s22, 0x800
	v_add_u32_e32 v223, 0x8000, v217
	global_load_lds_dwordx4 v223, s[6:7]
	s_add_u32 m0, s22, 0xc00
	v_add_u32_e32 v224, 0x8040, v217
	global_load_lds_dwordx4 v224, s[6:7]
	s_add_u32 m0, s22, 0x1000
	v_add_u32_e32 v223, 0x10000, v217
	global_load_lds_dwordx4 v223, s[6:7]
	s_add_u32 m0, s22, 0x1400
	v_add_u32_e32 v224, 0x10040, v217
	global_load_lds_dwordx4 v224, s[6:7]
	s_add_u32 m0, s22, 0x1800
	v_add_u32_e32 v223, 0x18000, v217
	global_load_lds_dwordx4 v223, s[6:7]
	s_add_u32 m0, s22, 0x1c00
	v_add_u32_e32 v224, 0x18040, v217
	global_load_lds_dwordx4 v224, s[6:7]
	v_add_u32_e32 v217, 0x80, v217
	s_add_u32 m0, s22, 0x8000
	v_mov_b32_e32 v223, v217
	global_load_lds_dwordx4 v223, s[6:7]
	s_add_u32 m0, s22, 0x8400
	v_add_u32_e32 v224, 0x40, v217
	global_load_lds_dwordx4 v224, s[6:7]
	s_add_u32 m0, s22, 0x8800
	v_add_u32_e32 v223, 0x8000, v217
	global_load_lds_dwordx4 v223, s[6:7]
	s_add_u32 m0, s22, 0x8c00
	v_add_u32_e32 v224, 0x8040, v217
	global_load_lds_dwordx4 v224, s[6:7]
	s_add_u32 m0, s22, 0x9000
	v_add_u32_e32 v223, 0x10000, v217
	global_load_lds_dwordx4 v223, s[6:7]
	s_add_u32 m0, s22, 0x9400
	v_add_u32_e32 v224, 0x10040, v217
	global_load_lds_dwordx4 v224, s[6:7]
	s_add_u32 m0, s22, 0x9800
	v_add_u32_e32 v223, 0x18000, v217
	global_load_lds_dwordx4 v223, s[6:7]
	s_add_u32 m0, s22, 0x9c00
	v_add_u32_e32 v224, 0x18040, v217
	global_load_lds_dwordx4 v224, s[6:7]
	v_add_u32_e32 v217, 0x80, v217
	global_load_dwordx4 v[166:169], v220, s[8:9]
	global_load_dwordx4 v[170:173], v220, s[8:9] offset:1024
	global_load_dwordx4 v[174:177], v221, s[8:9]
	global_load_dwordx4 v[178:181], v221, s[8:9] offset:1024
	v_add_u32_e32 v220, 0x800, v220
	v_add_u32_e32 v221, 0x800, v221
	s_waitcnt vmcnt(0)
	s_barrier
	ds_read_b128 v[134:137], v216
	ds_read_b128 v[138:141], v216 offset:2048
	ds_read_b128 v[142:145], v216 offset:4096
	ds_read_b128 v[146:149], v216 offset:6144
	ds_read_b128 v[150:153], v216 offset:8192
	ds_read_b128 v[154:157], v216 offset:10240

.Lg256b_w1_next_retry:
	s_cmp_ge_u32 s12, 256
	s_cbranch_scc1 .Lg256b_w1_nonext
	s_lshr_b32 s3, s12, 6
	s_lshl_b32 s3, s3, 3
	s_add_u32 s3, s3, s65
	s_lshr_b32 s17, s3, 2
	s_and_b32 s3, s3, 3
	s_lshl_b32 s17, s17, 3
	s_bfe_u32 s23, s12, 0x30003
	s_add_u32 s13, s17, s23
	s_lshl_b32 s3, s3, 3
	s_and_b32 s23, s12, 7
	s_add_u32 s14, s3, s23
	s_lshl_b32 s13, s13, 8
	s_lshl_b32 s14, s14, 7
	s_lshl_b32 s3, s15, 6
	s_add_u32 s17, s3, s13
	s_mul_i32 s17, s17, 0x800
	s_add_u32 s6, s18, s17
	s_addc_u32 s7, s19, 0
	v_mov_b32_e32 v217, v218
	ds_read_b128 v[158:161], v216 offset:12288
	s_waitcnt vmcnt(8) lgkmcnt(6)
	v_mfma_f32_16x16x32_bf16 v[2:5], v[166:169], v[134:137], v[2:5]
	global_load_dwordx4 v[196:199], v220, s[8:9]
	v_mfma_f32_16x16x32_bf16 v[6:9], v[174:177], v[134:137], v[6:9]
	global_load_dwordx4 v[200:203], v220, s[8:9] offset:1024
	ds_read_b128 v[162:165], v216 offset:14336
	s_waitcnt lgkmcnt(6)
	v_mfma_f32_16x16x32_bf16 v[10:13], v[166:169], v[138:141], v[10:13]
	global_load_dwordx4 v[204:207], v221, s[8:9]
	v_mfma_f32_16x16x32_bf16 v[14:17], v[174:177], v[138:141], v[14:17]
	global_load_dwordx4 v[212:215], v221, s[8:9] offset:1024
	ds_read_b128 v[134:137], v216 offset:16384
	s_waitcnt lgkmcnt(6)
	v_mfma_f32_16x16x32_bf16 v[18:21], v[166:169], v[142:145], v[18:21]
	v_mfma_f32_16x16x32_bf16 v[22:25], v[174:177], v[142:145], v[22:25]
	ds_read_b128 v[138:141], v216 offset:18432
	s_waitcnt lgkmcnt(6)
	v_mfma_f32_16x16x32_bf16 v[26:29], v[166:169], v[146:149], v[26:29]
	v_mfma_f32_16x16x32_bf16 v[30:33], v[174:177], v[146:149], v[30:33]
	ds_read_b128 v[142:145], v216 offset:20480
	s_waitcnt lgkmcnt(6)
	v_mfma_f32_16x16x32_bf16 v[34:37], v[166:169], v[150:153], v[34:37]
	v_mfma_f32_16x16x32_bf16 v[38:41], v[174:177], v[150:153], v[38:41]
	ds_read_b128 v[146:149], v216 offset:22528
	s_waitcnt lgkmcnt(6)
	v_mfma_f32_16x16x32_bf16 v[42:45], v[166:169], v[154:157], v[42:45]
	v_mfma_f32_16x16x32_bf16 v[46:49], v[174:177], v[154:157], v[46:49]
	ds_read_b128 v[150:153], v216 offset:24576
	s_waitcnt lgkmcnt(6)
	v_mfma_f32_16x16x32_bf16 v[50:53], v[166:169], v[158:161], v[50:53]
	v_mfma_f32_16x16x32_bf16 v[54:57], v[174:177], v[158:161], v[54:57]
	ds_read_b128 v[154:157], v216 offset:26624
	s_waitcnt lgkmcnt(6)
	v_mfma_f32_16x16x32_bf16 v[58:61], v[166:169], v[162:165], v[58:61]
	v_mfma_f32_16x16x32_bf16 v[62:65], v[174:177], v[162:165], v[62:65]
	ds_read_b128 v[158:161], v216 offset:28672
	s_waitcnt lgkmcnt(6)
	v_mfma_f32_16x16x32_bf16 v[66:69], v[166:169], v[134:137], v[66:69]
	v_mfma_f32_16x16x32_bf16 v[70:73], v[174:177], v[134:137], v[70:73]
	ds_read_b128 v[162:165], v216 offset:30720
	s_waitcnt lgkmcnt(6)
	v_mfma_f32_16x16x32_bf16 v[74:77], v[166:169], v[138:141], v[74:77]
	v_mfma_f32_16x16x32_bf16 v[78:81], v[174:177], v[138:141], v[78:81]
	ds_read_b128 v[134:137], v216 offset:1024
	s_waitcnt lgkmcnt(6)
	v_mfma_f32_16x16x32_bf16 v[82:85], v[166:169], v[142:145], v[82:85]
	v_mfma_f32_16x16x32_bf16 v[86:89], v[174:177], v[142:145], v[86:89]
	ds_read_b128 v[138:141], v216 offset:3072
	s_waitcnt lgkmcnt(6)
	v_mfma_f32_16x16x32_bf16 v[90:93], v[166:169], v[146:149], v[90:93]
	v_mfma_f32_16x16x32_bf16 v[94:97], v[174:177], v[146:149], v[94:97]
	ds_read_b128 v[142:145], v216 offset:5120
	s_waitcnt lgkmcnt(6)
	v_mfma_f32_16x16x32_bf16 v[98:101], v[166:169], v[150:153], v[98:101]
	v_mfma_f32_16x16x32_bf16 v[102:105], v[174:177], v[150:153], v[102:105]
	ds_read_b128 v[146:149], v216 offset:7168
	s_waitcnt lgkmcnt(6)
	v_mfma_f32_16x16x32_bf16 v[106:109], v[166:169], v[154:157], v[106:109]
	v_mfma_f32_16x16x32_bf16 v[110:113], v[174:177], v[154:157], v[110:113]
	ds_read_b128 v[150:153], v216 offset:9216
	s_waitcnt lgkmcnt(6)
	v_mfma_f32_16x16x32_bf16 v[114:117], v[166:169], v[158:161], v[114:117]
	v_mfma_f32_16x16x32_bf16 v[118:121], v[174:177], v[158:161], v[118:121]
	ds_read_b128 v[154:157], v216 offset:11264
	s_waitcnt lgkmcnt(6)
	v_mfma_f32_16x16x32_bf16 v[122:125], v[166:169], v[162:165], v[122:125]
	v_mfma_f32_16x16x32_bf16 v[126:129], v[174:177], v[162:165], v[126:129]
	ds_read_b128 v[158:161], v216 offset:13312
	s_waitcnt lgkmcnt(6)
	v_mfma_f32_16x16x32_bf16 v[2:5], v[170:173], v[134:137], v[2:5]
	v_mfma_f32_16x16x32_bf16 v[6:9], v[178:181], v[134:137], v[6:9]
	ds_read_b128 v[162:165], v216 offset:15360
	s_waitcnt lgkmcnt(6)
	v_mfma_f32_16x16x32_bf16 v[10:13], v[170:173], v[138:141], v[10:13]
	v_mfma_f32_16x16x32_bf16 v[14:17], v[178:181], v[138:141], v[14:17]
	ds_read_b128 v[134:137], v216 offset:17408
	s_waitcnt lgkmcnt(6)
	v_mfma_f32_16x16x32_bf16 v[18:21], v[170:173], v[142:145], v[18:21]
	v_mfma_f32_16x16x32_bf16 v[22:25], v[178:181], v[142:145], v[22:25]
	ds_read_b128 v[138:141], v216 offset:19456
	s_waitcnt lgkmcnt(6)
	v_mfma_f32_16x16x32_bf16 v[26:29], v[170:173], v[146:149], v[26:29]
	v_mfma_f32_16x16x32_bf16 v[30:33], v[178:181], v[146:149], v[30:33]
	ds_read_b128 v[142:145], v216 offset:21504
	s_waitcnt lgkmcnt(6)
	v_mfma_f32_16x16x32_bf16 v[34:37], v[170:173], v[150:153], v[34:37]
	v_mfma_f32_16x16x32_bf16 v[38:41], v[178:181], v[150:153], v[38:41]
	ds_read_b128 v[146:149], v216 offset:23552
	s_waitcnt lgkmcnt(6)
	v_mfma_f32_16x16x32_bf16 v[42:45], v[170:173], v[154:157], v[42:45]
	v_mfma_f32_16x16x32_bf16 v[46:49], v[178:181], v[154:157], v[46:49]
	ds_read_b128 v[150:153], v216 offset:25600
	s_waitcnt lgkmcnt(6)
	v_mfma_f32_16x16x32_bf16 v[50:53], v[170:173], v[158:161], v[50:53]
	v_mfma_f32_16x16x32_bf16 v[54:57], v[178:181], v[158:161], v[54:57]
	ds_read_b128 v[154:157], v216 offset:27648
	s_waitcnt lgkmcnt(6)
	v_mfma_f32_16x16x32_bf16 v[58:61], v[170:173], v[162:165], v[58:61]
	v_mfma_f32_16x16x32_bf16 v[62:65], v[178:181], v[162:165], v[62:65]
	ds_read_b128 v[158:161], v216 offset:29696
	s_waitcnt lgkmcnt(6)
	v_mfma_f32_16x16x32_bf16 v[66:69], v[170:173], v[134:137], v[66:69]
	v_mfma_f32_16x16x32_bf16 v[70:73], v[178:181], v[134:137], v[70:73]
	ds_read_b128 v[162:165], v216 offset:31744
	s_waitcnt vmcnt(4) lgkmcnt(0)
	s_barrier
	v_mfma_f32_16x16x32_bf16 v[74:77], v[170:173], v[138:141], v[74:77]
	s_add_u32 m0, s22, 0x0
	v_mov_b32_e32 v223, v217
	global_load_lds_dwordx4 v223, s[6:7]
	v_mfma_f32_16x16x32_bf16 v[78:81], v[178:181], v[138:141], v[78:81]
	s_add_u32 m0, s22, 0x400
	v_add_u32_e32 v224, 0x40, v217
	global_load_lds_dwordx4 v224, s[6:7]
	ds_read_b128 v[134:137], v216 offset:32768
	s_waitcnt lgkmcnt(6)
	v_mfma_f32_16x16x32_bf16 v[82:85], v[170:173], v[142:145], v[82:85]
	s_add_u32 m0, s22, 0x800
	v_add_u32_e32 v223, 0x8000, v217
	global_load_lds_dwordx4 v223, s[6:7]
	v_mfma_f32_16x16x32_bf16 v[86:89], v[178:181], v[142:145], v[86:89]
	s_add_u32 m0, s22, 0xc00
	v_add_u32_e32 v224, 0x8040, v217
	global_load_lds_dwordx4 v224, s[6:7]
	ds_read_b128 v[138:141], v216 offset:34816
	s_waitcnt lgkmcnt(6)
	v_mfma_f32_16x16x32_bf16 v[90:93], v[170:173], v[146:149], v[90:93]
	s_add_u32 m0, s22, 0x1000
	v_add_u32_e32 v223, 0x10000, v217
	global_load_lds_dwordx4 v223, s[6:7]
	v_mfma_f32_16x16x32_bf16 v[94:97], v[178:181], v[146:149], v[94:97]
	s_add_u32 m0, s22, 0x1400
	v_add_u32_e32 v224, 0x10040, v217
	global_load_lds_dwordx4 v224, s[6:7]
	ds_read_b128 v[142:145], v216 offset:36864
	s_waitcnt lgkmcnt(6)
	v_mfma_f32_16x16x32_bf16 v[98:101], v[170:173], v[150:153], v[98:101]
	s_add_u32 m0, s22, 0x1800
	v_add_u32_e32 v223, 0x18000, v217
	global_load_lds_dwordx4 v223, s[6:7]
	v_mfma_f32_16x16x32_bf16 v[102:105], v[178:181], v[150:153], v[102:105]
	s_add_u32 m0, s22, 0x1c00
	v_add_u32_e32 v224, 0x18040, v217
	global_load_lds_dwordx4 v224, s[6:7]
	ds_read_b128 v[146:149], v216 offset:38912
	s_waitcnt lgkmcnt(6)
	v_mfma_f32_16x16x32_bf16 v[106:109], v[170:173], v[154:157], v[106:109]
	v_mfma_f32_16x16x32_bf16 v[110:113], v[178:181], v[154:157], v[110:113]
	ds_read_b128 v[150:153], v216 offset:40960
	s_waitcnt lgkmcnt(6)
	v_mfma_f32_16x16x32_bf16 v[114:117], v[170:173], v[158:161], v[114:117]
	v_mfma_f32_16x16x32_bf16 v[118:121], v[178:181], v[158:161], v[118:121]
	ds_read_b128 v[154:157], v216 offset:43008
	s_waitcnt lgkmcnt(6)
	v_mfma_f32_16x16x32_bf16 v[122:125], v[170:173], v[162:165], v[122:125]
	v_mfma_f32_16x16x32_bf16 v[126:129], v[178:181], v[162:165], v[126:129]
	v_add_u32_e32 v217, 0x80, v217
	v_add_u32_e32 v220, 0x800, v220
	v_add_u32_e32 v221, 0x800, v221
	s_lshr_b32 s3, s14, 4
	s_lshl_b32 s17, s15, 1
	s_add_u32 s3, s3, s17
	s_mul_i32 s17, s3, 0x8000
	s_add_u32 s8, s20, s17
	s_addc_u32 s9, s21, 0
	v_mov_b32_e32 v220, v222
	v_add_u32_e32 v221, 0x8000, v222
	ds_read_b128 v[158:161], v216 offset:45056
	s_waitcnt vmcnt(8) lgkmcnt(6)
	v_mfma_f32_16x16x32_bf16 v[2:5], v[196:199], v[134:137], v[2:5]
	global_load_dwordx4 v[166:169], v220, s[8:9]
	v_mfma_f32_16x16x32_bf16 v[6:9], v[204:207], v[134:137], v[6:9]
	global_load_dwordx4 v[170:173], v220, s[8:9] offset:1024
	ds_read_b128 v[162:165], v216 offset:47104
	s_waitcnt lgkmcnt(6)
	v_mfma_f32_16x16x32_bf16 v[10:13], v[196:199], v[138:141], v[10:13]
	global_load_dwordx4 v[174:177], v221, s[8:9]
	v_mfma_f32_16x16x32_bf16 v[14:17], v[204:207], v[138:141], v[14:17]
	global_load_dwordx4 v[178:181], v221, s[8:9] offset:1024
	ds_read_b128 v[134:137], v216 offset:49152
	s_waitcnt lgkmcnt(6)
	v_mfma_f32_16x16x32_bf16 v[18:21], v[196:199], v[142:145], v[18:21]
	v_mfma_f32_16x16x32_bf16 v[22:25], v[204:207], v[142:145], v[22:25]
	ds_read_b128 v[138:141], v216 offset:51200
	s_waitcnt lgkmcnt(6)
	v_mfma_f32_16x16x32_bf16 v[26:29], v[196:199], v[146:149], v[26:29]
	v_mfma_f32_16x16x32_bf16 v[30:33], v[204:207], v[146:149], v[30:33]
	ds_read_b128 v[142:145], v216 offset:53248
	s_waitcnt lgkmcnt(6)
	v_mfma_f32_16x16x32_bf16 v[34:37], v[196:199], v[150:153], v[34:37]
	v_mfma_f32_16x16x32_bf16 v[38:41], v[204:207], v[150:153], v[38:41]
	ds_read_b128 v[146:149], v216 offset:55296
	s_waitcnt lgkmcnt(6)
	v_mfma_f32_16x16x32_bf16 v[42:45], v[196:199], v[154:157], v[42:45]
	v_mfma_f32_16x16x32_bf16 v[46:49], v[204:207], v[154:157], v[46:49]
	ds_read_b128 v[150:153], v216 offset:57344
	s_waitcnt lgkmcnt(6)
	v_mfma_f32_16x16x32_bf16 v[50:53], v[196:199], v[158:161], v[50:53]
	v_mfma_f32_16x16x32_bf16 v[54:57], v[204:207], v[158:161], v[54:57]
	ds_read_b128 v[154:157], v216 offset:59392
	s_waitcnt lgkmcnt(6)
	v_mfma_f32_16x16x32_bf16 v[58:61], v[196:199], v[162:165], v[58:61]
	v_mfma_f32_16x16x32_bf16 v[62:65], v[204:207], v[162:165], v[62:65]
	ds_read_b128 v[158:161], v216 offset:61440
	s_waitcnt lgkmcnt(6)
	v_mfma_f32_16x16x32_bf16 v[66:69], v[196:199], v[134:137], v[66:69]
	v_mfma_f32_16x16x32_bf16 v[70:73], v[204:207], v[134:137], v[70:73]
	ds_read_b128 v[162:165], v216 offset:63488
	s_waitcnt lgkmcnt(6)
	v_mfma_f32_16x16x32_bf16 v[74:77], v[196:199], v[138:141], v[74:77]
	v_mfma_f32_16x16x32_bf16 v[78:81], v[204:207], v[138:141], v[78:81]
	ds_read_b128 v[134:137], v216 offset:33792
	s_waitcnt lgkmcnt(6)
	v_mfma_f32_16x16x32_bf16 v[82:85], v[196:199], v[142:145], v[82:85]
	v_mfma_f32_16x16x32_bf16 v[86:89], v[204:207], v[142:145], v[86:89]
	ds_read_b128 v[138:141], v216 offset:35840
	s_waitcnt lgkmcnt(6)
	v_mfma_f32_16x16x32_bf16 v[90:93], v[196:199], v[146:149], v[90:93]
	v_mfma_f32_16x16x32_bf16 v[94:97], v[204:207], v[146:149], v[94:97]
	ds_read_b128 v[142:145], v216 offset:37888
	s_waitcnt lgkmcnt(6)
	v_mfma_f32_16x16x32_bf16 v[98:101], v[196:199], v[150:153], v[98:101]
	v_mfma_f32_16x16x32_bf16 v[102:105], v[204:207], v[150:153], v[102:105]
	ds_read_b128 v[146:149], v216 offset:39936
	s_waitcnt lgkmcnt(6)
	v_mfma_f32_16x16x32_bf16 v[106:109], v[196:199], v[154:157], v[106:109]
	v_mfma_f32_16x16x32_bf16 v[110:113], v[204:207], v[154:157], v[110:113]
	ds_read_b128 v[150:153], v216 offset:41984
	s_waitcnt lgkmcnt(6)
	v_mfma_f32_16x16x32_bf16 v[114:117], v[196:199], v[158:161], v[114:117]
	v_mfma_f32_16x16x32_bf16 v[118:121], v[204:207], v[158:161], v[118:121]
	ds_read_b128 v[154:157], v216 offset:44032
	s_waitcnt lgkmcnt(6)
	v_mfma_f32_16x16x32_bf16 v[122:125], v[196:199], v[162:165], v[122:125]
	v_mfma_f32_16x16x32_bf16 v[126:129], v[204:207], v[162:165], v[126:129]
	ds_read_b128 v[158:161], v216 offset:46080
	s_waitcnt lgkmcnt(6)
	v_mfma_f32_16x16x32_bf16 v[2:5], v[200:203], v[134:137], v[2:5]
	v_mfma_f32_16x16x32_bf16 v[6:9], v[212:215], v[134:137], v[6:9]
	ds_read_b128 v[162:165], v216 offset:48128
	s_waitcnt lgkmcnt(6)
	v_mfma_f32_16x16x32_bf16 v[10:13], v[200:203], v[138:141], v[10:13]
	v_mfma_f32_16x16x32_bf16 v[14:17], v[212:215], v[138:141], v[14:17]
	ds_read_b128 v[134:137], v216 offset:50176
	s_waitcnt lgkmcnt(6)
	v_mfma_f32_16x16x32_bf16 v[18:21], v[200:203], v[142:145], v[18:21]
	v_mfma_f32_16x16x32_bf16 v[22:25], v[212:215], v[142:145], v[22:25]
	ds_read_b128 v[138:141], v216 offset:52224
	s_waitcnt lgkmcnt(6)
	v_mfma_f32_16x16x32_bf16 v[26:29], v[200:203], v[146:149], v[26:29]
	v_mfma_f32_16x16x32_bf16 v[30:33], v[212:215], v[146:149], v[30:33]
	ds_read_b128 v[142:145], v216 offset:54272
	s_waitcnt lgkmcnt(6)
	v_mfma_f32_16x16x32_bf16 v[34:37], v[200:203], v[150:153], v[34:37]
	v_mfma_f32_16x16x32_bf16 v[38:41], v[212:215], v[150:153], v[38:41]
	ds_read_b128 v[146:149], v216 offset:56320
	s_waitcnt lgkmcnt(6)
	v_mfma_f32_16x16x32_bf16 v[42:45], v[200:203], v[154:157], v[42:45]
	v_mfma_f32_16x16x32_bf16 v[46:49], v[212:215], v[154:157], v[46:49]
	ds_read_b128 v[150:153], v216 offset:58368
	s_waitcnt lgkmcnt(6)
	v_mfma_f32_16x16x32_bf16 v[50:53], v[200:203], v[158:161], v[50:53]
	v_mfma_f32_16x16x32_bf16 v[54:57], v[212:215], v[158:161], v[54:57]
	ds_read_b128 v[154:157], v216 offset:60416
	s_waitcnt lgkmcnt(6)
	v_mfma_f32_16x16x32_bf16 v[58:61], v[200:203], v[162:165], v[58:61]
	v_mfma_f32_16x16x32_bf16 v[62:65], v[212:215], v[162:165], v[62:65]
	ds_read_b128 v[158:161], v216 offset:62464
	s_waitcnt lgkmcnt(6)
	v_mfma_f32_16x16x32_bf16 v[66:69], v[200:203], v[134:137], v[66:69]
	v_mfma_f32_16x16x32_bf16 v[70:73], v[212:215], v[134:137], v[70:73]
	ds_read_b128 v[162:165], v216 offset:64512
	s_waitcnt vmcnt(4) lgkmcnt(0)
	s_barrier
	v_mfma_f32_16x16x32_bf16 v[74:77], v[200:203], v[138:141], v[74:77]
	s_add_u32 m0, s22, 0x8000
	v_mov_b32_e32 v223, v217
	global_load_lds_dwordx4 v223, s[6:7]
	v_mfma_f32_16x16x32_bf16 v[78:81], v[212:215], v[138:141], v[78:81]
	s_add_u32 m0, s22, 0x8400
	v_add_u32_e32 v224, 0x40, v217
	global_load_lds_dwordx4 v224, s[6:7]
	ds_read_b128 v[134:137], v216
	s_waitcnt lgkmcnt(6)
	v_mfma_f32_16x16x32_bf16 v[82:85], v[200:203], v[142:145], v[82:85]
	s_add_u32 m0, s22, 0x8800
	v_add_u32_e32 v223, 0x8000, v217
	global_load_lds_dwordx4 v223, s[6:7]
	v_mfma_f32_16x16x32_bf16 v[86:89], v[212:215], v[142:145], v[86:89]
	s_add_u32 m0, s22, 0x8c00
	v_add_u32_e32 v224, 0x8040, v217
	global_load_lds_dwordx4 v224, s[6:7]
	ds_read_b128 v[138:141], v216 offset:2048
	s_waitcnt lgkmcnt(6)
	v_mfma_f32_16x16x32_bf16 v[90:93], v[200:203], v[146:149], v[90:93]
	s_add_u32 m0, s22, 0x9000
	v_add_u32_e32 v223, 0x10000, v217
	global_load_lds_dwordx4 v223, s[6:7]
	v_mfma_f32_16x16x32_bf16 v[94:97], v[212:215], v[146:149], v[94:97]
	s_add_u32 m0, s22, 0x9400
	v_add_u32_e32 v224, 0x10040, v217
	global_load_lds_dwordx4 v224, s[6:7]
	ds_read_b128 v[142:145], v216 offset:4096
	s_waitcnt lgkmcnt(6)
	v_mfma_f32_16x16x32_bf16 v[98:101], v[200:203], v[150:153], v[98:101]
	s_add_u32 m0, s22, 0x9800
	v_add_u32_e32 v223, 0x18000, v217
	global_load_lds_dwordx4 v223, s[6:7]
	v_mfma_f32_16x16x32_bf16 v[102:105], v[212:215], v[150:153], v[102:105]
	s_add_u32 m0, s22, 0x9c00
	v_add_u32_e32 v224, 0x18040, v217
	global_load_lds_dwordx4 v224, s[6:7]
	ds_read_b128 v[146:149], v216 offset:6144
	s_waitcnt lgkmcnt(6)
	v_mfma_f32_16x16x32_bf16 v[106:109], v[200:203], v[154:157], v[106:109]
	v_mfma_f32_16x16x32_bf16 v[110:113], v[212:215], v[154:157], v[110:113]
	ds_read_b128 v[150:153], v216 offset:8192
	s_waitcnt lgkmcnt(6)
	v_mfma_f32_16x16x32_bf16 v[114:117], v[200:203], v[158:161], v[114:117]
	v_mfma_f32_16x16x32_bf16 v[118:121], v[212:215], v[158:161], v[118:121]
	ds_read_b128 v[154:157], v216 offset:10240
	s_waitcnt lgkmcnt(6)
	v_mfma_f32_16x16x32_bf16 v[122:125], v[200:203], v[162:165], v[122:125]
	v_mfma_f32_16x16x32_bf16 v[126:129], v[212:215], v[162:165], v[126:129]
	v_add_u32_e32 v217, 0x80, v217
	v_add_u32_e32 v220, 0x800, v220
	v_add_u32_e32 v221, 0x800, v221
	s_mov_b32 s16, 1
	s_branch .Lg256b_w1_epi

.LBB0_60:
	s_andn2_b64 vcc, exec, s[4:5]
	s_cbranch_vccnz .LBB0_66
	v_readlane_b32 s4, v239, 0
	v_readlane_b32 s5, v239, 1
	s_andn2_b64 vcc, exec, s[4:5]
	s_cbranch_vccnz .LBB0_66
	s_load_dwordx2 s[4:5], s[0:1], 0x130
	s_load_dwordx2 s[24:25], s[0:1], 0x128
	v_and_b32_e32 v0, 63, v133
	v_lshrrev_b32_e32 v131, 6, v133
	v_lshrrev_b32_e32 v195, 2, v0
	v_readfirstlane_b32 s15, v131
	v_mul_u32_u24_e32 v218, 0x800, v195
	v_and_b32_e32 v195, 3, v0
	v_lshlrev_b32_e32 v195, 4, v195
	v_lshrrev_b32_e32 v131, 5, v0
	v_lshlrev_b32_e32 v131, 5, v131
	v_xor_b32_e32 v195, v195, v131
	v_add_u32_e32 v218, v218, v195
	v_and_b32_e32 v195, 15, v0
	v_lshrrev_b32_e32 v131, 4, v0
	v_lshlrev_b32_e32 v216, 6, v195
	v_lshl_or_b32 v216, v131, 4, v216
	v_and_b32_e32 v219, 8, v0
	v_lshlrev_b32_e32 v219, 2, v219
	v_xor_b32_e32 v216, v216, v219
	v_mul_u32_u24_e32 v219, 0x1000, v195
	v_lshl_or_b32 v219, v131, 4, v219
	v_lshlrev_b32_e32 v222, 4, v0
	s_waitcnt lgkmcnt(0)
	s_add_u32 s18, s4, 0x4b27800
	s_addc_u32 s19, s5, 0
	s_add_u32 s20, s4, 0x1927800
	s_addc_u32 s21, s5, 0
	s_mul_i32 s3, s62, 73728
	s_add_u32 s3, s3, 8192
	s_add_u32 s4, s4, s3
	s_addc_u32 s5, s5, 0
	v_lshlrev_b32_e32 v225, 4, v131
	s_lshl_b32 s22, s15, 13
	s_mov_b32 s12, s79
.Lg256b_wo_first_retry:
	s_cmp_ge_u32 s12, 64
	s_cbranch_scc1 .Lg256b_wo_done
	s_lshr_b32 s3, s12, 6
	s_lshl_b32 s3, s3, 3
	s_add_u32 s3, s3, s65
	s_mov_b32 s17, s3
	s_mov_b32 s3, 0
	s_lshl_b32 s17, s17, 3
	s_bfe_u32 s23, s12, 0x30003
	s_add_u32 s13, s17, s23
	s_lshl_b32 s3, s3, 3
	s_and_b32 s23, s12, 7
	s_add_u32 s14, s3, s23
	s_lshl_b32 s13, s13, 8
	s_lshl_b32 s14, s14, 7
	s_lshl_b32 s3, s15, 6
	s_add_u32 s17, s3, s13
	s_mul_i32 s17, s17, 0x800
	s_add_u32 s6, s18, s17
	s_addc_u32 s7, s19, 0
	s_lshr_b32 s3, s14, 4
	s_lshl_b32 s17, s15, 1
	s_add_u32 s3, s3, s17
	s_mul_i32 s17, s3, 0x8000
	s_add_u32 s8, s20, s17
	s_addc_u32 s9, s21, 0
	s_barrier
	v_mov_b32_e32 v217, v218
	v_mov_b32_e32 v220, v222
	v_add_u32_e32 v221, 0x8000, v222
	s_add_u32 m0, s22, 0x0
	v_mov_b32_e32 v223, v217
	global_load_lds_dwordx4 v223, s[6:7]
	s_add_u32 m0, s22, 0x400
	v_add_u32_e32 v224, 0x40, v217
	global_load_lds_dwordx4 v224, s[6:7]
	s_add_u32 m0, s22, 0x800
	v_add_u32_e32 v223, 0x8000, v217
	global_load_lds_dwordx4 v223, s[6:7]
	s_add_u32 m0, s22, 0xc00
	v_add_u32_e32 v224, 0x8040, v217
	global_load_lds_dwordx4 v224, s[6:7]
	s_add_u32 m0, s22, 0x1000
	v_add_u32_e32 v223, 0x10000, v217
	global_load_lds_dwordx4 v223, s[6:7]
	s_add_u32 m0, s22, 0x1400
	v_add_u32_e32 v224, 0x10040, v217
	global_load_lds_dwordx4 v224, s[6:7]
	s_add_u32 m0, s22, 0x1800
	v_add_u32_e32 v223, 0x18000, v217
	global_load_lds_dwordx4 v223, s[6:7]
	s_add_u32 m0, s22, 0x1c00
	v_add_u32_e32 v224, 0x18040, v217
	global_load_lds_dwordx4 v224, s[6:7]
	v_add_u32_e32 v217, 0x80, v217
	s_add_u32 m0, s22, 0x8000
	v_mov_b32_e32 v223, v217
	global_load_lds_dwordx4 v223, s[6:7]
	s_add_u32 m0, s22, 0x8400
	v_add_u32_e32 v224, 0x40, v217
	global_load_lds_dwordx4 v224, s[6:7]
	s_add_u32 m0, s22, 0x8800
	v_add_u32_e32 v223, 0x8000, v217
	global_load_lds_dwordx4 v223, s[6:7]
	s_add_u32 m0, s22, 0x8c00
	v_add_u32_e32 v224, 0x8040, v217
	global_load_lds_dwordx4 v224, s[6:7]
	s_add_u32 m0, s22, 0x9000
	v_add_u32_e32 v223, 0x10000, v217
	global_load_lds_dwordx4 v223, s[6:7]
	s_add_u32 m0, s22, 0x9400
	v_add_u32_e32 v224, 0x10040, v217
	global_load_lds_dwordx4 v224, s[6:7]
	s_add_u32 m0, s22, 0x9800
	v_add_u32_e32 v223, 0x18000, v217
	global_load_lds_dwordx4 v223, s[6:7]
	s_add_u32 m0, s22, 0x9c00
	v_add_u32_e32 v224, 0x18040, v217
	global_load_lds_dwordx4 v224, s[6:7]
	v_add_u32_e32 v217, 0x80, v217
	global_load_dwordx4 v[166:169], v220, s[8:9]
	global_load_dwordx4 v[170:173], v220, s[8:9] offset:1024
	global_load_dwordx4 v[174:177], v221, s[8:9]
	global_load_dwordx4 v[178:181], v221, s[8:9] offset:1024
	v_add_u32_e32 v220, 0x800, v220
	v_add_u32_e32 v221, 0x800, v221
	s_waitcnt vmcnt(0)
	s_barrier
	ds_read_b128 v[134:137], v216
	ds_read_b128 v[138:141], v216 offset:2048
	ds_read_b128 v[142:145], v216 offset:4096
	ds_read_b128 v[146:149], v216 offset:6144
	ds_read_b128 v[150:153], v216 offset:8192
	ds_read_b128 v[154:157], v216 offset:10240
.Lg256b_wo_tile:
	s_mul_i32 s17, s13, 0x1000
	s_lshl_b32 s3, s15, 5
	s_add_u32 s3, s3, s14
	s_mul_i32 s3, s3, 4
	s_add_u32 s17, s17, s3
	s_add_u32 s10, s24, s17
	s_addc_u32 s11, s25, 0
	s_lshl_b32 s3, s15, 5
	s_add_u32 s3, s3, s14
	s_lshl_b32 s3, s3, 2
	s_lshr_b32 s17, s13, 12
	s_max_u32 s17, s17, 1
	s_sub_u32 s17, s17, 1
	s_mul_i32 s17, s17, 24576
	s_add_u32 s3, s3, s17
	v_add_u32_e32 v234, s3, v225
	s_cmp_lg_u32 s62, 0
	s_cbranch_scc1 .Lg256b_wo_x_l1
	s_lshr_b32 s3, s13, 13
	s_lshl_b32 s3, s3, 3
	s_load_dwordx2 s[26:27], s[0:1], s3
	s_lshl_b32 s17, s13, 12
	s_and_b32 s17, s17, 0x1ffffff
	s_lshl_b32 s3, s15, 5
	s_add_u32 s3, s3, s14
	s_lshl_b32 s3, s3, 2
	s_add_u32 s17, s17, s3
	s_waitcnt lgkmcnt(6)
	s_waitcnt lgkmcnt(0)
	s_add_u32 s26, s26, s17
	s_addc_u32 s27, s27, 0
	s_branch .Lg256b_wo_x_go

.Lg256b_wo_x_go:
	ds_read_b128 v[158:161], v216 offset:12288
	s_waitcnt vmcnt(16) lgkmcnt(6)
	v_mfma_f32_16x16x32_bf16 v[2:5], v[166:169], v[134:137], 0
	global_load_dwordx4 v[196:199], v220, s[8:9]
	v_mfma_f32_16x16x32_bf16 v[6:9], v[174:177], v[134:137], 0
	global_load_dwordx4 v[200:203], v220, s[8:9] offset:1024
	ds_read_b128 v[162:165], v216 offset:14336
	s_waitcnt lgkmcnt(6)
	v_mfma_f32_16x16x32_bf16 v[10:13], v[166:169], v[138:141], 0
	global_load_dwordx4 v[204:207], v221, s[8:9]
	v_mfma_f32_16x16x32_bf16 v[14:17], v[174:177], v[138:141], 0
	global_load_dwordx4 v[212:215], v221, s[8:9] offset:1024
	ds_read_b128 v[134:137], v216 offset:16384
	s_waitcnt lgkmcnt(6)
	v_mfma_f32_16x16x32_bf16 v[18:21], v[166:169], v[142:145], 0
	v_mfma_f32_16x16x32_bf16 v[22:25], v[174:177], v[142:145], 0
	ds_read_b128 v[138:141], v216 offset:18432
	s_waitcnt lgkmcnt(6)
	v_mfma_f32_16x16x32_bf16 v[26:29], v[166:169], v[146:149], 0
	v_mfma_f32_16x16x32_bf16 v[30:33], v[174:177], v[146:149], 0
	ds_read_b128 v[142:145], v216 offset:20480
	s_waitcnt lgkmcnt(6)
	v_mfma_f32_16x16x32_bf16 v[34:37], v[166:169], v[150:153], 0
	v_mfma_f32_16x16x32_bf16 v[38:41], v[174:177], v[150:153], 0
	ds_read_b128 v[146:149], v216 offset:22528
	s_waitcnt lgkmcnt(6)
	v_mfma_f32_16x16x32_bf16 v[42:45], v[166:169], v[154:157], 0
	v_mfma_f32_16x16x32_bf16 v[46:49], v[174:177], v[154:157], 0
	ds_read_b128 v[150:153], v216 offset:24576
	s_waitcnt lgkmcnt(6)
	v_mfma_f32_16x16x32_bf16 v[50:53], v[166:169], v[158:161], 0
	v_mfma_f32_16x16x32_bf16 v[54:57], v[174:177], v[158:161], 0
	ds_read_b128 v[154:157], v216 offset:26624
	s_waitcnt lgkmcnt(6)
	v_mfma_f32_16x16x32_bf16 v[58:61], v[166:169], v[162:165], 0
	v_mfma_f32_16x16x32_bf16 v[62:65], v[174:177], v[162:165], 0
	ds_read_b128 v[158:161], v216 offset:28672
	s_waitcnt lgkmcnt(6)
	v_mfma_f32_16x16x32_bf16 v[66:69], v[166:169], v[134:137], 0
	v_mfma_f32_16x16x32_bf16 v[70:73], v[174:177], v[134:137], 0
	ds_read_b128 v[162:165], v216 offset:30720
	s_waitcnt lgkmcnt(6)
	v_mfma_f32_16x16x32_bf16 v[74:77], v[166:169], v[138:141], 0
	v_mfma_f32_16x16x32_bf16 v[78:81], v[174:177], v[138:141], 0
	ds_read_b128 v[134:137], v216 offset:1024
	s_waitcnt lgkmcnt(6)
	v_mfma_f32_16x16x32_bf16 v[82:85], v[166:169], v[142:145], 0
	v_mfma_f32_16x16x32_bf16 v[86:89], v[174:177], v[142:145], 0
	ds_read_b128 v[138:141], v216 offset:3072
	s_waitcnt lgkmcnt(6)
	v_mfma_f32_16x16x32_bf16 v[90:93], v[166:169], v[146:149], 0
	v_mfma_f32_16x16x32_bf16 v[94:97], v[174:177], v[146:149], 0
	ds_read_b128 v[142:145], v216 offset:5120
	s_waitcnt lgkmcnt(6)
	v_mfma_f32_16x16x32_bf16 v[98:101], v[166:169], v[150:153], 0
	v_mfma_f32_16x16x32_bf16 v[102:105], v[174:177], v[150:153], 0
	ds_read_b128 v[146:149], v216 offset:7168
	s_waitcnt lgkmcnt(6)
	v_mfma_f32_16x16x32_bf16 v[106:109], v[166:169], v[154:157], 0
	v_mfma_f32_16x16x32_bf16 v[110:113], v[174:177], v[154:157], 0
	ds_read_b128 v[150:153], v216 offset:9216
	s_waitcnt lgkmcnt(6)
	v_mfma_f32_16x16x32_bf16 v[114:117], v[166:169], v[158:161], 0
	v_mfma_f32_16x16x32_bf16 v[118:121], v[174:177], v[158:161], 0
	ds_read_b128 v[154:157], v216 offset:11264
	s_waitcnt lgkmcnt(6)
	v_mfma_f32_16x16x32_bf16 v[122:125], v[166:169], v[162:165], 0
	v_mfma_f32_16x16x32_bf16 v[126:129], v[174:177], v[162:165], 0
	ds_read_b128 v[158:161], v216 offset:13312
	s_waitcnt lgkmcnt(6)
	v_mfma_f32_16x16x32_bf16 v[2:5], v[170:173], v[134:137], v[2:5]
	v_mfma_f32_16x16x32_bf16 v[6:9], v[178:181], v[134:137], v[6:9]
	ds_read_b128 v[162:165], v216 offset:15360
	s_waitcnt lgkmcnt(6)
	v_mfma_f32_16x16x32_bf16 v[10:13], v[170:173], v[138:141], v[10:13]
	v_mfma_f32_16x16x32_bf16 v[14:17], v[178:181], v[138:141], v[14:17]
	ds_read_b128 v[134:137], v216 offset:17408
	s_waitcnt lgkmcnt(6)
	v_mfma_f32_16x16x32_bf16 v[18:21], v[170:173], v[142:145], v[18:21]
	v_mfma_f32_16x16x32_bf16 v[22:25], v[178:181], v[142:145], v[22:25]
	ds_read_b128 v[138:141], v216 offset:19456
	s_waitcnt lgkmcnt(6)
	v_mfma_f32_16x16x32_bf16 v[26:29], v[170:173], v[146:149], v[26:29]
	v_mfma_f32_16x16x32_bf16 v[30:33], v[178:181], v[146:149], v[30:33]
	ds_read_b128 v[142:145], v216 offset:21504
	s_waitcnt lgkmcnt(6)
	v_mfma_f32_16x16x32_bf16 v[34:37], v[170:173], v[150:153], v[34:37]
	v_mfma_f32_16x16x32_bf16 v[38:41], v[178:181], v[150:153], v[38:41]
	ds_read_b128 v[146:149], v216 offset:23552
	s_waitcnt lgkmcnt(6)
	v_mfma_f32_16x16x32_bf16 v[42:45], v[170:173], v[154:157], v[42:45]
	v_mfma_f32_16x16x32_bf16 v[46:49], v[178:181], v[154:157], v[46:49]
	ds_read_b128 v[150:153], v216 offset:25600
	s_waitcnt lgkmcnt(6)
	v_mfma_f32_16x16x32_bf16 v[50:53], v[170:173], v[158:161], v[50:53]
	v_mfma_f32_16x16x32_bf16 v[54:57], v[178:181], v[158:161], v[54:57]
	ds_read_b128 v[154:157], v216 offset:27648
	s_waitcnt lgkmcnt(6)
	v_mfma_f32_16x16x32_bf16 v[58:61], v[170:173], v[162:165], v[58:61]
	v_mfma_f32_16x16x32_bf16 v[62:65], v[178:181], v[162:165], v[62:65]
	ds_read_b128 v[158:161], v216 offset:29696
	s_waitcnt lgkmcnt(6)
	v_mfma_f32_16x16x32_bf16 v[66:69], v[170:173], v[134:137], v[66:69]
	v_mfma_f32_16x16x32_bf16 v[70:73], v[178:181], v[134:137], v[70:73]
	ds_read_b128 v[162:165], v216 offset:31744
	s_waitcnt vmcnt(12) lgkmcnt(0)
	s_barrier
	v_mfma_f32_16x16x32_bf16 v[74:77], v[170:173], v[138:141], v[74:77]
	s_add_u32 m0, s22, 0x0
	v_mov_b32_e32 v223, v217
	global_load_lds_dwordx4 v223, s[6:7]
	v_mfma_f32_16x16x32_bf16 v[78:81], v[178:181], v[138:141], v[78:81]
	s_add_u32 m0, s22, 0x400
	v_add_u32_e32 v224, 0x40, v217
	global_load_lds_dwordx4 v224, s[6:7]
	ds_read_b128 v[134:137], v216 offset:32768
	s_waitcnt lgkmcnt(6)
	v_mfma_f32_16x16x32_bf16 v[82:85], v[170:173], v[142:145], v[82:85]
	s_add_u32 m0, s22, 0x800
	v_add_u32_e32 v223, 0x8000, v217
	global_load_lds_dwordx4 v223, s[6:7]
	v_mfma_f32_16x16x32_bf16 v[86:89], v[178:181], v[142:145], v[86:89]
	s_add_u32 m0, s22, 0xc00
	v_add_u32_e32 v224, 0x8040, v217
	global_load_lds_dwordx4 v224, s[6:7]
	ds_read_b128 v[138:141], v216 offset:34816
	s_waitcnt lgkmcnt(6)
	v_mfma_f32_16x16x32_bf16 v[90:93], v[170:173], v[146:149], v[90:93]
	s_add_u32 m0, s22, 0x1000
	v_add_u32_e32 v223, 0x10000, v217
	global_load_lds_dwordx4 v223, s[6:7]
	v_mfma_f32_16x16x32_bf16 v[94:97], v[178:181], v[146:149], v[94:97]
	s_add_u32 m0, s22, 0x1400
	v_add_u32_e32 v224, 0x10040, v217
	global_load_lds_dwordx4 v224, s[6:7]
	ds_read_b128 v[142:145], v216 offset:36864
	s_waitcnt lgkmcnt(6)
	v_mfma_f32_16x16x32_bf16 v[98:101], v[170:173], v[150:153], v[98:101]
	s_add_u32 m0, s22, 0x1800
	v_add_u32_e32 v223, 0x18000, v217
	global_load_lds_dwordx4 v223, s[6:7]
	v_mfma_f32_16x16x32_bf16 v[102:105], v[178:181], v[150:153], v[102:105]
	s_add_u32 m0, s22, 0x1c00
	v_add_u32_e32 v224, 0x18040, v217
	global_load_lds_dwordx4 v224, s[6:7]
	ds_read_b128 v[146:149], v216 offset:38912
	s_waitcnt lgkmcnt(6)
	v_mfma_f32_16x16x32_bf16 v[106:109], v[170:173], v[154:157], v[106:109]
	v_mfma_f32_16x16x32_bf16 v[110:113], v[178:181], v[154:157], v[110:113]
	ds_read_b128 v[150:153], v216 offset:40960
	s_waitcnt lgkmcnt(6)
	v_mfma_f32_16x16x32_bf16 v[114:117], v[170:173], v[158:161], v[114:117]
	v_mfma_f32_16x16x32_bf16 v[118:121], v[178:181], v[158:161], v[118:121]
	ds_read_b128 v[154:157], v216 offset:43008
	s_waitcnt lgkmcnt(6)
	v_mfma_f32_16x16x32_bf16 v[122:125], v[170:173], v[162:165], v[122:125]
	v_mfma_f32_16x16x32_bf16 v[126:129], v[178:181], v[162:165], v[126:129]
	v_add_u32_e32 v217, 0x80, v217
	v_add_u32_e32 v220, 0x800, v220
	v_add_u32_e32 v221, 0x800, v221
	ds_read_b128 v[158:161], v216 offset:45056
	s_waitcnt vmcnt(8) lgkmcnt(6)
	v_mfma_f32_16x16x32_bf16 v[2:5], v[196:199], v[134:137], v[2:5]
	global_load_dwordx4 v[166:169], v220, s[8:9]
	v_mfma_f32_16x16x32_bf16 v[6:9], v[204:207], v[134:137], v[6:9]
	global_load_dwordx4 v[170:173], v220, s[8:9] offset:1024
	ds_read_b128 v[162:165], v216 offset:47104
	s_waitcnt lgkmcnt(6)
	v_mfma_f32_16x16x32_bf16 v[10:13], v[196:199], v[138:141], v[10:13]
	global_load_dwordx4 v[174:177], v221, s[8:9]
	v_mfma_f32_16x16x32_bf16 v[14:17], v[204:207], v[138:141], v[14:17]
	global_load_dwordx4 v[178:181], v221, s[8:9] offset:1024
	ds_read_b128 v[134:137], v216 offset:49152
	s_waitcnt lgkmcnt(6)
	v_mfma_f32_16x16x32_bf16 v[18:21], v[196:199], v[142:145], v[18:21]
	v_mfma_f32_16x16x32_bf16 v[22:25], v[204:207], v[142:145], v[22:25]
	ds_read_b128 v[138:141], v216 offset:51200
	s_waitcnt lgkmcnt(6)
	v_mfma_f32_16x16x32_bf16 v[26:29], v[196:199], v[146:149], v[26:29]
	v_mfma_f32_16x16x32_bf16 v[30:33], v[204:207], v[146:149], v[30:33]
	ds_read_b128 v[142:145], v216 offset:53248
	s_waitcnt lgkmcnt(6)
	v_mfma_f32_16x16x32_bf16 v[34:37], v[196:199], v[150:153], v[34:37]
	v_mfma_f32_16x16x32_bf16 v[38:41], v[204:207], v[150:153], v[38:41]
	ds_read_b128 v[146:149], v216 offset:55296
	s_waitcnt lgkmcnt(6)
	v_mfma_f32_16x16x32_bf16 v[42:45], v[196:199], v[154:157], v[42:45]
	v_mfma_f32_16x16x32_bf16 v[46:49], v[204:207], v[154:157], v[46:49]
	ds_read_b128 v[150:153], v216 offset:57344
	s_waitcnt lgkmcnt(6)
	v_mfma_f32_16x16x32_bf16 v[50:53], v[196:199], v[158:161], v[50:53]
	v_mfma_f32_16x16x32_bf16 v[54:57], v[204:207], v[158:161], v[54:57]
	ds_read_b128 v[154:157], v216 offset:59392
	s_waitcnt lgkmcnt(6)
	v_mfma_f32_16x16x32_bf16 v[58:61], v[196:199], v[162:165], v[58:61]
	v_mfma_f32_16x16x32_bf16 v[62:65], v[204:207], v[162:165], v[62:65]
	ds_read_b128 v[158:161], v216 offset:61440
	s_waitcnt lgkmcnt(6)
	v_mfma_f32_16x16x32_bf16 v[66:69], v[196:199], v[134:137], v[66:69]
	v_mfma_f32_16x16x32_bf16 v[70:73], v[204:207], v[134:137], v[70:73]
	ds_read_b128 v[162:165], v216 offset:63488
	s_waitcnt lgkmcnt(6)
	v_mfma_f32_16x16x32_bf16 v[74:77], v[196:199], v[138:141], v[74:77]
	v_mfma_f32_16x16x32_bf16 v[78:81], v[204:207], v[138:141], v[78:81]
	ds_read_b128 v[134:137], v216 offset:33792
	s_waitcnt lgkmcnt(6)
	v_mfma_f32_16x16x32_bf16 v[82:85], v[196:199], v[142:145], v[82:85]
	v_mfma_f32_16x16x32_bf16 v[86:89], v[204:207], v[142:145], v[86:89]
	ds_read_b128 v[138:141], v216 offset:35840
	s_waitcnt lgkmcnt(6)
	v_mfma_f32_16x16x32_bf16 v[90:93], v[196:199], v[146:149], v[90:93]
	v_mfma_f32_16x16x32_bf16 v[94:97], v[204:207], v[146:149], v[94:97]
	ds_read_b128 v[142:145], v216 offset:37888
	s_waitcnt lgkmcnt(6)
	v_mfma_f32_16x16x32_bf16 v[98:101], v[196:199], v[150:153], v[98:101]
	v_mfma_f32_16x16x32_bf16 v[102:105], v[204:207], v[150:153], v[102:105]
	ds_read_b128 v[146:149], v216 offset:39936
	s_waitcnt lgkmcnt(6)
	v_mfma_f32_16x16x32_bf16 v[106:109], v[196:199], v[154:157], v[106:109]
	v_mfma_f32_16x16x32_bf16 v[110:113], v[204:207], v[154:157], v[110:113]
	ds_read_b128 v[150:153], v216 offset:41984
	s_waitcnt lgkmcnt(6)
	v_mfma_f32_16x16x32_bf16 v[114:117], v[196:199], v[158:161], v[114:117]
	v_mfma_f32_16x16x32_bf16 v[118:121], v[204:207], v[158:161], v[118:121]
	ds_read_b128 v[154:157], v216 offset:44032
	s_waitcnt lgkmcnt(6)
	v_mfma_f32_16x16x32_bf16 v[122:125], v[196:199], v[162:165], v[122:125]
	v_mfma_f32_16x16x32_bf16 v[126:129], v[204:207], v[162:165], v[126:129]
	ds_read_b128 v[158:161], v216 offset:46080
	s_waitcnt lgkmcnt(6)
	v_mfma_f32_16x16x32_bf16 v[2:5], v[200:203], v[134:137], v[2:5]
	v_mfma_f32_16x16x32_bf16 v[6:9], v[212:215], v[134:137], v[6:9]
	ds_read_b128 v[162:165], v216 offset:48128
	s_waitcnt lgkmcnt(6)
	v_mfma_f32_16x16x32_bf16 v[10:13], v[200:203], v[138:141], v[10:13]
	v_mfma_f32_16x16x32_bf16 v[14:17], v[212:215], v[138:141], v[14:17]
	ds_read_b128 v[134:137], v216 offset:50176
	s_waitcnt lgkmcnt(6)
	v_mfma_f32_16x16x32_bf16 v[18:21], v[200:203], v[142:145], v[18:21]
	v_mfma_f32_16x16x32_bf16 v[22:25], v[212:215], v[142:145], v[22:25]
	ds_read_b128 v[138:141], v216 offset:52224
	s_waitcnt lgkmcnt(6)
	v_mfma_f32_16x16x32_bf16 v[26:29], v[200:203], v[146:149], v[26:29]
	v_mfma_f32_16x16x32_bf16 v[30:33], v[212:215], v[146:149], v[30:33]
	ds_read_b128 v[142:145], v216 offset:54272
	s_waitcnt lgkmcnt(6)
	v_mfma_f32_16x16x32_bf16 v[34:37], v[200:203], v[150:153], v[34:37]
	v_mfma_f32_16x16x32_bf16 v[38:41], v[212:215], v[150:153], v[38:41]
	ds_read_b128 v[146:149], v216 offset:56320
	s_waitcnt lgkmcnt(6)
	v_mfma_f32_16x16x32_bf16 v[42:45], v[200:203], v[154:157], v[42:45]
	v_mfma_f32_16x16x32_bf16 v[46:49], v[212:215], v[154:157], v[46:49]
	ds_read_b128 v[150:153], v216 offset:58368
	s_waitcnt lgkmcnt(6)
	v_mfma_f32_16x16x32_bf16 v[50:53], v[200:203], v[158:161], v[50:53]
	v_mfma_f32_16x16x32_bf16 v[54:57], v[212:215], v[158:161], v[54:57]
	ds_read_b128 v[154:157], v216 offset:60416
	s_waitcnt lgkmcnt(6)
	v_mfma_f32_16x16x32_bf16 v[58:61], v[200:203], v[162:165], v[58:61]
	v_mfma_f32_16x16x32_bf16 v[62:65], v[212:215], v[162:165], v[62:65]
	ds_read_b128 v[158:161], v216 offset:62464
	s_waitcnt lgkmcnt(6)
	v_mfma_f32_16x16x32_bf16 v[66:69], v[200:203], v[134:137], v[66:69]
	v_mfma_f32_16x16x32_bf16 v[70:73], v[212:215], v[134:137], v[70:73]
	ds_read_b128 v[162:165], v216 offset:64512
	s_waitcnt vmcnt(4) lgkmcnt(0)
	s_barrier
	v_mfma_f32_16x16x32_bf16 v[74:77], v[200:203], v[138:141], v[74:77]
	s_add_u32 m0, s22, 0x8000
	v_mov_b32_e32 v223, v217
	global_load_lds_dwordx4 v223, s[6:7]
	v_mfma_f32_16x16x32_bf16 v[78:81], v[212:215], v[138:141], v[78:81]
	s_add_u32 m0, s22, 0x8400
	v_add_u32_e32 v224, 0x40, v217
	global_load_lds_dwordx4 v224, s[6:7]
	ds_read_b128 v[134:137], v216
	s_waitcnt lgkmcnt(6)
	v_mfma_f32_16x16x32_bf16 v[82:85], v[200:203], v[142:145], v[82:85]
	s_add_u32 m0, s22, 0x8800
	v_add_u32_e32 v223, 0x8000, v217
	global_load_lds_dwordx4 v223, s[6:7]
	v_mfma_f32_16x16x32_bf16 v[86:89], v[212:215], v[142:145], v[86:89]
	s_add_u32 m0, s22, 0x8c00
	v_add_u32_e32 v224, 0x8040, v217
	global_load_lds_dwordx4 v224, s[6:7]
	ds_read_b128 v[138:141], v216 offset:2048
	s_waitcnt lgkmcnt(6)
	v_mfma_f32_16x16x32_bf16 v[90:93], v[200:203], v[146:149], v[90:93]
	s_add_u32 m0, s22, 0x9000
	v_add_u32_e32 v223, 0x10000, v217
	global_load_lds_dwordx4 v223, s[6:7]
	v_mfma_f32_16x16x32_bf16 v[94:97], v[212:215], v[146:149], v[94:97]
	s_add_u32 m0, s22, 0x9400
	v_add_u32_e32 v224, 0x10040, v217
	global_load_lds_dwordx4 v224, s[6:7]
	ds_read_b128 v[142:145], v216 offset:4096
	s_waitcnt lgkmcnt(6)
	v_mfma_f32_16x16x32_bf16 v[98:101], v[200:203], v[150:153], v[98:101]
	s_add_u32 m0, s22, 0x9800
	v_add_u32_e32 v223, 0x18000, v217
	global_load_lds_dwordx4 v223, s[6:7]
	v_mfma_f32_16x16x32_bf16 v[102:105], v[212:215], v[150:153], v[102:105]
	s_add_u32 m0, s22, 0x9c00
	v_add_u32_e32 v224, 0x18040, v217
	global_load_lds_dwordx4 v224, s[6:7]
	ds_read_b128 v[146:149], v216 offset:6144
	s_waitcnt lgkmcnt(6)
	v_mfma_f32_16x16x32_bf16 v[106:109], v[200:203], v[154:157], v[106:109]
	v_mfma_f32_16x16x32_bf16 v[110:113], v[212:215], v[154:157], v[110:113]
	ds_read_b128 v[150:153], v216 offset:8192
	s_waitcnt lgkmcnt(6)
	v_mfma_f32_16x16x32_bf16 v[114:117], v[200:203], v[158:161], v[114:117]
	v_mfma_f32_16x16x32_bf16 v[118:121], v[212:215], v[158:161], v[118:121]
	ds_read_b128 v[154:157], v216 offset:10240
	s_waitcnt lgkmcnt(6)
	v_mfma_f32_16x16x32_bf16 v[122:125], v[200:203], v[162:165], v[122:125]
	v_mfma_f32_16x16x32_bf16 v[126:129], v[212:215], v[162:165], v[126:129]
	v_add_u32_e32 v217, 0x80, v217
	v_add_u32_e32 v220, 0x800, v220
	v_add_u32_e32 v221, 0x800, v221
	s_mov_b32 s16, 6

.Lg256b_wo_next_retry:
	s_cmp_ge_u32 s12, 64
	s_cbranch_scc1 .Lg256b_wo_nonext
	s_lshr_b32 s3, s12, 6
	s_lshl_b32 s3, s3, 3
	s_add_u32 s3, s3, s65
	s_mov_b32 s17, s3
	s_mov_b32 s3, 0
	s_lshl_b32 s17, s17, 3
	s_bfe_u32 s23, s12, 0x30003
	s_add_u32 s13, s17, s23
	s_lshl_b32 s3, s3, 3
	s_and_b32 s23, s12, 7
	s_add_u32 s14, s3, s23
	s_lshl_b32 s13, s13, 8
	s_lshl_b32 s14, s14, 7
	s_lshl_b32 s3, s15, 6
	s_add_u32 s17, s3, s13
	s_mul_i32 s17, s17, 0x800
	s_add_u32 s6, s18, s17
	s_addc_u32 s7, s19, 0
	v_mov_b32_e32 v217, v218
	ds_read_b128 v[158:161], v216 offset:12288
	s_waitcnt vmcnt(8) lgkmcnt(6)
	v_mfma_f32_16x16x32_bf16 v[2:5], v[166:169], v[134:137], v[2:5]
	global_load_dwordx4 v[196:199], v220, s[8:9]
	v_mfma_f32_16x16x32_bf16 v[6:9], v[174:177], v[134:137], v[6:9]
	global_load_dwordx4 v[200:203], v220, s[8:9] offset:1024
	ds_read_b128 v[162:165], v216 offset:14336
	s_waitcnt lgkmcnt(6)
	v_mfma_f32_16x16x32_bf16 v[10:13], v[166:169], v[138:141], v[10:13]
	global_load_dwordx4 v[204:207], v221, s[8:9]
	v_mfma_f32_16x16x32_bf16 v[14:17], v[174:177], v[138:141], v[14:17]
	global_load_dwordx4 v[212:215], v221, s[8:9] offset:1024
	ds_read_b128 v[134:137], v216 offset:16384
	s_waitcnt lgkmcnt(6)
	v_mfma_f32_16x16x32_bf16 v[18:21], v[166:169], v[142:145], v[18:21]
	v_mfma_f32_16x16x32_bf16 v[22:25], v[174:177], v[142:145], v[22:25]
	ds_read_b128 v[138:141], v216 offset:18432
	s_waitcnt lgkmcnt(6)
	v_mfma_f32_16x16x32_bf16 v[26:29], v[166:169], v[146:149], v[26:29]
	v_mfma_f32_16x16x32_bf16 v[30:33], v[174:177], v[146:149], v[30:33]
	ds_read_b128 v[142:145], v216 offset:20480
	s_waitcnt lgkmcnt(6)
	v_mfma_f32_16x16x32_bf16 v[34:37], v[166:169], v[150:153], v[34:37]
	v_mfma_f32_16x16x32_bf16 v[38:41], v[174:177], v[150:153], v[38:41]
	ds_read_b128 v[146:149], v216 offset:22528
	s_waitcnt lgkmcnt(6)
	v_mfma_f32_16x16x32_bf16 v[42:45], v[166:169], v[154:157], v[42:45]
	v_mfma_f32_16x16x32_bf16 v[46:49], v[174:177], v[154:157], v[46:49]
	ds_read_b128 v[150:153], v216 offset:24576
	s_waitcnt lgkmcnt(6)
	v_mfma_f32_16x16x32_bf16 v[50:53], v[166:169], v[158:161], v[50:53]
	v_mfma_f32_16x16x32_bf16 v[54:57], v[174:177], v[158:161], v[54:57]
	ds_read_b128 v[154:157], v216 offset:26624
	s_waitcnt lgkmcnt(6)
	v_mfma_f32_16x16x32_bf16 v[58:61], v[166:169], v[162:165], v[58:61]
	v_mfma_f32_16x16x32_bf16 v[62:65], v[174:177], v[162:165], v[62:65]
	ds_read_b128 v[158:161], v216 offset:28672
	s_waitcnt lgkmcnt(6)
	v_mfma_f32_16x16x32_bf16 v[66:69], v[166:169], v[134:137], v[66:69]
	v_mfma_f32_16x16x32_bf16 v[70:73], v[174:177], v[134:137], v[70:73]
	ds_read_b128 v[162:165], v216 offset:30720
	s_waitcnt lgkmcnt(6)
	v_mfma_f32_16x16x32_bf16 v[74:77], v[166:169], v[138:141], v[74:77]
	v_mfma_f32_16x16x32_bf16 v[78:81], v[174:177], v[138:141], v[78:81]
	ds_read_b128 v[134:137], v216 offset:1024
	s_waitcnt lgkmcnt(6)
	v_mfma_f32_16x16x32_bf16 v[82:85], v[166:169], v[142:145], v[82:85]
	v_mfma_f32_16x16x32_bf16 v[86:89], v[174:177], v[142:145], v[86:89]
	ds_read_b128 v[138:141], v216 offset:3072
	s_waitcnt lgkmcnt(6)
	v_mfma_f32_16x16x32_bf16 v[90:93], v[166:169], v[146:149], v[90:93]
	v_mfma_f32_16x16x32_bf16 v[94:97], v[174:177], v[146:149], v[94:97]
	ds_read_b128 v[142:145], v216 offset:5120
	s_waitcnt lgkmcnt(6)
	v_mfma_f32_16x16x32_bf16 v[98:101], v[166:169], v[150:153], v[98:101]
	v_mfma_f32_16x16x32_bf16 v[102:105], v[174:177], v[150:153], v[102:105]
	ds_read_b128 v[146:149], v216 offset:7168
	s_waitcnt lgkmcnt(6)
	v_mfma_f32_16x16x32_bf16 v[106:109], v[166:169], v[154:157], v[106:109]
	v_mfma_f32_16x16x32_bf16 v[110:113], v[174:177], v[154:157], v[110:113]
	ds_read_b128 v[150:153], v216 offset:9216
	s_waitcnt lgkmcnt(6)
	v_mfma_f32_16x16x32_bf16 v[114:117], v[166:169], v[158:161], v[114:117]
	v_mfma_f32_16x16x32_bf16 v[118:121], v[174:177], v[158:161], v[118:121]
	ds_read_b128 v[154:157], v216 offset:11264
	s_waitcnt lgkmcnt(6)
	v_mfma_f32_16x16x32_bf16 v[122:125], v[166:169], v[162:165], v[122:125]
	v_mfma_f32_16x16x32_bf16 v[126:129], v[174:177], v[162:165], v[126:129]
	ds_read_b128 v[158:161], v216 offset:13312
	s_waitcnt lgkmcnt(6)
	v_mfma_f32_16x16x32_bf16 v[2:5], v[170:173], v[134:137], v[2:5]
	v_mfma_f32_16x16x32_bf16 v[6:9], v[178:181], v[134:137], v[6:9]
	ds_read_b128 v[162:165], v216 offset:15360
	s_waitcnt lgkmcnt(6)
	v_mfma_f32_16x16x32_bf16 v[10:13], v[170:173], v[138:141], v[10:13]
	v_mfma_f32_16x16x32_bf16 v[14:17], v[178:181], v[138:141], v[14:17]
	ds_read_b128 v[134:137], v216 offset:17408
	s_waitcnt lgkmcnt(6)
	v_mfma_f32_16x16x32_bf16 v[18:21], v[170:173], v[142:145], v[18:21]
	v_mfma_f32_16x16x32_bf16 v[22:25], v[178:181], v[142:145], v[22:25]
	ds_read_b128 v[138:141], v216 offset:19456
	s_waitcnt lgkmcnt(6)
	v_mfma_f32_16x16x32_bf16 v[26:29], v[170:173], v[146:149], v[26:29]
	v_mfma_f32_16x16x32_bf16 v[30:33], v[178:181], v[146:149], v[30:33]
	ds_read_b128 v[142:145], v216 offset:21504
	s_waitcnt lgkmcnt(6)
	v_mfma_f32_16x16x32_bf16 v[34:37], v[170:173], v[150:153], v[34:37]
	v_mfma_f32_16x16x32_bf16 v[38:41], v[178:181], v[150:153], v[38:41]
	ds_read_b128 v[146:149], v216 offset:23552
	s_waitcnt lgkmcnt(6)
	v_mfma_f32_16x16x32_bf16 v[42:45], v[170:173], v[154:157], v[42:45]
	v_mfma_f32_16x16x32_bf16 v[46:49], v[178:181], v[154:157], v[46:49]
	ds_read_b128 v[150:153], v216 offset:25600
	s_waitcnt lgkmcnt(6)
	v_mfma_f32_16x16x32_bf16 v[50:53], v[170:173], v[158:161], v[50:53]
	v_mfma_f32_16x16x32_bf16 v[54:57], v[178:181], v[158:161], v[54:57]
	ds_read_b128 v[154:157], v216 offset:27648
	s_waitcnt lgkmcnt(6)
	v_mfma_f32_16x16x32_bf16 v[58:61], v[170:173], v[162:165], v[58:61]
	v_mfma_f32_16x16x32_bf16 v[62:65], v[178:181], v[162:165], v[62:65]
	ds_read_b128 v[158:161], v216 offset:29696
	s_waitcnt lgkmcnt(6)
	v_mfma_f32_16x16x32_bf16 v[66:69], v[170:173], v[134:137], v[66:69]
	v_mfma_f32_16x16x32_bf16 v[70:73], v[178:181], v[134:137], v[70:73]
	ds_read_b128 v[162:165], v216 offset:31744
	s_waitcnt vmcnt(4) lgkmcnt(0)
	s_barrier
	v_mfma_f32_16x16x32_bf16 v[74:77], v[170:173], v[138:141], v[74:77]
	s_add_u32 m0, s22, 0x0
	v_mov_b32_e32 v223, v217
	global_load_lds_dwordx4 v223, s[6:7]
	v_mfma_f32_16x16x32_bf16 v[78:81], v[178:181], v[138:141], v[78:81]
	s_add_u32 m0, s22, 0x400
	v_add_u32_e32 v224, 0x40, v217
	global_load_lds_dwordx4 v224, s[6:7]
	ds_read_b128 v[134:137], v216 offset:32768
	s_waitcnt lgkmcnt(6)
	v_mfma_f32_16x16x32_bf16 v[82:85], v[170:173], v[142:145], v[82:85]
	s_add_u32 m0, s22, 0x800
	v_add_u32_e32 v223, 0x8000, v217
	global_load_lds_dwordx4 v223, s[6:7]
	v_mfma_f32_16x16x32_bf16 v[86:89], v[178:181], v[142:145], v[86:89]
	s_add_u32 m0, s22, 0xc00
	v_add_u32_e32 v224, 0x8040, v217
	global_load_lds_dwordx4 v224, s[6:7]
	ds_read_b128 v[138:141], v216 offset:34816
	s_waitcnt lgkmcnt(6)
	v_mfma_f32_16x16x32_bf16 v[90:93], v[170:173], v[146:149], v[90:93]
	s_add_u32 m0, s22, 0x1000
	v_add_u32_e32 v223, 0x10000, v217
	global_load_lds_dwordx4 v223, s[6:7]
	v_mfma_f32_16x16x32_bf16 v[94:97], v[178:181], v[146:149], v[94:97]
	s_add_u32 m0, s22, 0x1400
	v_add_u32_e32 v224, 0x10040, v217
	global_load_lds_dwordx4 v224, s[6:7]
	ds_read_b128 v[142:145], v216 offset:36864
	s_waitcnt lgkmcnt(6)
	v_mfma_f32_16x16x32_bf16 v[98:101], v[170:173], v[150:153], v[98:101]
	s_add_u32 m0, s22, 0x1800
	v_add_u32_e32 v223, 0x18000, v217
	global_load_lds_dwordx4 v223, s[6:7]
	v_mfma_f32_16x16x32_bf16 v[102:105], v[178:181], v[150:153], v[102:105]
	s_add_u32 m0, s22, 0x1c00
	v_add_u32_e32 v224, 0x18040, v217
	global_load_lds_dwordx4 v224, s[6:7]
	ds_read_b128 v[146:149], v216 offset:38912
	s_waitcnt lgkmcnt(6)
	v_mfma_f32_16x16x32_bf16 v[106:109], v[170:173], v[154:157], v[106:109]
	v_mfma_f32_16x16x32_bf16 v[110:113], v[178:181], v[154:157], v[110:113]
	ds_read_b128 v[150:153], v216 offset:40960
	s_waitcnt lgkmcnt(6)
	v_mfma_f32_16x16x32_bf16 v[114:117], v[170:173], v[158:161], v[114:117]
	v_mfma_f32_16x16x32_bf16 v[118:121], v[178:181], v[158:161], v[118:121]
	ds_read_b128 v[154:157], v216 offset:43008
	s_waitcnt lgkmcnt(6)
	v_mfma_f32_16x16x32_bf16 v[122:125], v[170:173], v[162:165], v[122:125]
	v_mfma_f32_16x16x32_bf16 v[126:129], v[178:181], v[162:165], v[126:129]
	v_add_u32_e32 v217, 0x80, v217
	v_add_u32_e32 v220, 0x800, v220
	v_add_u32_e32 v221, 0x800, v221
	s_lshr_b32 s3, s14, 4
	s_lshl_b32 s17, s15, 1
	s_add_u32 s3, s3, s17
	s_mul_i32 s17, s3, 0x8000
	s_add_u32 s8, s20, s17
	s_addc_u32 s9, s21, 0
	v_mov_b32_e32 v220, v222
	v_add_u32_e32 v221, 0x8000, v222
	ds_read_b128 v[158:161], v216 offset:45056
	s_waitcnt vmcnt(8) lgkmcnt(6)
	v_mfma_f32_16x16x32_bf16 v[2:5], v[196:199], v[134:137], v[2:5]
	global_load_dwordx4 v[166:169], v220, s[8:9]
	v_mfma_f32_16x16x32_bf16 v[6:9], v[204:207], v[134:137], v[6:9]
	global_load_dwordx4 v[170:173], v220, s[8:9] offset:1024
	ds_read_b128 v[162:165], v216 offset:47104
	s_waitcnt lgkmcnt(6)
	v_mfma_f32_16x16x32_bf16 v[10:13], v[196:199], v[138:141], v[10:13]
	global_load_dwordx4 v[174:177], v221, s[8:9]
	v_mfma_f32_16x16x32_bf16 v[14:17], v[204:207], v[138:141], v[14:17]
	global_load_dwordx4 v[178:181], v221, s[8:9] offset:1024
	ds_read_b128 v[134:137], v216 offset:49152
	s_waitcnt lgkmcnt(6)
	v_mfma_f32_16x16x32_bf16 v[18:21], v[196:199], v[142:145], v[18:21]
	v_mfma_f32_16x16x32_bf16 v[22:25], v[204:207], v[142:145], v[22:25]
	ds_read_b128 v[138:141], v216 offset:51200
	s_waitcnt lgkmcnt(6)
	v_mfma_f32_16x16x32_bf16 v[26:29], v[196:199], v[146:149], v[26:29]
	v_mfma_f32_16x16x32_bf16 v[30:33], v[204:207], v[146:149], v[30:33]
	ds_read_b128 v[142:145], v216 offset:53248
	s_waitcnt lgkmcnt(6)
	v_mfma_f32_16x16x32_bf16 v[34:37], v[196:199], v[150:153], v[34:37]
	v_mfma_f32_16x16x32_bf16 v[38:41], v[204:207], v[150:153], v[38:41]
	ds_read_b128 v[146:149], v216 offset:55296
	s_waitcnt lgkmcnt(6)
	v_mfma_f32_16x16x32_bf16 v[42:45], v[196:199], v[154:157], v[42:45]
	v_mfma_f32_16x16x32_bf16 v[46:49], v[204:207], v[154:157], v[46:49]
	ds_read_b128 v[150:153], v216 offset:57344
	s_waitcnt lgkmcnt(6)
	v_mfma_f32_16x16x32_bf16 v[50:53], v[196:199], v[158:161], v[50:53]
	v_mfma_f32_16x16x32_bf16 v[54:57], v[204:207], v[158:161], v[54:57]
	ds_read_b128 v[154:157], v216 offset:59392
	s_waitcnt lgkmcnt(6)
	v_mfma_f32_16x16x32_bf16 v[58:61], v[196:199], v[162:165], v[58:61]
	v_mfma_f32_16x16x32_bf16 v[62:65], v[204:207], v[162:165], v[62:65]
	ds_read_b128 v[158:161], v216 offset:61440
	s_waitcnt lgkmcnt(6)
	v_mfma_f32_16x16x32_bf16 v[66:69], v[196:199], v[134:137], v[66:69]
	v_mfma_f32_16x16x32_bf16 v[70:73], v[204:207], v[134:137], v[70:73]
	ds_read_b128 v[162:165], v216 offset:63488
	s_waitcnt lgkmcnt(6)
	v_mfma_f32_16x16x32_bf16 v[74:77], v[196:199], v[138:141], v[74:77]
	v_mfma_f32_16x16x32_bf16 v[78:81], v[204:207], v[138:141], v[78:81]
	ds_read_b128 v[134:137], v216 offset:33792
	s_waitcnt lgkmcnt(6)
	v_mfma_f32_16x16x32_bf16 v[82:85], v[196:199], v[142:145], v[82:85]
	v_mfma_f32_16x16x32_bf16 v[86:89], v[204:207], v[142:145], v[86:89]
	ds_read_b128 v[138:141], v216 offset:35840
	s_waitcnt lgkmcnt(6)
	v_mfma_f32_16x16x32_bf16 v[90:93], v[196:199], v[146:149], v[90:93]
	v_mfma_f32_16x16x32_bf16 v[94:97], v[204:207], v[146:149], v[94:97]
	ds_read_b128 v[142:145], v216 offset:37888
	s_waitcnt lgkmcnt(6)
	v_mfma_f32_16x16x32_bf16 v[98:101], v[196:199], v[150:153], v[98:101]
	v_mfma_f32_16x16x32_bf16 v[102:105], v[204:207], v[150:153], v[102:105]
	ds_read_b128 v[146:149], v216 offset:39936
	s_waitcnt lgkmcnt(6)
	v_mfma_f32_16x16x32_bf16 v[106:109], v[196:199], v[154:157], v[106:109]
	v_mfma_f32_16x16x32_bf16 v[110:113], v[204:207], v[154:157], v[110:113]
	ds_read_b128 v[150:153], v216 offset:41984
	s_waitcnt lgkmcnt(6)
	v_mfma_f32_16x16x32_bf16 v[114:117], v[196:199], v[158:161], v[114:117]
	v_mfma_f32_16x16x32_bf16 v[118:121], v[204:207], v[158:161], v[118:121]
	ds_read_b128 v[154:157], v216 offset:44032
	s_waitcnt lgkmcnt(6)
	v_mfma_f32_16x16x32_bf16 v[122:125], v[196:199], v[162:165], v[122:125]
	v_mfma_f32_16x16x32_bf16 v[126:129], v[204:207], v[162:165], v[126:129]
	ds_read_b128 v[158:161], v216 offset:46080
	s_waitcnt lgkmcnt(6)
	v_mfma_f32_16x16x32_bf16 v[2:5], v[200:203], v[134:137], v[2:5]
	v_mfma_f32_16x16x32_bf16 v[6:9], v[212:215], v[134:137], v[6:9]
	ds_read_b128 v[162:165], v216 offset:48128
	s_waitcnt lgkmcnt(6)
	v_mfma_f32_16x16x32_bf16 v[10:13], v[200:203], v[138:141], v[10:13]
	v_mfma_f32_16x16x32_bf16 v[14:17], v[212:215], v[138:141], v[14:17]
	ds_read_b128 v[134:137], v216 offset:50176
	s_waitcnt lgkmcnt(6)
	v_mfma_f32_16x16x32_bf16 v[18:21], v[200:203], v[142:145], v[18:21]
	v_mfma_f32_16x16x32_bf16 v[22:25], v[212:215], v[142:145], v[22:25]
	ds_read_b128 v[138:141], v216 offset:52224
	s_waitcnt lgkmcnt(6)
	v_mfma_f32_16x16x32_bf16 v[26:29], v[200:203], v[146:149], v[26:29]
	v_mfma_f32_16x16x32_bf16 v[30:33], v[212:215], v[146:149], v[30:33]
	ds_read_b128 v[142:145], v216 offset:54272
	s_waitcnt lgkmcnt(6)
	v_mfma_f32_16x16x32_bf16 v[34:37], v[200:203], v[150:153], v[34:37]
	v_mfma_f32_16x16x32_bf16 v[38:41], v[212:215], v[150:153], v[38:41]
	ds_read_b128 v[146:149], v216 offset:56320
	s_waitcnt lgkmcnt(6)
	v_mfma_f32_16x16x32_bf16 v[42:45], v[200:203], v[154:157], v[42:45]
	v_mfma_f32_16x16x32_bf16 v[46:49], v[212:215], v[154:157], v[46:49]
	ds_read_b128 v[150:153], v216 offset:58368
	s_waitcnt lgkmcnt(6)
	v_mfma_f32_16x16x32_bf16 v[50:53], v[200:203], v[158:161], v[50:53]
	v_mfma_f32_16x16x32_bf16 v[54:57], v[212:215], v[158:161], v[54:57]
	ds_read_b128 v[154:157], v216 offset:60416
	s_waitcnt lgkmcnt(6)
	v_mfma_f32_16x16x32_bf16 v[58:61], v[200:203], v[162:165], v[58:61]
	v_mfma_f32_16x16x32_bf16 v[62:65], v[212:215], v[162:165], v[62:65]
	ds_read_b128 v[158:161], v216 offset:62464
	s_waitcnt lgkmcnt(6)
	v_mfma_f32_16x16x32_bf16 v[66:69], v[200:203], v[134:137], v[66:69]
	v_mfma_f32_16x16x32_bf16 v[70:73], v[212:215], v[134:137], v[70:73]
	ds_read_b128 v[162:165], v216 offset:64512
	s_waitcnt vmcnt(4) lgkmcnt(0)
	s_barrier
	v_mfma_f32_16x16x32_bf16 v[74:77], v[200:203], v[138:141], v[74:77]
	s_add_u32 m0, s22, 0x8000
	v_mov_b32_e32 v223, v217
	global_load_lds_dwordx4 v223, s[6:7]
	v_mfma_f32_16x16x32_bf16 v[78:81], v[212:215], v[138:141], v[78:81]
	s_add_u32 m0, s22, 0x8400
	v_add_u32_e32 v224, 0x40, v217
	global_load_lds_dwordx4 v224, s[6:7]
	ds_read_b128 v[134:137], v216
	s_waitcnt lgkmcnt(6)
	v_mfma_f32_16x16x32_bf16 v[82:85], v[200:203], v[142:145], v[82:85]
	s_add_u32 m0, s22, 0x8800
	v_add_u32_e32 v223, 0x8000, v217
	global_load_lds_dwordx4 v223, s[6:7]
	v_mfma_f32_16x16x32_bf16 v[86:89], v[212:215], v[142:145], v[86:89]
	s_add_u32 m0, s22, 0x8c00
	v_add_u32_e32 v224, 0x8040, v217
	global_load_lds_dwordx4 v224, s[6:7]
	ds_read_b128 v[138:141], v216 offset:2048
	s_waitcnt lgkmcnt(6)
	v_mfma_f32_16x16x32_bf16 v[90:93], v[200:203], v[146:149], v[90:93]
	s_add_u32 m0, s22, 0x9000
	v_add_u32_e32 v223, 0x10000, v217
	global_load_lds_dwordx4 v223, s[6:7]
	v_mfma_f32_16x16x32_bf16 v[94:97], v[212:215], v[146:149], v[94:97]
	s_add_u32 m0, s22, 0x9400
	v_add_u32_e32 v224, 0x10040, v217
	global_load_lds_dwordx4 v224, s[6:7]
	ds_read_b128 v[142:145], v216 offset:4096
	s_waitcnt lgkmcnt(6)
	v_mfma_f32_16x16x32_bf16 v[98:101], v[200:203], v[150:153], v[98:101]
	s_add_u32 m0, s22, 0x9800
	v_add_u32_e32 v223, 0x18000, v217
	global_load_lds_dwordx4 v223, s[6:7]
	v_mfma_f32_16x16x32_bf16 v[102:105], v[212:215], v[150:153], v[102:105]
	s_add_u32 m0, s22, 0x9c00
	v_add_u32_e32 v224, 0x18040, v217
	global_load_lds_dwordx4 v224, s[6:7]
	ds_read_b128 v[146:149], v216 offset:6144
	s_waitcnt lgkmcnt(6)
	v_mfma_f32_16x16x32_bf16 v[106:109], v[200:203], v[154:157], v[106:109]
	v_mfma_f32_16x16x32_bf16 v[110:113], v[212:215], v[154:157], v[110:113]
	ds_read_b128 v[150:153], v216 offset:8192
	s_waitcnt lgkmcnt(6)
	v_mfma_f32_16x16x32_bf16 v[114:117], v[200:203], v[158:161], v[114:117]
	v_mfma_f32_16x16x32_bf16 v[118:121], v[212:215], v[158:161], v[118:121]
	ds_read_b128 v[154:157], v216 offset:10240
	s_waitcnt lgkmcnt(6)
	v_mfma_f32_16x16x32_bf16 v[122:125], v[200:203], v[162:165], v[122:125]
	v_mfma_f32_16x16x32_bf16 v[126:129], v[212:215], v[162:165], v[126:129]
	v_add_u32_e32 v217, 0x80, v217
	v_add_u32_e32 v220, 0x800, v220
	v_add_u32_e32 v221, 0x800, v221
	s_mov_b32 s16, 1
	s_branch .Lg256b_wo_epi

.LBB0_805:
	s_andn2_b64 vcc, exec, s[4:5]
	s_cbranch_vccnz .LBB0_843
	v_readlane_b32 s4, v239, 13
	v_readlane_b32 s5, v239, 14
	s_andn2_b64 vcc, exec, s[4:5]
	s_cbranch_vccnz .LBB0_843
	s_load_dwordx2 s[4:5], s[0:1], 0x130
	v_and_b32_e32 v0, 63, v133
	v_lshrrev_b32_e32 v131, 6, v133
	v_lshrrev_b32_e32 v195, 2, v0
	v_readfirstlane_b32 s15, v131
	v_mul_u32_u24_e32 v218, 0x800, v195
	v_and_b32_e32 v195, 3, v0
	v_lshlrev_b32_e32 v195, 4, v195
	v_lshrrev_b32_e32 v131, 5, v0
	v_lshlrev_b32_e32 v131, 5, v131
	v_xor_b32_e32 v195, v195, v131
	v_add_u32_e32 v218, v218, v195
	v_and_b32_e32 v195, 15, v0
	v_lshrrev_b32_e32 v131, 4, v0
	v_lshlrev_b32_e32 v216, 6, v195
	v_lshl_or_b32 v216, v131, 4, v216
	v_and_b32_e32 v219, 8, v0
	v_lshlrev_b32_e32 v219, 2, v219
	v_xor_b32_e32 v216, v216, v219
	v_mul_u32_u24_e32 v219, 0x1440, v195
	v_lshl_or_b32 v219, v131, 3, v219
	v_lshlrev_b32_e32 v222, 4, v0
	s_waitcnt lgkmcnt(0)
	s_add_u32 s18, s4, 0x2b27800
	s_addc_u32 s19, s5, 0
	s_add_u32 s20, s4, 0x9e7800
	s_addc_u32 s21, s5, 0
	s_add_u32 s24, s4, 0x4b27800
	s_addc_u32 s25, s5, 0
	s_lshl_b32 s22, s15, 13
	s_mov_b32 s12, s79
.Lg256b_ip_first_retry:
	s_cmp_ge_u32 s12, 192
	s_cbranch_scc1 .Lg256b_ip_done
	s_lshr_b32 s3, s12, 6
	s_lshl_b32 s3, s3, 3
	s_add_u32 s3, s3, s65
	s_mul_i32 s17, s3, 11
	s_lshr_b32 s17, s17, 5
	s_mul_i32 s23, s17, 3
	s_sub_u32 s3, s3, s23
	s_lshl_b32 s17, s17, 3
	s_bfe_u32 s23, s12, 0x30003
	s_add_u32 s13, s17, s23
	s_lshl_b32 s3, s3, 3
	s_and_b32 s23, s12, 7
	s_add_u32 s14, s3, s23
	s_cmp_lt_u32 s14, 21
	s_cbranch_scc1 .Lg256b_ip_first_ok
	s_add_u32 s12, s12, s83
	s_branch .Lg256b_ip_first_retry
.Lg256b_ip_first_ok:
	s_lshl_b32 s13, s13, 8
	s_lshl_b32 s14, s14, 7
	s_lshl_b32 s3, s15, 6
	s_add_u32 s17, s3, s13
	s_mul_i32 s17, s17, 0x800
	s_add_u32 s6, s18, s17
	s_addc_u32 s7, s19, 0
	s_lshr_b32 s3, s14, 4
	s_lshl_b32 s17, s15, 1
	s_add_u32 s3, s3, s17
	s_mul_i32 s17, s3, 0x8000
	s_add_u32 s8, s20, s17
	s_addc_u32 s9, s21, 0
	s_barrier
	v_mov_b32_e32 v217, v218
	v_mov_b32_e32 v220, v222
	v_add_u32_e32 v221, 0x8000, v222
	s_add_u32 m0, s22, 0x0
	v_mov_b32_e32 v223, v217
	global_load_lds_dwordx4 v223, s[6:7]
	s_add_u32 m0, s22, 0x400
	v_add_u32_e32 v224, 0x40, v217
	global_load_lds_dwordx4 v224, s[6:7]
	s_add_u32 m0, s22, 0x800
	v_add_u32_e32 v223, 0x8000, v217
	global_load_lds_dwordx4 v223, s[6:7]
	s_add_u32 m0, s22, 0xc00
	v_add_u32_e32 v224, 0x8040, v217
	global_load_lds_dwordx4 v224, s[6:7]
	s_add_u32 m0, s22, 0x1000
	v_add_u32_e32 v223, 0x10000, v217
	global_load_lds_dwordx4 v223, s[6:7]
	s_add_u32 m0, s22, 0x1400
	v_add_u32_e32 v224, 0x10040, v217
	global_load_lds_dwordx4 v224, s[6:7]
	s_add_u32 m0, s22, 0x1800
	v_add_u32_e32 v223, 0x18000, v217
	global_load_lds_dwordx4 v223, s[6:7]
	s_add_u32 m0, s22, 0x1c00
	v_add_u32_e32 v224, 0x18040, v217
	global_load_lds_dwordx4 v224, s[6:7]
	v_add_u32_e32 v217, 0x80, v217
	s_add_u32 m0, s22, 0x8000
	v_mov_b32_e32 v223, v217
	global_load_lds_dwordx4 v223, s[6:7]
	s_add_u32 m0, s22, 0x8400
	v_add_u32_e32 v224, 0x40, v217
	global_load_lds_dwordx4 v224, s[6:7]
	s_add_u32 m0, s22, 0x8800
	v_add_u32_e32 v223, 0x8000, v217
	global_load_lds_dwordx4 v223, s[6:7]
	s_add_u32 m0, s22, 0x8c00
	v_add_u32_e32 v224, 0x8040, v217
	global_load_lds_dwordx4 v224, s[6:7]
	s_add_u32 m0, s22, 0x9000
	v_add_u32_e32 v223, 0x10000, v217
	global_load_lds_dwordx4 v223, s[6:7]
	s_add_u32 m0, s22, 0x9400
	v_add_u32_e32 v224, 0x10040, v217
	global_load_lds_dwordx4 v224, s[6:7]
	s_add_u32 m0, s22, 0x9800
	v_add_u32_e32 v223, 0x18000, v217
	global_load_lds_dwordx4 v223, s[6:7]
	s_add_u32 m0, s22, 0x9c00
	v_add_u32_e32 v224, 0x18040, v217
	global_load_lds_dwordx4 v224, s[6:7]
	v_add_u32_e32 v217, 0x80, v217
	global_load_dwordx4 v[166:169], v220, s[8:9]
	global_load_dwordx4 v[170:173], v220, s[8:9] offset:1024
	global_load_dwordx4 v[174:177], v221, s[8:9]
	global_load_dwordx4 v[178:181], v221, s[8:9] offset:1024
	v_add_u32_e32 v220, 0x800, v220
	v_add_u32_e32 v221, 0x800, v221
	s_waitcnt vmcnt(0)
	s_barrier
	ds_read_b128 v[134:137], v216
	ds_read_b128 v[138:141], v216 offset:2048
	ds_read_b128 v[142:145], v216 offset:4096
	ds_read_b128 v[146:149], v216 offset:6144
	ds_read_b128 v[150:153], v216 offset:8192
	ds_read_b128 v[154:157], v216 offset:10240
.Lg256b_ip_tile:
	s_mul_i32 s17, s13, 0x1440
	s_lshl_b32 s3, s15, 5
	s_add_u32 s3, s3, s14
	s_mul_i32 s3, s3, 2
	s_add_u32 s17, s17, s3
	s_add_u32 s10, s24, s17
	s_addc_u32 s11, s25, 0
	s_cmp_eq_u32 s14, 2560
	s_cselect_b32 s27, 1, 0
	s_cmp_lg_u32 s15, 0
	s_cselect_b32 s3, 1, 0
	s_and_b32 s27, s27, s3
	ds_read_b128 v[158:161], v216 offset:12288
	s_waitcnt vmcnt(0) lgkmcnt(6)
	v_mfma_f32_16x16x32_bf16 v[2:5], v[166:169], v[134:137], 0
	global_load_dwordx4 v[196:199], v220, s[8:9]
	v_mfma_f32_16x16x32_bf16 v[6:9], v[174:177], v[134:137], 0
	global_load_dwordx4 v[200:203], v220, s[8:9] offset:1024
	ds_read_b128 v[162:165], v216 offset:14336
	s_waitcnt lgkmcnt(6)
	v_mfma_f32_16x16x32_bf16 v[10:13], v[166:169], v[138:141], 0
	global_load_dwordx4 v[204:207], v221, s[8:9]
	v_mfma_f32_16x16x32_bf16 v[14:17], v[174:177], v[138:141], 0
	global_load_dwordx4 v[212:215], v221, s[8:9] offset:1024
	ds_read_b128 v[134:137], v216 offset:16384
	s_waitcnt lgkmcnt(6)
	v_mfma_f32_16x16x32_bf16 v[18:21], v[166:169], v[142:145], 0
	v_mfma_f32_16x16x32_bf16 v[22:25], v[174:177], v[142:145], 0
	ds_read_b128 v[138:141], v216 offset:18432
	s_waitcnt lgkmcnt(6)
	v_mfma_f32_16x16x32_bf16 v[26:29], v[166:169], v[146:149], 0
	v_mfma_f32_16x16x32_bf16 v[30:33], v[174:177], v[146:149], 0
	ds_read_b128 v[142:145], v216 offset:20480
	s_waitcnt lgkmcnt(6)
	v_mfma_f32_16x16x32_bf16 v[34:37], v[166:169], v[150:153], 0
	v_mfma_f32_16x16x32_bf16 v[38:41], v[174:177], v[150:153], 0
	ds_read_b128 v[146:149], v216 offset:22528
	s_waitcnt lgkmcnt(6)
	v_mfma_f32_16x16x32_bf16 v[42:45], v[166:169], v[154:157], 0
	v_mfma_f32_16x16x32_bf16 v[46:49], v[174:177], v[154:157], 0
	ds_read_b128 v[150:153], v216 offset:24576
	s_waitcnt lgkmcnt(6)
	v_mfma_f32_16x16x32_bf16 v[50:53], v[166:169], v[158:161], 0
	v_mfma_f32_16x16x32_bf16 v[54:57], v[174:177], v[158:161], 0
	ds_read_b128 v[154:157], v216 offset:26624
	s_waitcnt lgkmcnt(6)
	v_mfma_f32_16x16x32_bf16 v[58:61], v[166:169], v[162:165], 0
	v_mfma_f32_16x16x32_bf16 v[62:65], v[174:177], v[162:165], 0
	ds_read_b128 v[158:161], v216 offset:28672
	s_waitcnt lgkmcnt(6)
	v_mfma_f32_16x16x32_bf16 v[66:69], v[166:169], v[134:137], 0
	v_mfma_f32_16x16x32_bf16 v[70:73], v[174:177], v[134:137], 0
	ds_read_b128 v[162:165], v216 offset:30720
	s_waitcnt lgkmcnt(6)
	v_mfma_f32_16x16x32_bf16 v[74:77], v[166:169], v[138:141], 0
	v_mfma_f32_16x16x32_bf16 v[78:81], v[174:177], v[138:141], 0
	ds_read_b128 v[134:137], v216 offset:1024
	s_waitcnt lgkmcnt(6)
	v_mfma_f32_16x16x32_bf16 v[82:85], v[166:169], v[142:145], 0
	v_mfma_f32_16x16x32_bf16 v[86:89], v[174:177], v[142:145], 0
	ds_read_b128 v[138:141], v216 offset:3072
	s_waitcnt lgkmcnt(6)
	v_mfma_f32_16x16x32_bf16 v[90:93], v[166:169], v[146:149], 0
	v_mfma_f32_16x16x32_bf16 v[94:97], v[174:177], v[146:149], 0
	ds_read_b128 v[142:145], v216 offset:5120
	s_waitcnt lgkmcnt(6)
	v_mfma_f32_16x16x32_bf16 v[98:101], v[166:169], v[150:153], 0
	v_mfma_f32_16x16x32_bf16 v[102:105], v[174:177], v[150:153], 0
	ds_read_b128 v[146:149], v216 offset:7168
	s_waitcnt lgkmcnt(6)
	v_mfma_f32_16x16x32_bf16 v[106:109], v[166:169], v[154:157], 0
	v_mfma_f32_16x16x32_bf16 v[110:113], v[174:177], v[154:157], 0
	ds_read_b128 v[150:153], v216 offset:9216
	s_waitcnt lgkmcnt(6)
	v_mfma_f32_16x16x32_bf16 v[114:117], v[166:169], v[158:161], 0
	v_mfma_f32_16x16x32_bf16 v[118:121], v[174:177], v[158:161], 0
	ds_read_b128 v[154:157], v216 offset:11264
	s_waitcnt lgkmcnt(6)
	v_mfma_f32_16x16x32_bf16 v[122:125], v[166:169], v[162:165], 0
	v_mfma_f32_16x16x32_bf16 v[126:129], v[174:177], v[162:165], 0
	ds_read_b128 v[158:161], v216 offset:13312
	s_waitcnt lgkmcnt(6)
	v_mfma_f32_16x16x32_bf16 v[2:5], v[170:173], v[134:137], v[2:5]
	v_mfma_f32_16x16x32_bf16 v[6:9], v[178:181], v[134:137], v[6:9]
	ds_read_b128 v[162:165], v216 offset:15360
	s_waitcnt lgkmcnt(6)
	v_mfma_f32_16x16x32_bf16 v[10:13], v[170:173], v[138:141], v[10:13]
	v_mfma_f32_16x16x32_bf16 v[14:17], v[178:181], v[138:141], v[14:17]
	ds_read_b128 v[134:137], v216 offset:17408
	s_waitcnt lgkmcnt(6)
	v_mfma_f32_16x16x32_bf16 v[18:21], v[170:173], v[142:145], v[18:21]
	v_mfma_f32_16x16x32_bf16 v[22:25], v[178:181], v[142:145], v[22:25]
	ds_read_b128 v[138:141], v216 offset:19456
	s_waitcnt lgkmcnt(6)
	v_mfma_f32_16x16x32_bf16 v[26:29], v[170:173], v[146:149], v[26:29]
	v_mfma_f32_16x16x32_bf16 v[30:33], v[178:181], v[146:149], v[30:33]
	ds_read_b128 v[142:145], v216 offset:21504
	s_waitcnt lgkmcnt(6)
	v_mfma_f32_16x16x32_bf16 v[34:37], v[170:173], v[150:153], v[34:37]
	v_mfma_f32_16x16x32_bf16 v[38:41], v[178:181], v[150:153], v[38:41]
	ds_read_b128 v[146:149], v216 offset:23552
	s_waitcnt lgkmcnt(6)
	v_mfma_f32_16x16x32_bf16 v[42:45], v[170:173], v[154:157], v[42:45]
	v_mfma_f32_16x16x32_bf16 v[46:49], v[178:181], v[154:157], v[46:49]
	ds_read_b128 v[150:153], v216 offset:25600
	s_waitcnt lgkmcnt(6)
	v_mfma_f32_16x16x32_bf16 v[50:53], v[170:173], v[158:161], v[50:53]
	v_mfma_f32_16x16x32_bf16 v[54:57], v[178:181], v[158:161], v[54:57]
	ds_read_b128 v[154:157], v216 offset:27648
	s_waitcnt lgkmcnt(6)
	v_mfma_f32_16x16x32_bf16 v[58:61], v[170:173], v[162:165], v[58:61]
	v_mfma_f32_16x16x32_bf16 v[62:65], v[178:181], v[162:165], v[62:65]
	ds_read_b128 v[158:161], v216 offset:29696
	s_waitcnt lgkmcnt(6)
	v_mfma_f32_16x16x32_bf16 v[66:69], v[170:173], v[134:137], v[66:69]
	v_mfma_f32_16x16x32_bf16 v[70:73], v[178:181], v[134:137], v[70:73]
	ds_read_b128 v[162:165], v216 offset:31744
	s_waitcnt vmcnt(0) lgkmcnt(0)
	s_barrier
	v_mfma_f32_16x16x32_bf16 v[74:77], v[170:173], v[138:141], v[74:77]
	s_add_u32 m0, s22, 0x0
	v_mov_b32_e32 v223, v217
	global_load_lds_dwordx4 v223, s[6:7]
	v_mfma_f32_16x16x32_bf16 v[78:81], v[178:181], v[138:141], v[78:81]
	s_add_u32 m0, s22, 0x400
	v_add_u32_e32 v224, 0x40, v217
	global_load_lds_dwordx4 v224, s[6:7]
	ds_read_b128 v[134:137], v216 offset:32768
	s_waitcnt lgkmcnt(6)
	v_mfma_f32_16x16x32_bf16 v[82:85], v[170:173], v[142:145], v[82:85]
	s_add_u32 m0, s22, 0x800
	v_add_u32_e32 v223, 0x8000, v217
	global_load_lds_dwordx4 v223, s[6:7]
	v_mfma_f32_16x16x32_bf16 v[86:89], v[178:181], v[142:145], v[86:89]
	s_add_u32 m0, s22, 0xc00
	v_add_u32_e32 v224, 0x8040, v217
	global_load_lds_dwordx4 v224, s[6:7]
	ds_read_b128 v[138:141], v216 offset:34816
	s_waitcnt lgkmcnt(6)
	v_mfma_f32_16x16x32_bf16 v[90:93], v[170:173], v[146:149], v[90:93]
	s_add_u32 m0, s22, 0x1000
	v_add_u32_e32 v223, 0x10000, v217
	global_load_lds_dwordx4 v223, s[6:7]
	v_mfma_f32_16x16x32_bf16 v[94:97], v[178:181], v[146:149], v[94:97]
	s_add_u32 m0, s22, 0x1400
	v_add_u32_e32 v224, 0x10040, v217
	global_load_lds_dwordx4 v224, s[6:7]
	ds_read_b128 v[142:145], v216 offset:36864
	s_waitcnt lgkmcnt(6)
	v_mfma_f32_16x16x32_bf16 v[98:101], v[170:173], v[150:153], v[98:101]
	s_add_u32 m0, s22, 0x1800
	v_add_u32_e32 v223, 0x18000, v217
	global_load_lds_dwordx4 v223, s[6:7]
	v_mfma_f32_16x16x32_bf16 v[102:105], v[178:181], v[150:153], v[102:105]
	s_add_u32 m0, s22, 0x1c00
	v_add_u32_e32 v224, 0x18040, v217
	global_load_lds_dwordx4 v224, s[6:7]
	ds_read_b128 v[146:149], v216 offset:38912
	s_waitcnt lgkmcnt(6)
	v_mfma_f32_16x16x32_bf16 v[106:109], v[170:173], v[154:157], v[106:109]
	v_mfma_f32_16x16x32_bf16 v[110:113], v[178:181], v[154:157], v[110:113]
	ds_read_b128 v[150:153], v216 offset:40960
	s_waitcnt lgkmcnt(6)
	v_mfma_f32_16x16x32_bf16 v[114:117], v[170:173], v[158:161], v[114:117]
	v_mfma_f32_16x16x32_bf16 v[118:121], v[178:181], v[158:161], v[118:121]
	ds_read_b128 v[154:157], v216 offset:43008
	s_waitcnt lgkmcnt(6)
	v_mfma_f32_16x16x32_bf16 v[122:125], v[170:173], v[162:165], v[122:125]
	v_mfma_f32_16x16x32_bf16 v[126:129], v[178:181], v[162:165], v[126:129]
	v_add_u32_e32 v217, 0x80, v217
	v_add_u32_e32 v220, 0x800, v220
	v_add_u32_e32 v221, 0x800, v221
	ds_read_b128 v[158:161], v216 offset:45056
	s_waitcnt vmcnt(8) lgkmcnt(6)
	v_mfma_f32_16x16x32_bf16 v[2:5], v[196:199], v[134:137], v[2:5]
	global_load_dwordx4 v[166:169], v220, s[8:9]
	v_mfma_f32_16x16x32_bf16 v[6:9], v[204:207], v[134:137], v[6:9]
	global_load_dwordx4 v[170:173], v220, s[8:9] offset:1024
	ds_read_b128 v[162:165], v216 offset:47104
	s_waitcnt lgkmcnt(6)
	v_mfma_f32_16x16x32_bf16 v[10:13], v[196:199], v[138:141], v[10:13]
	global_load_dwordx4 v[174:177], v221, s[8:9]
	v_mfma_f32_16x16x32_bf16 v[14:17], v[204:207], v[138:141], v[14:17]
	global_load_dwordx4 v[178:181], v221, s[8:9] offset:1024
	ds_read_b128 v[134:137], v216 offset:49152
	s_waitcnt lgkmcnt(6)
	v_mfma_f32_16x16x32_bf16 v[18:21], v[196:199], v[142:145], v[18:21]
	v_mfma_f32_16x16x32_bf16 v[22:25], v[204:207], v[142:145], v[22:25]
	ds_read_b128 v[138:141], v216 offset:51200
	s_waitcnt lgkmcnt(6)
	v_mfma_f32_16x16x32_bf16 v[26:29], v[196:199], v[146:149], v[26:29]
	v_mfma_f32_16x16x32_bf16 v[30:33], v[204:207], v[146:149], v[30:33]
	ds_read_b128 v[142:145], v216 offset:53248
	s_waitcnt lgkmcnt(6)
	v_mfma_f32_16x16x32_bf16 v[34:37], v[196:199], v[150:153], v[34:37]
	v_mfma_f32_16x16x32_bf16 v[38:41], v[204:207], v[150:153], v[38:41]
	ds_read_b128 v[146:149], v216 offset:55296
	s_waitcnt lgkmcnt(6)
	v_mfma_f32_16x16x32_bf16 v[42:45], v[196:199], v[154:157], v[42:45]
	v_mfma_f32_16x16x32_bf16 v[46:49], v[204:207], v[154:157], v[46:49]
	ds_read_b128 v[150:153], v216 offset:57344
	s_waitcnt lgkmcnt(6)
	v_mfma_f32_16x16x32_bf16 v[50:53], v[196:199], v[158:161], v[50:53]
	v_mfma_f32_16x16x32_bf16 v[54:57], v[204:207], v[158:161], v[54:57]
	ds_read_b128 v[154:157], v216 offset:59392
	s_waitcnt lgkmcnt(6)
	v_mfma_f32_16x16x32_bf16 v[58:61], v[196:199], v[162:165], v[58:61]
	v_mfma_f32_16x16x32_bf16 v[62:65], v[204:207], v[162:165], v[62:65]
	ds_read_b128 v[158:161], v216 offset:61440
	s_waitcnt lgkmcnt(6)
	v_mfma_f32_16x16x32_bf16 v[66:69], v[196:199], v[134:137], v[66:69]
	v_mfma_f32_16x16x32_bf16 v[70:73], v[204:207], v[134:137], v[70:73]
	ds_read_b128 v[162:165], v216 offset:63488
	s_waitcnt lgkmcnt(6)
	v_mfma_f32_16x16x32_bf16 v[74:77], v[196:199], v[138:141], v[74:77]
	v_mfma_f32_16x16x32_bf16 v[78:81], v[204:207], v[138:141], v[78:81]
	ds_read_b128 v[134:137], v216 offset:33792
	s_waitcnt lgkmcnt(6)
	v_mfma_f32_16x16x32_bf16 v[82:85], v[196:199], v[142:145], v[82:85]
	v_mfma_f32_16x16x32_bf16 v[86:89], v[204:207], v[142:145], v[86:89]
	ds_read_b128 v[138:141], v216 offset:35840
	s_waitcnt lgkmcnt(6)
	v_mfma_f32_16x16x32_bf16 v[90:93], v[196:199], v[146:149], v[90:93]
	v_mfma_f32_16x16x32_bf16 v[94:97], v[204:207], v[146:149], v[94:97]
	ds_read_b128 v[142:145], v216 offset:37888
	s_waitcnt lgkmcnt(6)
	v_mfma_f32_16x16x32_bf16 v[98:101], v[196:199], v[150:153], v[98:101]
	v_mfma_f32_16x16x32_bf16 v[102:105], v[204:207], v[150:153], v[102:105]
	ds_read_b128 v[146:149], v216 offset:39936
	s_waitcnt lgkmcnt(6)
	v_mfma_f32_16x16x32_bf16 v[106:109], v[196:199], v[154:157], v[106:109]
	v_mfma_f32_16x16x32_bf16 v[110:113], v[204:207], v[154:157], v[110:113]
	ds_read_b128 v[150:153], v216 offset:41984
	s_waitcnt lgkmcnt(6)
	v_mfma_f32_16x16x32_bf16 v[114:117], v[196:199], v[158:161], v[114:117]
	v_mfma_f32_16x16x32_bf16 v[118:121], v[204:207], v[158:161], v[118:121]
	ds_read_b128 v[154:157], v216 offset:44032
	s_waitcnt lgkmcnt(6)
	v_mfma_f32_16x16x32_bf16 v[122:125], v[196:199], v[162:165], v[122:125]
	v_mfma_f32_16x16x32_bf16 v[126:129], v[204:207], v[162:165], v[126:129]
	ds_read_b128 v[158:161], v216 offset:46080
	s_waitcnt lgkmcnt(6)
	v_mfma_f32_16x16x32_bf16 v[2:5], v[200:203], v[134:137], v[2:5]
	v_mfma_f32_16x16x32_bf16 v[6:9], v[212:215], v[134:137], v[6:9]
	ds_read_b128 v[162:165], v216 offset:48128
	s_waitcnt lgkmcnt(6)
	v_mfma_f32_16x16x32_bf16 v[10:13], v[200:203], v[138:141], v[10:13]
	v_mfma_f32_16x16x32_bf16 v[14:17], v[212:215], v[138:141], v[14:17]
	ds_read_b128 v[134:137], v216 offset:50176
	s_waitcnt lgkmcnt(6)
	v_mfma_f32_16x16x32_bf16 v[18:21], v[200:203], v[142:145], v[18:21]
	v_mfma_f32_16x16x32_bf16 v[22:25], v[212:215], v[142:145], v[22:25]
	ds_read_b128 v[138:141], v216 offset:52224
	s_waitcnt lgkmcnt(6)
	v_mfma_f32_16x16x32_bf16 v[26:29], v[200:203], v[146:149], v[26:29]
	v_mfma_f32_16x16x32_bf16 v[30:33], v[212:215], v[146:149], v[30:33]
	ds_read_b128 v[142:145], v216 offset:54272
	s_waitcnt lgkmcnt(6)
	v_mfma_f32_16x16x32_bf16 v[34:37], v[200:203], v[150:153], v[34:37]
	v_mfma_f32_16x16x32_bf16 v[38:41], v[212:215], v[150:153], v[38:41]
	ds_read_b128 v[146:149], v216 offset:56320
	s_waitcnt lgkmcnt(6)
	v_mfma_f32_16x16x32_bf16 v[42:45], v[200:203], v[154:157], v[42:45]
	v_mfma_f32_16x16x32_bf16 v[46:49], v[212:215], v[154:157], v[46:49]
	ds_read_b128 v[150:153], v216 offset:58368
	s_waitcnt lgkmcnt(6)
	v_mfma_f32_16x16x32_bf16 v[50:53], v[200:203], v[158:161], v[50:53]
	v_mfma_f32_16x16x32_bf16 v[54:57], v[212:215], v[158:161], v[54:57]
	ds_read_b128 v[154:157], v216 offset:60416
	s_waitcnt lgkmcnt(6)
	v_mfma_f32_16x16x32_bf16 v[58:61], v[200:203], v[162:165], v[58:61]
	v_mfma_f32_16x16x32_bf16 v[62:65], v[212:215], v[162:165], v[62:65]
	ds_read_b128 v[158:161], v216 offset:62464
	s_waitcnt lgkmcnt(6)
	v_mfma_f32_16x16x32_bf16 v[66:69], v[200:203], v[134:137], v[66:69]
	v_mfma_f32_16x16x32_bf16 v[70:73], v[212:215], v[134:137], v[70:73]
	ds_read_b128 v[162:165], v216 offset:64512
	s_waitcnt vmcnt(4) lgkmcnt(0)
	s_barrier
	v_mfma_f32_16x16x32_bf16 v[74:77], v[200:203], v[138:141], v[74:77]
	s_add_u32 m0, s22, 0x8000
	v_mov_b32_e32 v223, v217
	global_load_lds_dwordx4 v223, s[6:7]
	v_mfma_f32_16x16x32_bf16 v[78:81], v[212:215], v[138:141], v[78:81]
	s_add_u32 m0, s22, 0x8400
	v_add_u32_e32 v224, 0x40, v217
	global_load_lds_dwordx4 v224, s[6:7]
	ds_read_b128 v[134:137], v216
	s_waitcnt lgkmcnt(6)
	v_mfma_f32_16x16x32_bf16 v[82:85], v[200:203], v[142:145], v[82:85]
	s_add_u32 m0, s22, 0x8800
	v_add_u32_e32 v223, 0x8000, v217
	global_load_lds_dwordx4 v223, s[6:7]
	v_mfma_f32_16x16x32_bf16 v[86:89], v[212:215], v[142:145], v[86:89]
	s_add_u32 m0, s22, 0x8c00
	v_add_u32_e32 v224, 0x8040, v217
	global_load_lds_dwordx4 v224, s[6:7]
	ds_read_b128 v[138:141], v216 offset:2048
	s_waitcnt lgkmcnt(6)
	v_mfma_f32_16x16x32_bf16 v[90:93], v[200:203], v[146:149], v[90:93]
	s_add_u32 m0, s22, 0x9000
	v_add_u32_e32 v223, 0x10000, v217
	global_load_lds_dwordx4 v223, s[6:7]
	v_mfma_f32_16x16x32_bf16 v[94:97], v[212:215], v[146:149], v[94:97]
	s_add_u32 m0, s22, 0x9400
	v_add_u32_e32 v224, 0x10040, v217
	global_load_lds_dwordx4 v224, s[6:7]
	ds_read_b128 v[142:145], v216 offset:4096
	s_waitcnt lgkmcnt(6)
	v_mfma_f32_16x16x32_bf16 v[98:101], v[200:203], v[150:153], v[98:101]
	s_add_u32 m0, s22, 0x9800
	v_add_u32_e32 v223, 0x18000, v217
	global_load_lds_dwordx4 v223, s[6:7]
	v_mfma_f32_16x16x32_bf16 v[102:105], v[212:215], v[150:153], v[102:105]
	s_add_u32 m0, s22, 0x9c00
	v_add_u32_e32 v224, 0x18040, v217
	global_load_lds_dwordx4 v224, s[6:7]
	ds_read_b128 v[146:149], v216 offset:6144
	s_waitcnt lgkmcnt(6)
	v_mfma_f32_16x16x32_bf16 v[106:109], v[200:203], v[154:157], v[106:109]
	v_mfma_f32_16x16x32_bf16 v[110:113], v[212:215], v[154:157], v[110:113]
	ds_read_b128 v[150:153], v216 offset:8192
	s_waitcnt lgkmcnt(6)
	v_mfma_f32_16x16x32_bf16 v[114:117], v[200:203], v[158:161], v[114:117]
	v_mfma_f32_16x16x32_bf16 v[118:121], v[212:215], v[158:161], v[118:121]
	ds_read_b128 v[154:157], v216 offset:10240
	s_waitcnt lgkmcnt(6)
	v_mfma_f32_16x16x32_bf16 v[122:125], v[200:203], v[162:165], v[122:125]
	v_mfma_f32_16x16x32_bf16 v[126:129], v[212:215], v[162:165], v[126:129]
	v_add_u32_e32 v217, 0x80, v217
	v_add_u32_e32 v220, 0x800, v220
	v_add_u32_e32 v221, 0x800, v221
	s_mov_b32 s16, 6

.Lg256b_ip_next_ok:
	s_lshl_b32 s13, s13, 8
	s_lshl_b32 s14, s14, 7
	s_lshl_b32 s3, s15, 6
	s_add_u32 s17, s3, s13
	s_mul_i32 s17, s17, 0x800
	s_add_u32 s6, s18, s17
	s_addc_u32 s7, s19, 0
	v_mov_b32_e32 v217, v218
	ds_read_b128 v[158:161], v216 offset:12288
	s_waitcnt vmcnt(8) lgkmcnt(6)
	v_mfma_f32_16x16x32_bf16 v[2:5], v[166:169], v[134:137], v[2:5]
	global_load_dwordx4 v[196:199], v220, s[8:9]
	v_mfma_f32_16x16x32_bf16 v[6:9], v[174:177], v[134:137], v[6:9]
	global_load_dwordx4 v[200:203], v220, s[8:9] offset:1024
	ds_read_b128 v[162:165], v216 offset:14336
	s_waitcnt lgkmcnt(6)
	v_mfma_f32_16x16x32_bf16 v[10:13], v[166:169], v[138:141], v[10:13]
	global_load_dwordx4 v[204:207], v221, s[8:9]
	v_mfma_f32_16x16x32_bf16 v[14:17], v[174:177], v[138:141], v[14:17]
	global_load_dwordx4 v[212:215], v221, s[8:9] offset:1024
	ds_read_b128 v[134:137], v216 offset:16384
	s_waitcnt lgkmcnt(6)
	v_mfma_f32_16x16x32_bf16 v[18:21], v[166:169], v[142:145], v[18:21]
	v_mfma_f32_16x16x32_bf16 v[22:25], v[174:177], v[142:145], v[22:25]
	ds_read_b128 v[138:141], v216 offset:18432
	s_waitcnt lgkmcnt(6)
	v_mfma_f32_16x16x32_bf16 v[26:29], v[166:169], v[146:149], v[26:29]
	v_mfma_f32_16x16x32_bf16 v[30:33], v[174:177], v[146:149], v[30:33]
	ds_read_b128 v[142:145], v216 offset:20480
	s_waitcnt lgkmcnt(6)
	v_mfma_f32_16x16x32_bf16 v[34:37], v[166:169], v[150:153], v[34:37]
	v_mfma_f32_16x16x32_bf16 v[38:41], v[174:177], v[150:153], v[38:41]
	ds_read_b128 v[146:149], v216 offset:22528
	s_waitcnt lgkmcnt(6)
	v_mfma_f32_16x16x32_bf16 v[42:45], v[166:169], v[154:157], v[42:45]
	v_mfma_f32_16x16x32_bf16 v[46:49], v[174:177], v[154:157], v[46:49]
	ds_read_b128 v[150:153], v216 offset:24576
	s_waitcnt lgkmcnt(6)
	v_mfma_f32_16x16x32_bf16 v[50:53], v[166:169], v[158:161], v[50:53]
	v_mfma_f32_16x16x32_bf16 v[54:57], v[174:177], v[158:161], v[54:57]
	ds_read_b128 v[154:157], v216 offset:26624
	s_waitcnt lgkmcnt(6)
	v_mfma_f32_16x16x32_bf16 v[58:61], v[166:169], v[162:165], v[58:61]
	v_mfma_f32_16x16x32_bf16 v[62:65], v[174:177], v[162:165], v[62:65]
	ds_read_b128 v[158:161], v216 offset:28672
	s_waitcnt lgkmcnt(6)
	v_mfma_f32_16x16x32_bf16 v[66:69], v[166:169], v[134:137], v[66:69]
	v_mfma_f32_16x16x32_bf16 v[70:73], v[174:177], v[134:137], v[70:73]
	ds_read_b128 v[162:165], v216 offset:30720
	s_waitcnt lgkmcnt(6)
	v_mfma_f32_16x16x32_bf16 v[74:77], v[166:169], v[138:141], v[74:77]
	v_mfma_f32_16x16x32_bf16 v[78:81], v[174:177], v[138:141], v[78:81]
	ds_read_b128 v[134:137], v216 offset:1024
	s_waitcnt lgkmcnt(6)
	v_mfma_f32_16x16x32_bf16 v[82:85], v[166:169], v[142:145], v[82:85]
	v_mfma_f32_16x16x32_bf16 v[86:89], v[174:177], v[142:145], v[86:89]
	ds_read_b128 v[138:141], v216 offset:3072
	s_waitcnt lgkmcnt(6)
	v_mfma_f32_16x16x32_bf16 v[90:93], v[166:169], v[146:149], v[90:93]
	v_mfma_f32_16x16x32_bf16 v[94:97], v[174:177], v[146:149], v[94:97]
	ds_read_b128 v[142:145], v216 offset:5120
	s_waitcnt lgkmcnt(6)
	v_mfma_f32_16x16x32_bf16 v[98:101], v[166:169], v[150:153], v[98:101]
	v_mfma_f32_16x16x32_bf16 v[102:105], v[174:177], v[150:153], v[102:105]
	ds_read_b128 v[146:149], v216 offset:7168
	s_waitcnt lgkmcnt(6)
	v_mfma_f32_16x16x32_bf16 v[106:109], v[166:169], v[154:157], v[106:109]
	v_mfma_f32_16x16x32_bf16 v[110:113], v[174:177], v[154:157], v[110:113]
	ds_read_b128 v[150:153], v216 offset:9216
	s_waitcnt lgkmcnt(6)
	v_mfma_f32_16x16x32_bf16 v[114:117], v[166:169], v[158:161], v[114:117]
	v_mfma_f32_16x16x32_bf16 v[118:121], v[174:177], v[158:161], v[118:121]
	ds_read_b128 v[154:157], v216 offset:11264
	s_waitcnt lgkmcnt(6)
	v_mfma_f32_16x16x32_bf16 v[122:125], v[166:169], v[162:165], v[122:125]
	v_mfma_f32_16x16x32_bf16 v[126:129], v[174:177], v[162:165], v[126:129]
	ds_read_b128 v[158:161], v216 offset:13312
	s_waitcnt lgkmcnt(6)
	v_mfma_f32_16x16x32_bf16 v[2:5], v[170:173], v[134:137], v[2:5]
	v_mfma_f32_16x16x32_bf16 v[6:9], v[178:181], v[134:137], v[6:9]
	ds_read_b128 v[162:165], v216 offset:15360
	s_waitcnt lgkmcnt(6)
	v_mfma_f32_16x16x32_bf16 v[10:13], v[170:173], v[138:141], v[10:13]
	v_mfma_f32_16x16x32_bf16 v[14:17], v[178:181], v[138:141], v[14:17]
	ds_read_b128 v[134:137], v216 offset:17408
	s_waitcnt lgkmcnt(6)
	v_mfma_f32_16x16x32_bf16 v[18:21], v[170:173], v[142:145], v[18:21]
	v_mfma_f32_16x16x32_bf16 v[22:25], v[178:181], v[142:145], v[22:25]
	ds_read_b128 v[138:141], v216 offset:19456
	s_waitcnt lgkmcnt(6)
	v_mfma_f32_16x16x32_bf16 v[26:29], v[170:173], v[146:149], v[26:29]
	v_mfma_f32_16x16x32_bf16 v[30:33], v[178:181], v[146:149], v[30:33]
	ds_read_b128 v[142:145], v216 offset:21504
	s_waitcnt lgkmcnt(6)
	v_mfma_f32_16x16x32_bf16 v[34:37], v[170:173], v[150:153], v[34:37]
	v_mfma_f32_16x16x32_bf16 v[38:41], v[178:181], v[150:153], v[38:41]
	ds_read_b128 v[146:149], v216 offset:23552
	s_waitcnt lgkmcnt(6)
	v_mfma_f32_16x16x32_bf16 v[42:45], v[170:173], v[154:157], v[42:45]
	v_mfma_f32_16x16x32_bf16 v[46:49], v[178:181], v[154:157], v[46:49]
	ds_read_b128 v[150:153], v216 offset:25600
	s_waitcnt lgkmcnt(6)
	v_mfma_f32_16x16x32_bf16 v[50:53], v[170:173], v[158:161], v[50:53]
	v_mfma_f32_16x16x32_bf16 v[54:57], v[178:181], v[158:161], v[54:57]
	ds_read_b128 v[154:157], v216 offset:27648
	s_waitcnt lgkmcnt(6)
	v_mfma_f32_16x16x32_bf16 v[58:61], v[170:173], v[162:165], v[58:61]
	v_mfma_f32_16x16x32_bf16 v[62:65], v[178:181], v[162:165], v[62:65]
	ds_read_b128 v[158:161], v216 offset:29696
	s_waitcnt lgkmcnt(6)
	v_mfma_f32_16x16x32_bf16 v[66:69], v[170:173], v[134:137], v[66:69]
	v_mfma_f32_16x16x32_bf16 v[70:73], v[178:181], v[134:137], v[70:73]
	ds_read_b128 v[162:165], v216 offset:31744
	s_waitcnt vmcnt(4) lgkmcnt(0)
	s_barrier
	v_mfma_f32_16x16x32_bf16 v[74:77], v[170:173], v[138:141], v[74:77]
	s_add_u32 m0, s22, 0x0
	v_mov_b32_e32 v223, v217
	global_load_lds_dwordx4 v223, s[6:7]
	v_mfma_f32_16x16x32_bf16 v[78:81], v[178:181], v[138:141], v[78:81]
	s_add_u32 m0, s22, 0x400
	v_add_u32_e32 v224, 0x40, v217
	global_load_lds_dwordx4 v224, s[6:7]
	ds_read_b128 v[134:137], v216 offset:32768
	s_waitcnt lgkmcnt(6)
	v_mfma_f32_16x16x32_bf16 v[82:85], v[170:173], v[142:145], v[82:85]
	s_add_u32 m0, s22, 0x800
	v_add_u32_e32 v223, 0x8000, v217
	global_load_lds_dwordx4 v223, s[6:7]
	v_mfma_f32_16x16x32_bf16 v[86:89], v[178:181], v[142:145], v[86:89]
	s_add_u32 m0, s22, 0xc00
	v_add_u32_e32 v224, 0x8040, v217
	global_load_lds_dwordx4 v224, s[6:7]
	ds_read_b128 v[138:141], v216 offset:34816
	s_waitcnt lgkmcnt(6)
	v_mfma_f32_16x16x32_bf16 v[90:93], v[170:173], v[146:149], v[90:93]
	s_add_u32 m0, s22, 0x1000
	v_add_u32_e32 v223, 0x10000, v217
	global_load_lds_dwordx4 v223, s[6:7]
	v_mfma_f32_16x16x32_bf16 v[94:97], v[178:181], v[146:149], v[94:97]
	s_add_u32 m0, s22, 0x1400
	v_add_u32_e32 v224, 0x10040, v217
	global_load_lds_dwordx4 v224, s[6:7]
	ds_read_b128 v[142:145], v216 offset:36864
	s_waitcnt lgkmcnt(6)
	v_mfma_f32_16x16x32_bf16 v[98:101], v[170:173], v[150:153], v[98:101]
	s_add_u32 m0, s22, 0x1800
	v_add_u32_e32 v223, 0x18000, v217
	global_load_lds_dwordx4 v223, s[6:7]
	v_mfma_f32_16x16x32_bf16 v[102:105], v[178:181], v[150:153], v[102:105]
	s_add_u32 m0, s22, 0x1c00
	v_add_u32_e32 v224, 0x18040, v217
	global_load_lds_dwordx4 v224, s[6:7]
	ds_read_b128 v[146:149], v216 offset:38912
	s_waitcnt lgkmcnt(6)
	v_mfma_f32_16x16x32_bf16 v[106:109], v[170:173], v[154:157], v[106:109]
	v_mfma_f32_16x16x32_bf16 v[110:113], v[178:181], v[154:157], v[110:113]
	ds_read_b128 v[150:153], v216 offset:40960
	s_waitcnt lgkmcnt(6)
	v_mfma_f32_16x16x32_bf16 v[114:117], v[170:173], v[158:161], v[114:117]
	v_mfma_f32_16x16x32_bf16 v[118:121], v[178:181], v[158:161], v[118:121]
	ds_read_b128 v[154:157], v216 offset:43008
	s_waitcnt lgkmcnt(6)
	v_mfma_f32_16x16x32_bf16 v[122:125], v[170:173], v[162:165], v[122:125]
	v_mfma_f32_16x16x32_bf16 v[126:129], v[178:181], v[162:165], v[126:129]
	v_add_u32_e32 v217, 0x80, v217
	v_add_u32_e32 v220, 0x800, v220
	v_add_u32_e32 v221, 0x800, v221
	s_lshr_b32 s3, s14, 4
	s_lshl_b32 s17, s15, 1
	s_add_u32 s3, s3, s17
	s_mul_i32 s17, s3, 0x8000
	s_add_u32 s8, s20, s17
	s_addc_u32 s9, s21, 0
	v_mov_b32_e32 v220, v222
	v_add_u32_e32 v221, 0x8000, v222
	ds_read_b128 v[158:161], v216 offset:45056
	s_waitcnt vmcnt(8) lgkmcnt(6)
	v_mfma_f32_16x16x32_bf16 v[2:5], v[196:199], v[134:137], v[2:5]
	global_load_dwordx4 v[166:169], v220, s[8:9]
	v_mfma_f32_16x16x32_bf16 v[6:9], v[204:207], v[134:137], v[6:9]
	global_load_dwordx4 v[170:173], v220, s[8:9] offset:1024
	ds_read_b128 v[162:165], v216 offset:47104
	s_waitcnt lgkmcnt(6)
	v_mfma_f32_16x16x32_bf16 v[10:13], v[196:199], v[138:141], v[10:13]
	global_load_dwordx4 v[174:177], v221, s[8:9]
	v_mfma_f32_16x16x32_bf16 v[14:17], v[204:207], v[138:141], v[14:17]
	global_load_dwordx4 v[178:181], v221, s[8:9] offset:1024
	ds_read_b128 v[134:137], v216 offset:49152
	s_waitcnt lgkmcnt(6)
	v_mfma_f32_16x16x32_bf16 v[18:21], v[196:199], v[142:145], v[18:21]
	v_mfma_f32_16x16x32_bf16 v[22:25], v[204:207], v[142:145], v[22:25]
	ds_read_b128 v[138:141], v216 offset:51200
	s_waitcnt lgkmcnt(6)
	v_mfma_f32_16x16x32_bf16 v[26:29], v[196:199], v[146:149], v[26:29]
	v_mfma_f32_16x16x32_bf16 v[30:33], v[204:207], v[146:149], v[30:33]
	ds_read_b128 v[142:145], v216 offset:53248
	s_waitcnt lgkmcnt(6)
	v_mfma_f32_16x16x32_bf16 v[34:37], v[196:199], v[150:153], v[34:37]
	v_mfma_f32_16x16x32_bf16 v[38:41], v[204:207], v[150:153], v[38:41]
	ds_read_b128 v[146:149], v216 offset:55296
	s_waitcnt lgkmcnt(6)
	v_mfma_f32_16x16x32_bf16 v[42:45], v[196:199], v[154:157], v[42:45]
	v_mfma_f32_16x16x32_bf16 v[46:49], v[204:207], v[154:157], v[46:49]
	ds_read_b128 v[150:153], v216 offset:57344
	s_waitcnt lgkmcnt(6)
	v_mfma_f32_16x16x32_bf16 v[50:53], v[196:199], v[158:161], v[50:53]
	v_mfma_f32_16x16x32_bf16 v[54:57], v[204:207], v[158:161], v[54:57]
	ds_read_b128 v[154:157], v216 offset:59392
	s_waitcnt lgkmcnt(6)
	v_mfma_f32_16x16x32_bf16 v[58:61], v[196:199], v[162:165], v[58:61]
	v_mfma_f32_16x16x32_bf16 v[62:65], v[204:207], v[162:165], v[62:65]
	ds_read_b128 v[158:161], v216 offset:61440
	s_waitcnt lgkmcnt(6)
	v_mfma_f32_16x16x32_bf16 v[66:69], v[196:199], v[134:137], v[66:69]
	v_mfma_f32_16x16x32_bf16 v[70:73], v[204:207], v[134:137], v[70:73]
	ds_read_b128 v[162:165], v216 offset:63488
	s_waitcnt lgkmcnt(6)
	v_mfma_f32_16x16x32_bf16 v[74:77], v[196:199], v[138:141], v[74:77]
	v_mfma_f32_16x16x32_bf16 v[78:81], v[204:207], v[138:141], v[78:81]
	ds_read_b128 v[134:137], v216 offset:33792
	s_waitcnt lgkmcnt(6)
	v_mfma_f32_16x16x32_bf16 v[82:85], v[196:199], v[142:145], v[82:85]
	v_mfma_f32_16x16x32_bf16 v[86:89], v[204:207], v[142:145], v[86:89]
	ds_read_b128 v[138:141], v216 offset:35840
	s_waitcnt lgkmcnt(6)
	v_mfma_f32_16x16x32_bf16 v[90:93], v[196:199], v[146:149], v[90:93]
	v_mfma_f32_16x16x32_bf16 v[94:97], v[204:207], v[146:149], v[94:97]
	ds_read_b128 v[142:145], v216 offset:37888
	s_waitcnt lgkmcnt(6)
	v_mfma_f32_16x16x32_bf16 v[98:101], v[196:199], v[150:153], v[98:101]
	v_mfma_f32_16x16x32_bf16 v[102:105], v[204:207], v[150:153], v[102:105]
	ds_read_b128 v[146:149], v216 offset:39936
	s_waitcnt lgkmcnt(6)
	v_mfma_f32_16x16x32_bf16 v[106:109], v[196:199], v[154:157], v[106:109]
	v_mfma_f32_16x16x32_bf16 v[110:113], v[204:207], v[154:157], v[110:113]
	ds_read_b128 v[150:153], v216 offset:41984
	s_waitcnt lgkmcnt(6)
	v_mfma_f32_16x16x32_bf16 v[114:117], v[196:199], v[158:161], v[114:117]
	v_mfma_f32_16x16x32_bf16 v[118:121], v[204:207], v[158:161], v[118:121]
	ds_read_b128 v[154:157], v216 offset:44032
	s_waitcnt lgkmcnt(6)
	v_mfma_f32_16x16x32_bf16 v[122:125], v[196:199], v[162:165], v[122:125]
	v_mfma_f32_16x16x32_bf16 v[126:129], v[204:207], v[162:165], v[126:129]
	ds_read_b128 v[158:161], v216 offset:46080
	s_waitcnt lgkmcnt(6)
	v_mfma_f32_16x16x32_bf16 v[2:5], v[200:203], v[134:137], v[2:5]
	v_mfma_f32_16x16x32_bf16 v[6:9], v[212:215], v[134:137], v[6:9]
	ds_read_b128 v[162:165], v216 offset:48128
	s_waitcnt lgkmcnt(6)
	v_mfma_f32_16x16x32_bf16 v[10:13], v[200:203], v[138:141], v[10:13]
	v_mfma_f32_16x16x32_bf16 v[14:17], v[212:215], v[138:141], v[14:17]
	ds_read_b128 v[134:137], v216 offset:50176
	s_waitcnt lgkmcnt(6)
	v_mfma_f32_16x16x32_bf16 v[18:21], v[200:203], v[142:145], v[18:21]
	v_mfma_f32_16x16x32_bf16 v[22:25], v[212:215], v[142:145], v[22:25]
	ds_read_b128 v[138:141], v216 offset:52224
	s_waitcnt lgkmcnt(6)
	v_mfma_f32_16x16x32_bf16 v[26:29], v[200:203], v[146:149], v[26:29]
	v_mfma_f32_16x16x32_bf16 v[30:33], v[212:215], v[146:149], v[30:33]
	ds_read_b128 v[142:145], v216 offset:54272
	s_waitcnt lgkmcnt(6)
	v_mfma_f32_16x16x32_bf16 v[34:37], v[200:203], v[150:153], v[34:37]
	v_mfma_f32_16x16x32_bf16 v[38:41], v[212:215], v[150:153], v[38:41]
	ds_read_b128 v[146:149], v216 offset:56320
	s_waitcnt lgkmcnt(6)
	v_mfma_f32_16x16x32_bf16 v[42:45], v[200:203], v[154:157], v[42:45]
	v_mfma_f32_16x16x32_bf16 v[46:49], v[212:215], v[154:157], v[46:49]
	ds_read_b128 v[150:153], v216 offset:58368
	s_waitcnt lgkmcnt(6)
	v_mfma_f32_16x16x32_bf16 v[50:53], v[200:203], v[158:161], v[50:53]
	v_mfma_f32_16x16x32_bf16 v[54:57], v[212:215], v[158:161], v[54:57]
	ds_read_b128 v[154:157], v216 offset:60416
	s_waitcnt lgkmcnt(6)
	v_mfma_f32_16x16x32_bf16 v[58:61], v[200:203], v[162:165], v[58:61]
	v_mfma_f32_16x16x32_bf16 v[62:65], v[212:215], v[162:165], v[62:65]
	ds_read_b128 v[158:161], v216 offset:62464
	s_waitcnt lgkmcnt(6)
	v_mfma_f32_16x16x32_bf16 v[66:69], v[200:203], v[134:137], v[66:69]
	v_mfma_f32_16x16x32_bf16 v[70:73], v[212:215], v[134:137], v[70:73]
	ds_read_b128 v[162:165], v216 offset:64512
	s_waitcnt vmcnt(4) lgkmcnt(0)
	s_barrier
	v_mfma_f32_16x16x32_bf16 v[74:77], v[200:203], v[138:141], v[74:77]
	s_add_u32 m0, s22, 0x8000
	v_mov_b32_e32 v223, v217
	global_load_lds_dwordx4 v223, s[6:7]
	v_mfma_f32_16x16x32_bf16 v[78:81], v[212:215], v[138:141], v[78:81]
	s_add_u32 m0, s22, 0x8400
	v_add_u32_e32 v224, 0x40, v217
	global_load_lds_dwordx4 v224, s[6:7]
	ds_read_b128 v[134:137], v216
	s_waitcnt lgkmcnt(6)
	v_mfma_f32_16x16x32_bf16 v[82:85], v[200:203], v[142:145], v[82:85]
	s_add_u32 m0, s22, 0x8800
	v_add_u32_e32 v223, 0x8000, v217
	global_load_lds_dwordx4 v223, s[6:7]
	v_mfma_f32_16x16x32_bf16 v[86:89], v[212:215], v[142:145], v[86:89]
	s_add_u32 m0, s22, 0x8c00
	v_add_u32_e32 v224, 0x8040, v217
	global_load_lds_dwordx4 v224, s[6:7]
	ds_read_b128 v[138:141], v216 offset:2048
	s_waitcnt lgkmcnt(6)
	v_mfma_f32_16x16x32_bf16 v[90:93], v[200:203], v[146:149], v[90:93]
	s_add_u32 m0, s22, 0x9000
	v_add_u32_e32 v223, 0x10000, v217
	global_load_lds_dwordx4 v223, s[6:7]
	v_mfma_f32_16x16x32_bf16 v[94:97], v[212:215], v[146:149], v[94:97]
	s_add_u32 m0, s22, 0x9400
	v_add_u32_e32 v224, 0x10040, v217
	global_load_lds_dwordx4 v224, s[6:7]
	ds_read_b128 v[142:145], v216 offset:4096
	s_waitcnt lgkmcnt(6)
	v_mfma_f32_16x16x32_bf16 v[98:101], v[200:203], v[150:153], v[98:101]
	s_add_u32 m0, s22, 0x9800
	v_add_u32_e32 v223, 0x18000, v217
	global_load_lds_dwordx4 v223, s[6:7]
	v_mfma_f32_16x16x32_bf16 v[102:105], v[212:215], v[150:153], v[102:105]
	s_add_u32 m0, s22, 0x9c00
	v_add_u32_e32 v224, 0x18040, v217
	global_load_lds_dwordx4 v224, s[6:7]
	ds_read_b128 v[146:149], v216 offset:6144
	s_waitcnt lgkmcnt(6)
	v_mfma_f32_16x16x32_bf16 v[106:109], v[200:203], v[154:157], v[106:109]
	v_mfma_f32_16x16x32_bf16 v[110:113], v[212:215], v[154:157], v[110:113]
	ds_read_b128 v[150:153], v216 offset:8192
	s_waitcnt lgkmcnt(6)
	v_mfma_f32_16x16x32_bf16 v[114:117], v[200:203], v[158:161], v[114:117]
	v_mfma_f32_16x16x32_bf16 v[118:121], v[212:215], v[158:161], v[118:121]
	ds_read_b128 v[154:157], v216 offset:10240
	s_waitcnt lgkmcnt(6)
	v_mfma_f32_16x16x32_bf16 v[122:125], v[200:203], v[162:165], v[122:125]
	v_mfma_f32_16x16x32_bf16 v[126:129], v[212:215], v[162:165], v[126:129]
	v_add_u32_e32 v217, 0x80, v217
	v_add_u32_e32 v220, 0x800, v220
	v_add_u32_e32 v221, 0x800, v221
	s_mov_b32 s16, 1
	s_branch .Lg256b_ip_epi

.Lg256b_ip_epi:
	s_cmp_lg_u32 s27, 0
	s_cbranch_scc1 .Lg256b_ip_mskip
	v_cvt_pk_bf16_f32 v2, v2, v3
	v_cvt_pk_bf16_f32 v3, v4, v5
	global_store_dwordx2 v219, v[2:3], s[10:11]
	v_cvt_pk_bf16_f32 v6, v6, v7
	v_cvt_pk_bf16_f32 v7, v8, v9
	global_store_dwordx2 v219, v[6:7], s[10:11] offset:32
	v_add_u32_e32 v131, 0x14400, v219
	v_cvt_pk_bf16_f32 v10, v10, v11
	v_cvt_pk_bf16_f32 v11, v12, v13
	global_store_dwordx2 v131, v[10:11], s[10:11]
	v_cvt_pk_bf16_f32 v14, v14, v15
	v_cvt_pk_bf16_f32 v15, v16, v17
	global_store_dwordx2 v131, v[14:15], s[10:11] offset:32
	v_add_u32_e32 v131, 0x28800, v219
	v_cvt_pk_bf16_f32 v18, v18, v19
	v_cvt_pk_bf16_f32 v19, v20, v21
	global_store_dwordx2 v131, v[18:19], s[10:11]
	v_cvt_pk_bf16_f32 v22, v22, v23
	v_cvt_pk_bf16_f32 v23, v24, v25
	global_store_dwordx2 v131, v[22:23], s[10:11] offset:32
	v_add_u32_e32 v131, 0x3cc00, v219
	v_cvt_pk_bf16_f32 v26, v26, v27
	v_cvt_pk_bf16_f32 v27, v28, v29
	global_store_dwordx2 v131, v[26:27], s[10:11]
	v_cvt_pk_bf16_f32 v30, v30, v31
	v_cvt_pk_bf16_f32 v31, v32, v33
	global_store_dwordx2 v131, v[30:31], s[10:11] offset:32
	v_add_u32_e32 v131, 0x51000, v219
	v_cvt_pk_bf16_f32 v34, v34, v35
	v_cvt_pk_bf16_f32 v35, v36, v37
	global_store_dwordx2 v131, v[34:35], s[10:11]
	v_cvt_pk_bf16_f32 v38, v38, v39
	v_cvt_pk_bf16_f32 v39, v40, v41
	global_store_dwordx2 v131, v[38:39], s[10:11] offset:32
	v_add_u32_e32 v131, 0x65400, v219
	v_cvt_pk_bf16_f32 v42, v42, v43
	v_cvt_pk_bf16_f32 v43, v44, v45
	global_store_dwordx2 v131, v[42:43], s[10:11]
	v_cvt_pk_bf16_f32 v46, v46, v47
	v_cvt_pk_bf16_f32 v47, v48, v49
	global_store_dwordx2 v131, v[46:47], s[10:11] offset:32
	v_add_u32_e32 v131, 0x79800, v219
	v_cvt_pk_bf16_f32 v50, v50, v51
	v_cvt_pk_bf16_f32 v51, v52, v53
	global_store_dwordx2 v131, v[50:51], s[10:11]
	v_cvt_pk_bf16_f32 v54, v54, v55
	v_cvt_pk_bf16_f32 v55, v56, v57
	global_store_dwordx2 v131, v[54:55], s[10:11] offset:32
	v_add_u32_e32 v131, 0x8dc00, v219
	v_cvt_pk_bf16_f32 v58, v58, v59
	v_cvt_pk_bf16_f32 v59, v60, v61
	global_store_dwordx2 v131, v[58:59], s[10:11]
	v_cvt_pk_bf16_f32 v62, v62, v63
	v_cvt_pk_bf16_f32 v63, v64, v65
	global_store_dwordx2 v131, v[62:63], s[10:11] offset:32
	v_add_u32_e32 v131, 0xa2000, v219
	v_cvt_pk_bf16_f32 v66, v66, v67
	v_cvt_pk_bf16_f32 v67, v68, v69
	global_store_dwordx2 v131, v[66:67], s[10:11]
	v_cvt_pk_bf16_f32 v70, v70, v71
	v_cvt_pk_bf16_f32 v71, v72, v73
	global_store_dwordx2 v131, v[70:71], s[10:11] offset:32
	v_add_u32_e32 v131, 0xb6400, v219
	v_cvt_pk_bf16_f32 v74, v74, v75
	v_cvt_pk_bf16_f32 v75, v76, v77
	global_store_dwordx2 v131, v[74:75], s[10:11]
	v_cvt_pk_bf16_f32 v78, v78, v79
	v_cvt_pk_bf16_f32 v79, v80, v81
	global_store_dwordx2 v131, v[78:79], s[10:11] offset:32
	v_add_u32_e32 v131, 0xca800, v219
	v_cvt_pk_bf16_f32 v82, v82, v83
	v_cvt_pk_bf16_f32 v83, v84, v85
	global_store_dwordx2 v131, v[82:83], s[10:11]
	v_cvt_pk_bf16_f32 v86, v86, v87
	v_cvt_pk_bf16_f32 v87, v88, v89
	global_store_dwordx2 v131, v[86:87], s[10:11] offset:32
	v_add_u32_e32 v131, 0xdec00, v219
	v_cvt_pk_bf16_f32 v90, v90, v91
	v_cvt_pk_bf16_f32 v91, v92, v93
	global_store_dwordx2 v131, v[90:91], s[10:11]
	v_cvt_pk_bf16_f32 v94, v94, v95
	v_cvt_pk_bf16_f32 v95, v96, v97
	global_store_dwordx2 v131, v[94:95], s[10:11] offset:32
	v_add_u32_e32 v131, 0xf3000, v219
	v_cvt_pk_bf16_f32 v98, v98, v99
	v_cvt_pk_bf16_f32 v99, v100, v101
	global_store_dwordx2 v131, v[98:99], s[10:11]
	v_cvt_pk_bf16_f32 v102, v102, v103
	v_cvt_pk_bf16_f32 v103, v104, v105
	global_store_dwordx2 v131, v[102:103], s[10:11] offset:32
	v_add_u32_e32 v131, 0x107400, v219
	v_cvt_pk_bf16_f32 v106, v106, v107
	v_cvt_pk_bf16_f32 v107, v108, v109
	global_store_dwordx2 v131, v[106:107], s[10:11]
	v_cvt_pk_bf16_f32 v110, v110, v111
	v_cvt_pk_bf16_f32 v111, v112, v113
	global_store_dwordx2 v131, v[110:111], s[10:11] offset:32
	v_add_u32_e32 v131, 0x11b800, v219
	v_cvt_pk_bf16_f32 v114, v114, v115
	v_cvt_pk_bf16_f32 v115, v116, v117
	global_store_dwordx2 v131, v[114:115], s[10:11]
	v_cvt_pk_bf16_f32 v118, v118, v119
	v_cvt_pk_bf16_f32 v119, v120, v121
	global_store_dwordx2 v131, v[118:119], s[10:11] offset:32
	v_add_u32_e32 v131, 0x12fc00, v219
	v_cvt_pk_bf16_f32 v122, v122, v123
	v_cvt_pk_bf16_f32 v123, v124, v125
	global_store_dwordx2 v131, v[122:123], s[10:11]
	v_cvt_pk_bf16_f32 v126, v126, v127
	v_cvt_pk_bf16_f32 v127, v128, v129
	global_store_dwordx2 v131, v[126:127], s[10:11] offset:32

.Lcv_skip_w1:
	s_cmp_lt_u32 s25, 656
	s_cbranch_scc1 .Lcv_do_win
.Lcv_skip_win:
	s_cmp_lt_u32 s25, 1936
	s_cbranch_scc1 .Lcv_skip_wout
	s_cmp_lt_u32 s25, 2192
	s_cbranch_scc1 .Lcv_do_wout
.Lcv_skip_wout:
	s_cmp_lt_u32 s25, 3216
	s_cbranch_scc1 .Lcv_skip_w2
	s_cmp_lt_u32 s25, 4240
	s_cbranch_scc1 .Lcv_do_w2

.Lcv_do_win:
	s_load_dwordx2 s[20:21], s[0:1], 0x70
	s_mul_i32 s27, s25, 1599
	s_lshr_b32 s27, s27, 16
	s_mul_i32 s26, s27, 41
	s_sub_u32 s26, s25, s26
	s_mov_b32 s25, s27
	s_mov_b32 s18, 2576
	s_mov_b32 s19, 32
	s_mov_b32 s28, 0x9e7800
	s_mov_b32 s29, 1
	s_mul_i32 s27, s62, 0xa10000
	s_waitcnt lgkmcnt(0)
	s_add_u32 s20, s20, s27
	s_addc_u32 s21, s21, 0
	s_branch .Lcv_tile
.Lcv_do_wout:
	s_load_dwordx2 s[20:21], s[0:1], 0x110
	s_sub_u32 s25, s25, 1936
	s_and_b32 s26, s25, 15
	s_lshr_b32 s25, s25, 4
	s_mov_b32 s18, 1024
	s_mov_b32 s19, 32
	s_mov_b32 s28, 0x1927800
	s_mov_b32 s29, 0
	s_mul_i32 s27, s62, 0x400000
	s_waitcnt lgkmcnt(0)
	s_add_u32 s20, s20, s27
	s_addc_u32 s21, s21, 0
	s_branch .Lcv_tile
.Lcv_do_w2:
	s_load_dwordx2 s[20:21], s[0:1], 0x120
	s_sub_u32 s25, s25, 3216
	s_and_b32 s26, s25, 15
	s_lshr_b32 s25, s25, 4
	s_mov_b32 s18, 1024
	s_mov_b32 s19, 128
	s_mov_b32 s28, 0x2327800
	s_mov_b32 s29, 0
	s_mul_i32 s27, s62, 0x1000000
	s_waitcnt lgkmcnt(0)
	s_add_u32 s20, s20, s27
	s_addc_u32 s21, s21, 0
	s_branch .Lcv_tile
